# 4-phase K-loop, no setprio, loop-counter SALU moved out of the MFMA tail into the load segment
# speedup vs baseline: 1.0537x; 1.0077x over previous
; #define PG8_STAGE(bufoff, gbase, voff) do { _Pragma("unroll") for (int _i = 0; _i < 2; ++_i) \
;         __builtin_amdgcn_global_load_lds((const unsigned*)((const char*)(gbase) + (voff)[_i]), (PG8_LAS unsigned*)(lds + (bufoff) + ldsw + _i * 8192), 16, 0, 0); } while (0)
; #define PG8_LDA(dst, b, h) do { _Pragma("unroll") for (int m = 0; m < 4; ++m) _Pragma("unroll") for (int k = 0; k < 2; ++k) dst[m][k] = *(const PG8_LAS bf16x8*)(lds + PG8_SA(b, h) + aoff + m * 2048 + k * 1024); } while (0)
; #define PG8_LDB(dst, b, h) do { _Pragma("unroll") for (int n = 0; n < 2; ++n) _Pragma("unroll") for (int k = 0; k < 2; ++k) dst[n][k] = *(const PG8_LAS bf16x8*)(lds + PG8_SB(b, h) + boff + n * 2048 + k * 1024); } while (0)
; #define PG8_MMA(ai, bj, At, Bt) do { __builtin_amdgcn_s_setprio(1); _Pragma("unroll") for (int m = 0; m < 4; ++m) _Pragma("unroll") for (int n = 0; n < 2; ++n) _Pragma("unroll") for (int k = 0; k < 2; ++k) \
;         acc[ai][bj][m][n] = __builtin_amdgcn_mfma_f32_16x16x32_bf16(Bt[n][k], At[m][k], acc[ai][bj][m][n], 0, 0, 0); __builtin_amdgcn_s_setprio(0); } while (0)
; #define PG8_WAIT_V(n) asm volatile("s_waitcnt vmcnt(" #n ")" ::: "memory")
; template <class Epi, class Sched>
; __device__ __forceinline__ void gemm_phase(PG8_LAS unsigned char* lds, const Gemm g, const Sched& S, const Epi& E) {
;     ...
;         for (int t = 0; t < nt; t += 2) {
;             const bool last = (t == nt - 2);
;             const char* a1 = cA + (size_t)(t + 1) * kstep;
;             const char* a2 = last ? nA : cA + (size_t)(t + 2) * kstep; const char* b2 = last ? nB : cB + (size_t)(t + 2) * kstepB;
;             const char* a3 = a2 + kstep; const char* b3 = b2 + kstepB;
;             if (last && has_next) S.a_ready(nxt);
;             PG8_LDB(B0, 0, 0); PG8_SCHED; PG8_LDA(At, 0, 0); PG8_STAGE(PG8_SA(1, 1), a1 + hstep, voffA);
;             PG8_WAIT_L(8); PG8_BAR; PG8_WAIT_L(0); PG8_MMA(0, 0, At, B0); PG8_BAR; PG8_SCHED;
;             PG8_LDB(B1, 0, 1); PG8_STAGE(PG8_SB(0, 0), b2, voffB);
;             PG8_BAR; PG8_WAIT_L(0); PG8_MMA(0, 1, At, B1); PG8_BAR;
;             PG8_LDA(At, 0, 1); PG8_STAGE(PG8_SA(0, 0), a2, voffA);
;             PG8_BAR; PG8_WAIT_L(0); PG8_MMA(1, 0, At, B0); PG8_BAR; PG8_SCHED;
;             PG8_STAGE(PG8_SB(0, 1), b2 + hstepB, voffB);
;             PG8_WAIT_V(6); PG8_BAR; PG8_MMA(1, 1, At, B1); PG8_BAR;
.Lhalf_skip_y_0:
.LBB0_79:
	ds_read_b128 v[152:155], v149
	ds_read_b128 v[156:159], v149 offset:1024
	ds_read_b128 v[160:163], v149 offset:2048
	ds_read_b128 v[164:167], v149 offset:3072
	s_add_u32 s24, s22, 0xfff80080
	s_addc_u32 s25, s23, -1
	s_cmp_eq_u32 s61, 28
	s_cselect_b32 s27, s13, s25
	s_cselect_b32 s26, s57, s24
	s_cselect_b32 s25, s15, s60
	s_cselect_b32 s24, s58, s59
	v_lshl_add_u64 v[144:145], s[22:23], 0, v[136:137]
	s_add_i32 m0, s21, 0xc000
	ds_read_b128 v[168:171], v150
	ds_read_b128 v[172:175], v150 offset:1024
	ds_read_b128 v[176:179], v150 offset:2048
	ds_read_b128 v[180:183], v150 offset:3072
	ds_read_b128 v[184:187], v150 offset:4096
	ds_read_b128 v[188:191], v150 offset:5120
	ds_read_b128 v[192:195], v150 offset:6144
	ds_read_b128 v[196:199], v150 offset:7168
	global_load_lds_dwordx4 v[144:145], off
	v_lshl_add_u64 v[144:145], s[22:23], 0, v[138:139]
	s_add_i32 m0, s21, 0xe000
	s_nop 0
	global_load_lds_dwordx4 v[144:145], off
	s_add_i32 s62, s53, s38
	v_lshl_add_u64 v[144:145], s[24:25], 0, v[128:129]
	s_mov_b32 m0, s62
	ds_read_b128 v[200:203], v151
	ds_read_b128 v[204:207], v151 offset:1024
	ds_read_b128 v[208:211], v151 offset:2048
	ds_read_b128 v[212:215], v151 offset:3072
	s_waitcnt vmcnt(8)
	s_waitcnt lgkmcnt(0)
	s_barrier
	v_mfma_f32_16x16x32_bf16 v[124:127], v[152:155], v[168:171], v[124:127]
	v_mfma_f32_16x16x32_bf16 v[120:123], v[160:163], v[168:171], v[120:123]
	v_mfma_f32_16x16x32_bf16 v[108:111], v[152:155], v[176:179], v[108:111]
	v_mfma_f32_16x16x32_bf16 v[104:107], v[160:163], v[176:179], v[104:107]
	v_mfma_f32_16x16x32_bf16 v[92:95], v[152:155], v[184:187], v[92:95]
	v_mfma_f32_16x16x32_bf16 v[88:91], v[160:163], v[184:187], v[88:91]
	v_mfma_f32_16x16x32_bf16 v[76:79], v[152:155], v[192:195], v[76:79]
	v_mfma_f32_16x16x32_bf16 v[72:75], v[160:163], v[192:195], v[72:75]
	v_mfma_f32_16x16x32_bf16 v[124:127], v[156:159], v[172:175], v[124:127]
	v_mfma_f32_16x16x32_bf16 v[120:123], v[164:167], v[172:175], v[120:123]
	v_mfma_f32_16x16x32_bf16 v[108:111], v[156:159], v[180:183], v[108:111]
	v_mfma_f32_16x16x32_bf16 v[104:107], v[164:167], v[180:183], v[104:107]
	v_mfma_f32_16x16x32_bf16 v[92:95], v[156:159], v[188:191], v[92:95]
	v_mfma_f32_16x16x32_bf16 v[88:91], v[164:167], v[188:191], v[88:91]
	v_mfma_f32_16x16x32_bf16 v[76:79], v[156:159], v[196:199], v[76:79]
	v_mfma_f32_16x16x32_bf16 v[72:75], v[164:167], v[196:199], v[72:75]
	v_mfma_f32_16x16x32_bf16 v[116:119], v[200:203], v[168:171], v[116:119]
	v_mfma_f32_16x16x32_bf16 v[112:115], v[208:211], v[168:171], v[112:115]
	v_mfma_f32_16x16x32_bf16 v[100:103], v[200:203], v[176:179], v[100:103]
	v_mfma_f32_16x16x32_bf16 v[96:99], v[208:211], v[176:179], v[96:99]
	v_mfma_f32_16x16x32_bf16 v[84:87], v[200:203], v[184:187], v[84:87]
	v_mfma_f32_16x16x32_bf16 v[80:83], v[208:211], v[184:187], v[80:83]
	v_mfma_f32_16x16x32_bf16 v[68:71], v[200:203], v[192:195], v[68:71]
	v_mfma_f32_16x16x32_bf16 v[64:67], v[208:211], v[192:195], v[64:67]
	v_mfma_f32_16x16x32_bf16 v[116:119], v[204:207], v[172:175], v[116:119]
	v_mfma_f32_16x16x32_bf16 v[112:115], v[212:215], v[172:175], v[112:115]
	v_mfma_f32_16x16x32_bf16 v[100:103], v[204:207], v[180:183], v[100:103]
	v_mfma_f32_16x16x32_bf16 v[96:99], v[212:215], v[180:183], v[96:99]
	v_mfma_f32_16x16x32_bf16 v[84:87], v[204:207], v[188:191], v[84:87]
	v_mfma_f32_16x16x32_bf16 v[80:83], v[212:215], v[188:191], v[80:83]
	v_mfma_f32_16x16x32_bf16 v[68:71], v[204:207], v[196:199], v[68:71]
	v_mfma_f32_16x16x32_bf16 v[64:67], v[212:215], v[196:199], v[64:67]
	s_barrier
	global_load_lds_dwordx4 v[144:145], off
	v_lshl_add_u64 v[144:145], s[24:25], 0, v[130:131]
	s_add_i32 m0, s62, 0x2000
	s_nop 0
	global_load_lds_dwordx4 v[144:145], off
	s_mov_b32 m0, s21
	v_lshl_add_u64 v[144:145], s[26:27], 0, v[134:135]
	ds_read_b128 v[168:171], v150 offset:16384
	ds_read_b128 v[172:175], v150 offset:17408
	ds_read_b128 v[176:179], v150 offset:18432
	ds_read_b128 v[180:183], v150 offset:19456
	ds_read_b128 v[184:187], v150 offset:20480
	ds_read_b128 v[188:191], v150 offset:21504
	ds_read_b128 v[192:195], v150 offset:22528
	ds_read_b128 v[196:199], v150 offset:23552
	global_load_lds_dwordx4 v[144:145], off
	v_lshl_add_u64 v[216:217], s[26:27], 0, v[132:133]
	s_mov_b32 m0, s46
	s_nop 0
	global_load_lds_dwordx4 v[216:217], off
	s_add_u32 s62, s24, 0x4000
	s_addc_u32 s63, s25, 0
	s_add_i32 s64, s54, s38
	v_lshl_add_u64 v[250:251], s[62:63], 0, v[128:129]
	s_mov_b32 m0, s64
	s_nop 0
	global_load_lds_dwordx4 v[250:251], off
	v_lshl_add_u64 v[250:251], s[62:63], 0, v[130:131]
	s_add_i32 m0, s64, 0x2000
	s_nop 0
	global_load_lds_dwordx4 v[250:251], off
	s_waitcnt vmcnt(8)
	s_waitcnt lgkmcnt(0)
	s_barrier
; #define PG8_STAGE(bufoff, gbase, voff) do { _Pragma("unroll") for (int _i = 0; _i < 2; ++_i) \
;         __builtin_amdgcn_global_load_lds((const unsigned*)((const char*)(gbase) + (voff)[_i]), (PG8_LAS unsigned*)(lds + (bufoff) + ldsw + _i * 8192), 16, 0, 0); } while (0)
; #define PG8_LDA(dst, b, h) do { _Pragma("unroll") for (int m = 0; m < 4; ++m) _Pragma("unroll") for (int k = 0; k < 2; ++k) dst[m][k] = *(const PG8_LAS bf16x8*)(lds + PG8_SA(b, h) + aoff + m * 2048 + k * 1024); } while (0)
; #define PG8_LDB(dst, b, h) do { _Pragma("unroll") for (int n = 0; n < 2; ++n) _Pragma("unroll") for (int k = 0; k < 2; ++k) dst[n][k] = *(const PG8_LAS bf16x8*)(lds + PG8_SB(b, h) + boff + n * 2048 + k * 1024); } while (0)
; #define PG8_MMA(ai, bj, At, Bt) do { __builtin_amdgcn_s_setprio(1); _Pragma("unroll") for (int m = 0; m < 4; ++m) _Pragma("unroll") for (int n = 0; n < 2; ++n) _Pragma("unroll") for (int k = 0; k < 2; ++k) \
;         acc[ai][bj][m][n] = __builtin_amdgcn_mfma_f32_16x16x32_bf16(Bt[n][k], At[m][k], acc[ai][bj][m][n], 0, 0, 0); __builtin_amdgcn_s_setprio(0); } while (0)
; #define PG8_WAIT_V(n) asm volatile("s_waitcnt vmcnt(" #n ")" ::: "memory")
; #define PG8_WAIT_L(n) asm volatile("s_waitcnt lgkmcnt(" #n ")" ::: "memory")
; #define PG8_BAR __builtin_amdgcn_s_barrier()
; #define PG8_SCHED __builtin_amdgcn_sched_barrier(0)
; template <class Epi, class Sched>
; __device__ __forceinline__ void gemm_phase(PG8_LAS unsigned char* lds, const Gemm g, const Sched& S, const Epi& E) {
;     ...
;             PG8_BAR; PG8_WAIT_L(0); PG8_MMA(1, 0, At, B0); PG8_BAR; PG8_SCHED;
;             PG8_STAGE(PG8_SB(0, 1), b2 + hstepB, voffB);
;             PG8_WAIT_V(6); PG8_BAR; PG8_MMA(1, 1, At, B1); PG8_BAR;
;             PG8_LDB(B0, 1, 0); PG8_SCHED; PG8_LDA(At, 1, 0); PG8_STAGE(PG8_SA(0, 1), a2 + hstep, voffA);
;             PG8_WAIT_L(8); PG8_BAR; PG8_WAIT_L(0); PG8_MMA(0, 0, At, B0); PG8_BAR; PG8_SCHED;
;             PG8_LDB(B1, 1, 1); PG8_STAGE(PG8_SB(1, 0), b3, voffB);
;             PG8_BAR; PG8_WAIT_L(0); PG8_MMA(0, 1, At, B1); PG8_BAR;
	v_mfma_f32_16x16x32_bf16 v[60:63], v[152:155], v[168:171], v[60:63]
	v_mfma_f32_16x16x32_bf16 v[56:59], v[160:163], v[168:171], v[56:59]
	v_mfma_f32_16x16x32_bf16 v[44:47], v[152:155], v[176:179], v[44:47]
	v_mfma_f32_16x16x32_bf16 v[40:43], v[160:163], v[176:179], v[40:43]
	v_mfma_f32_16x16x32_bf16 v[28:31], v[152:155], v[184:187], v[28:31]
	v_mfma_f32_16x16x32_bf16 v[24:27], v[160:163], v[184:187], v[24:27]
	v_mfma_f32_16x16x32_bf16 v[12:15], v[152:155], v[192:195], v[12:15]
	v_mfma_f32_16x16x32_bf16 v[8:11], v[160:163], v[192:195], v[8:11]
	v_mfma_f32_16x16x32_bf16 v[60:63], v[156:159], v[172:175], v[60:63]
	v_mfma_f32_16x16x32_bf16 v[56:59], v[164:167], v[172:175], v[56:59]
	v_mfma_f32_16x16x32_bf16 v[44:47], v[156:159], v[180:183], v[44:47]
	v_mfma_f32_16x16x32_bf16 v[40:43], v[164:167], v[180:183], v[40:43]
	v_mfma_f32_16x16x32_bf16 v[28:31], v[156:159], v[188:191], v[28:31]
	v_mfma_f32_16x16x32_bf16 v[24:27], v[164:167], v[188:191], v[24:27]
	v_mfma_f32_16x16x32_bf16 v[12:15], v[156:159], v[196:199], v[12:15]
	v_mfma_f32_16x16x32_bf16 v[8:11], v[164:167], v[196:199], v[8:11]
	v_mfma_f32_16x16x32_bf16 v[52:55], v[200:203], v[168:171], v[52:55]
	v_mfma_f32_16x16x32_bf16 v[48:51], v[208:211], v[168:171], v[48:51]
	v_mfma_f32_16x16x32_bf16 v[36:39], v[200:203], v[176:179], v[36:39]
	v_mfma_f32_16x16x32_bf16 v[32:35], v[208:211], v[176:179], v[32:35]
	v_mfma_f32_16x16x32_bf16 v[20:23], v[200:203], v[184:187], v[20:23]
	v_mfma_f32_16x16x32_bf16 v[16:19], v[208:211], v[184:187], v[16:19]
	v_mfma_f32_16x16x32_bf16 v[4:7], v[200:203], v[192:195], v[4:7]
	v_mfma_f32_16x16x32_bf16 v[0:3], v[208:211], v[192:195], v[0:3]
	v_mfma_f32_16x16x32_bf16 v[52:55], v[204:207], v[172:175], v[52:55]
	v_mfma_f32_16x16x32_bf16 v[48:51], v[212:215], v[172:175], v[48:51]
	v_mfma_f32_16x16x32_bf16 v[36:39], v[204:207], v[180:183], v[36:39]
	v_mfma_f32_16x16x32_bf16 v[32:35], v[212:215], v[180:183], v[32:35]
	v_mfma_f32_16x16x32_bf16 v[20:23], v[204:207], v[188:191], v[20:23]
	v_mfma_f32_16x16x32_bf16 v[16:19], v[212:215], v[188:191], v[16:19]
	v_mfma_f32_16x16x32_bf16 v[4:7], v[204:207], v[196:199], v[4:7]
	v_mfma_f32_16x16x32_bf16 v[0:3], v[212:215], v[196:199], v[0:3]
	s_barrier
	s_add_i32 s62, 0, 0x18000
	v_add_u32_e32 v164, s62, v147
	ds_read_b128 v[152:155], v164
	ds_read_b128 v[156:159], v164 offset:1024
	ds_read_b128 v[160:163], v164 offset:2048
	ds_read_b128 v[164:167], v164 offset:3072
	s_add_u32 s26, s26, 0x80000
	s_addc_u32 s27, s27, 0
	s_mov_b32 m0, s47
	v_lshl_add_u64 v[200:201], s[26:27], 0, v[134:135]
	ds_read_b128 v[168:171], v150 offset:32768
	ds_read_b128 v[172:175], v150 offset:33792
	ds_read_b128 v[176:179], v150 offset:34816
	ds_read_b128 v[180:183], v150 offset:35840
	ds_read_b128 v[184:187], v150 offset:36864
	ds_read_b128 v[188:191], v150 offset:37888
	ds_read_b128 v[192:195], v150 offset:38912
	ds_read_b128 v[196:199], v150 offset:39936
	global_load_lds_dwordx4 v[200:201], off
	v_lshl_add_u64 v[200:201], s[26:27], 0, v[132:133]
	s_mov_b32 m0, s48
	s_nop 0
	global_load_lds_dwordx4 v[200:201], off
	s_add_i32 s63, 0, 0x1c000
	s_add_u32 s26, s24, 0x8000
	s_addc_u32 s27, s25, 0
	s_add_i32 s62, s62, s38
	v_add_u32_e32 v212, s63, v147
	v_lshl_add_u64 v[218:219], s[26:27], 0, v[128:129]
	s_mov_b32 m0, s62
	ds_read_b128 v[200:203], v212
	ds_read_b128 v[204:207], v212 offset:1024
	ds_read_b128 v[208:211], v212 offset:2048
	ds_read_b128 v[212:215], v212 offset:3072
	s_waitcnt vmcnt(8)
	s_waitcnt lgkmcnt(0)
	s_barrier
	v_mfma_f32_16x16x32_bf16 v[124:127], v[152:155], v[168:171], v[124:127]
	v_mfma_f32_16x16x32_bf16 v[120:123], v[160:163], v[168:171], v[120:123]
	v_mfma_f32_16x16x32_bf16 v[108:111], v[152:155], v[176:179], v[108:111]
	v_mfma_f32_16x16x32_bf16 v[104:107], v[160:163], v[176:179], v[104:107]
	v_mfma_f32_16x16x32_bf16 v[92:95], v[152:155], v[184:187], v[92:95]
	v_mfma_f32_16x16x32_bf16 v[88:91], v[160:163], v[184:187], v[88:91]
	v_mfma_f32_16x16x32_bf16 v[76:79], v[152:155], v[192:195], v[76:79]
	v_mfma_f32_16x16x32_bf16 v[72:75], v[160:163], v[192:195], v[72:75]
	v_mfma_f32_16x16x32_bf16 v[124:127], v[156:159], v[172:175], v[124:127]
	v_mfma_f32_16x16x32_bf16 v[120:123], v[164:167], v[172:175], v[120:123]
	v_mfma_f32_16x16x32_bf16 v[108:111], v[156:159], v[180:183], v[108:111]
	v_mfma_f32_16x16x32_bf16 v[104:107], v[164:167], v[180:183], v[104:107]
	v_mfma_f32_16x16x32_bf16 v[92:95], v[156:159], v[188:191], v[92:95]
	v_mfma_f32_16x16x32_bf16 v[88:91], v[164:167], v[188:191], v[88:91]
	v_mfma_f32_16x16x32_bf16 v[76:79], v[156:159], v[196:199], v[76:79]
	v_mfma_f32_16x16x32_bf16 v[72:75], v[164:167], v[196:199], v[72:75]
	v_mfma_f32_16x16x32_bf16 v[116:119], v[200:203], v[168:171], v[116:119]
	v_mfma_f32_16x16x32_bf16 v[112:115], v[208:211], v[168:171], v[112:115]
	v_mfma_f32_16x16x32_bf16 v[100:103], v[200:203], v[176:179], v[100:103]
	v_mfma_f32_16x16x32_bf16 v[96:99], v[208:211], v[176:179], v[96:99]
	v_mfma_f32_16x16x32_bf16 v[84:87], v[200:203], v[184:187], v[84:87]
	v_mfma_f32_16x16x32_bf16 v[80:83], v[208:211], v[184:187], v[80:83]
	v_mfma_f32_16x16x32_bf16 v[68:71], v[200:203], v[192:195], v[68:71]
	v_mfma_f32_16x16x32_bf16 v[64:67], v[208:211], v[192:195], v[64:67]
	v_mfma_f32_16x16x32_bf16 v[116:119], v[204:207], v[172:175], v[116:119]
	v_mfma_f32_16x16x32_bf16 v[112:115], v[212:215], v[172:175], v[112:115]
	v_mfma_f32_16x16x32_bf16 v[100:103], v[204:207], v[180:183], v[100:103]
	v_mfma_f32_16x16x32_bf16 v[96:99], v[212:215], v[180:183], v[96:99]
	v_mfma_f32_16x16x32_bf16 v[84:87], v[204:207], v[188:191], v[84:87]
	v_mfma_f32_16x16x32_bf16 v[80:83], v[212:215], v[188:191], v[80:83]
	v_mfma_f32_16x16x32_bf16 v[68:71], v[204:207], v[196:199], v[68:71]
	v_mfma_f32_16x16x32_bf16 v[64:67], v[212:215], v[196:199], v[64:67]
	s_barrier
; #define PG8_STAGE(bufoff, gbase, voff) do { _Pragma("unroll") for (int _i = 0; _i < 2; ++_i) \
;         __builtin_amdgcn_global_load_lds((const unsigned*)((const char*)(gbase) + (voff)[_i]), (PG8_LAS unsigned*)(lds + (bufoff) + ldsw + _i * 8192), 16, 0, 0); } while (0)
; #define PG8_LDA(dst, b, h) do { _Pragma("unroll") for (int m = 0; m < 4; ++m) _Pragma("unroll") for (int k = 0; k < 2; ++k) dst[m][k] = *(const PG8_LAS bf16x8*)(lds + PG8_SA(b, h) + aoff + m * 2048 + k * 1024); } while (0)
; #define PG8_LDB(dst, b, h) do { _Pragma("unroll") for (int n = 0; n < 2; ++n) _Pragma("unroll") for (int k = 0; k < 2; ++k) dst[n][k] = *(const PG8_LAS bf16x8*)(lds + PG8_SB(b, h) + boff + n * 2048 + k * 1024); } while (0)
; #define PG8_MMA(ai, bj, At, Bt) do { __builtin_amdgcn_s_setprio(1); _Pragma("unroll") for (int m = 0; m < 4; ++m) _Pragma("unroll") for (int n = 0; n < 2; ++n) _Pragma("unroll") for (int k = 0; k < 2; ++k) \
;         acc[ai][bj][m][n] = __builtin_amdgcn_mfma_f32_16x16x32_bf16(Bt[n][k], At[m][k], acc[ai][bj][m][n], 0, 0, 0); __builtin_amdgcn_s_setprio(0); } while (0)
; #define PG8_WAIT_V(n) asm volatile("s_waitcnt vmcnt(" #n ")" ::: "memory")
; #define PG8_WAIT_L(n) asm volatile("s_waitcnt lgkmcnt(" #n ")" ::: "memory")
; #define PG8_BAR __builtin_amdgcn_s_barrier()
; #define PG8_SCHED __builtin_amdgcn_sched_barrier(0)
; template <class Epi, class Sched>
; __device__ __forceinline__ void gemm_phase(PG8_LAS unsigned char* lds, const Gemm g, const Sched& S, const Epi& E) {
;     ...
;             PG8_LDB(B1, 1, 1); PG8_STAGE(PG8_SB(1, 0), b3, voffB);
;             PG8_BAR; PG8_WAIT_L(0); PG8_MMA(0, 1, At, B1); PG8_BAR;
;             PG8_LDA(At, 1, 1); PG8_STAGE(PG8_SA(1, 0), a3, voffA);
;             PG8_BAR; PG8_WAIT_L(0); PG8_MMA(1, 0, At, B0); PG8_BAR; PG8_SCHED;
;             PG8_STAGE(PG8_SB(1, 1), b3 + hstepB, voffB);
;             PG8_WAIT_V(6); PG8_BAR; PG8_MMA(1, 1, At, B1); PG8_BAR;
;         }
	global_load_lds_dwordx4 v[218:219], off
	v_lshl_add_u64 v[218:219], s[26:27], 0, v[130:131]
	s_add_i32 m0, s62, 0x2000
	s_nop 0
	global_load_lds_dwordx4 v[218:219], off
	s_mov_b32 m0, s50
	v_lshl_add_u64 v[144:145], v[144:145], 0, s[10:11]
	ds_read_b128 v[168:171], v150 offset:49152
	ds_read_b128 v[172:175], v150 offset:50176
	ds_read_b128 v[176:179], v150 offset:51200
	ds_read_b128 v[180:183], v150 offset:52224
	ds_read_b128 v[184:187], v150 offset:53248
	ds_read_b128 v[188:191], v150 offset:54272
	ds_read_b128 v[192:195], v150 offset:55296
	ds_read_b128 v[196:199], v150 offset:56320
	global_load_lds_dwordx4 v[144:145], off
	v_lshl_add_u64 v[144:145], v[216:217], 0, s[10:11]
	s_mov_b32 m0, s51
	s_nop 0
	global_load_lds_dwordx4 v[144:145], off
	s_add_u32 s24, s24, 0xc000
	s_addc_u32 s25, s25, 0
	s_add_i32 s26, s63, s38
	v_lshl_add_u64 v[144:145], s[24:25], 0, v[128:129]
	s_mov_b32 m0, s26
	s_nop 0
	global_load_lds_dwordx4 v[144:145], off
	v_lshl_add_u64 v[144:145], s[24:25], 0, v[130:131]
	s_add_i32 m0, s26, 0x2000
	s_nop 0
	global_load_lds_dwordx4 v[144:145], off
	s_add_i32 s61, s61, 2
	s_add_u32 s59, s59, 0x10000
	s_addc_u32 s60, s60, 0
	s_add_u32 s22, s22, 0x100
	s_addc_u32 s23, s23, 0
	s_cmp_gt_u32 s61, 29
	s_waitcnt vmcnt(8)
	s_waitcnt lgkmcnt(0)
	s_barrier
	v_mfma_f32_16x16x32_bf16 v[60:63], v[152:155], v[168:171], v[60:63]
	v_mfma_f32_16x16x32_bf16 v[56:59], v[160:163], v[168:171], v[56:59]
	v_mfma_f32_16x16x32_bf16 v[44:47], v[152:155], v[176:179], v[44:47]
	v_mfma_f32_16x16x32_bf16 v[40:43], v[160:163], v[176:179], v[40:43]
	v_mfma_f32_16x16x32_bf16 v[28:31], v[152:155], v[184:187], v[28:31]
	v_mfma_f32_16x16x32_bf16 v[24:27], v[160:163], v[184:187], v[24:27]
	v_mfma_f32_16x16x32_bf16 v[12:15], v[152:155], v[192:195], v[12:15]
	v_mfma_f32_16x16x32_bf16 v[8:11], v[160:163], v[192:195], v[8:11]
	v_mfma_f32_16x16x32_bf16 v[60:63], v[156:159], v[172:175], v[60:63]
	v_mfma_f32_16x16x32_bf16 v[56:59], v[164:167], v[172:175], v[56:59]
	v_mfma_f32_16x16x32_bf16 v[44:47], v[156:159], v[180:183], v[44:47]
	v_mfma_f32_16x16x32_bf16 v[40:43], v[164:167], v[180:183], v[40:43]
	v_mfma_f32_16x16x32_bf16 v[28:31], v[156:159], v[188:191], v[28:31]
	v_mfma_f32_16x16x32_bf16 v[24:27], v[164:167], v[188:191], v[24:27]
	v_mfma_f32_16x16x32_bf16 v[12:15], v[156:159], v[196:199], v[12:15]
	v_mfma_f32_16x16x32_bf16 v[8:11], v[164:167], v[196:199], v[8:11]
	v_mfma_f32_16x16x32_bf16 v[52:55], v[200:203], v[168:171], v[52:55]
	v_mfma_f32_16x16x32_bf16 v[48:51], v[208:211], v[168:171], v[48:51]
	v_mfma_f32_16x16x32_bf16 v[36:39], v[200:203], v[176:179], v[36:39]
	v_mfma_f32_16x16x32_bf16 v[32:35], v[208:211], v[176:179], v[32:35]
	v_mfma_f32_16x16x32_bf16 v[20:23], v[200:203], v[184:187], v[20:23]
	v_mfma_f32_16x16x32_bf16 v[16:19], v[208:211], v[184:187], v[16:19]
	v_mfma_f32_16x16x32_bf16 v[4:7], v[200:203], v[192:195], v[4:7]
	v_mfma_f32_16x16x32_bf16 v[0:3], v[208:211], v[192:195], v[0:3]
	v_mfma_f32_16x16x32_bf16 v[52:55], v[204:207], v[172:175], v[52:55]
	v_mfma_f32_16x16x32_bf16 v[48:51], v[212:215], v[172:175], v[48:51]
	v_mfma_f32_16x16x32_bf16 v[36:39], v[204:207], v[180:183], v[36:39]
	v_mfma_f32_16x16x32_bf16 v[32:35], v[212:215], v[180:183], v[32:35]
	v_mfma_f32_16x16x32_bf16 v[20:23], v[204:207], v[188:191], v[20:23]
	v_mfma_f32_16x16x32_bf16 v[16:19], v[212:215], v[188:191], v[16:19]
	v_mfma_f32_16x16x32_bf16 v[4:7], v[204:207], v[196:199], v[4:7]
	v_mfma_f32_16x16x32_bf16 v[0:3], v[212:215], v[196:199], v[0:3]
	s_barrier
	s_cbranch_scc0 .LBB0_79
	s_cmp_eq_u32 s78, 0
	s_cbranch_scc0 .Lhalf_skip_x_0
	s_barrier

; #define PG8_STAGE(bufoff, gbase, voff) do { _Pragma("unroll") for (int _i = 0; _i < 2; ++_i) \
;         __builtin_amdgcn_global_load_lds((const unsigned*)((const char*)(gbase) + (voff)[_i]), (PG8_LAS unsigned*)(lds + (bufoff) + ldsw + _i * 8192), 16, 0, 0); } while (0)
; #define PG8_LDA(dst, b, h) do { _Pragma("unroll") for (int m = 0; m < 4; ++m) _Pragma("unroll") for (int k = 0; k < 2; ++k) dst[m][k] = *(const PG8_LAS bf16x8*)(lds + PG8_SA(b, h) + aoff + m * 2048 + k * 1024); } while (0)
; #define PG8_LDB(dst, b, h) do { _Pragma("unroll") for (int n = 0; n < 2; ++n) _Pragma("unroll") for (int k = 0; k < 2; ++k) dst[n][k] = *(const PG8_LAS bf16x8*)(lds + PG8_SB(b, h) + boff + n * 2048 + k * 1024); } while (0)
; #define PG8_MMA(ai, bj, At, Bt) do { __builtin_amdgcn_s_setprio(1); _Pragma("unroll") for (int m = 0; m < 4; ++m) _Pragma("unroll") for (int n = 0; n < 2; ++n) _Pragma("unroll") for (int k = 0; k < 2; ++k) \
;         acc[ai][bj][m][n] = __builtin_amdgcn_mfma_f32_16x16x32_bf16(Bt[n][k], At[m][k], acc[ai][bj][m][n], 0, 0, 0); __builtin_amdgcn_s_setprio(0); } while (0)
; #define PG8_WAIT_V(n) asm volatile("s_waitcnt vmcnt(" #n ")" ::: "memory")
; template <class Epi, class Sched>
; __device__ __forceinline__ void gemm_phase(PG8_LAS unsigned char* lds, const Gemm g, const Sched& S, const Epi& E) {
;     ...
;         for (int t = 0; t < nt; t += 2) {
;             const bool last = (t == nt - 2);
;             const char* a1 = cA + (size_t)(t + 1) * kstep;
;             const char* a2 = last ? nA : cA + (size_t)(t + 2) * kstep; const char* b2 = last ? nB : cB + (size_t)(t + 2) * kstepB;
;             const char* a3 = a2 + kstep; const char* b3 = b2 + kstepB;
;             if (last && has_next) S.a_ready(nxt);
;             PG8_LDB(B0, 0, 0); PG8_SCHED; PG8_LDA(At, 0, 0); PG8_STAGE(PG8_SA(1, 1), a1 + hstep, voffA);
;             PG8_WAIT_L(8); PG8_BAR; PG8_WAIT_L(0); PG8_MMA(0, 0, At, B0); PG8_BAR; PG8_SCHED;
;             PG8_LDB(B1, 0, 1); PG8_STAGE(PG8_SB(0, 0), b2, voffB);
;             PG8_BAR; PG8_WAIT_L(0); PG8_MMA(0, 1, At, B1); PG8_BAR;
;             PG8_LDA(At, 0, 1); PG8_STAGE(PG8_SA(0, 0), a2, voffA);
;             PG8_BAR; PG8_WAIT_L(0); PG8_MMA(1, 0, At, B0); PG8_BAR; PG8_SCHED;
;             PG8_STAGE(PG8_SB(0, 1), b2 + hstepB, voffB);
;             PG8_WAIT_V(6); PG8_BAR; PG8_MMA(1, 1, At, B1); PG8_BAR;
.Lhalf_skip_y_1:
.LBB0_155:
	ds_read_b128 v[144:147], v153
	ds_read_b128 v[156:159], v153 offset:1024
	ds_read_b128 v[160:163], v153 offset:2048
	ds_read_b128 v[164:167], v153 offset:3072
	s_add_u32 s26, s24, 0x100
	s_addc_u32 s27, s25, 0
	s_cmpk_eq_i32 s67, 0x52
	s_cselect_b32 s31, s7, s27
	s_cselect_b32 s30, s6, s26
	s_cselect_b32 s29, s9, s66
	s_cselect_b32 s28, s8, s65
	v_lshl_add_u64 v[148:149], s[24:25], 0, v[136:137]
	s_add_i32 m0, s51, 0xc000
	ds_read_b128 v[168:171], v154
	ds_read_b128 v[172:175], v154 offset:1024
	ds_read_b128 v[176:179], v154 offset:2048
	ds_read_b128 v[180:183], v154 offset:3072
	ds_read_b128 v[184:187], v154 offset:4096
	ds_read_b128 v[188:191], v154 offset:5120
	ds_read_b128 v[192:195], v154 offset:6144
	ds_read_b128 v[196:199], v154 offset:7168
	global_load_lds_dwordx4 v[148:149], off
	v_lshl_add_u64 v[148:149], s[24:25], 0, v[138:139]
	s_add_i32 m0, s51, 0xe000
	s_nop 0
	global_load_lds_dwordx4 v[148:149], off
	s_add_i32 s24, s59, s50
	v_lshl_add_u64 v[148:149], s[28:29], 0, v[128:129]
	s_mov_b32 m0, s24
	ds_read_b128 v[200:203], v155
	ds_read_b128 v[204:207], v155 offset:1024
	ds_read_b128 v[208:211], v155 offset:2048
	ds_read_b128 v[212:215], v155 offset:3072
	s_waitcnt vmcnt(8)
	s_waitcnt lgkmcnt(0)
	s_barrier
	v_mfma_f32_16x16x32_bf16 v[124:127], v[144:147], v[168:171], v[124:127]
	v_mfma_f32_16x16x32_bf16 v[120:123], v[160:163], v[168:171], v[120:123]
	v_mfma_f32_16x16x32_bf16 v[108:111], v[144:147], v[176:179], v[108:111]
	v_mfma_f32_16x16x32_bf16 v[104:107], v[160:163], v[176:179], v[104:107]
	v_mfma_f32_16x16x32_bf16 v[92:95], v[144:147], v[184:187], v[92:95]
	v_mfma_f32_16x16x32_bf16 v[88:91], v[160:163], v[184:187], v[88:91]
	v_mfma_f32_16x16x32_bf16 v[76:79], v[144:147], v[192:195], v[76:79]
	v_mfma_f32_16x16x32_bf16 v[72:75], v[160:163], v[192:195], v[72:75]
	v_mfma_f32_16x16x32_bf16 v[124:127], v[156:159], v[172:175], v[124:127]
	v_mfma_f32_16x16x32_bf16 v[120:123], v[164:167], v[172:175], v[120:123]
	v_mfma_f32_16x16x32_bf16 v[108:111], v[156:159], v[180:183], v[108:111]
	v_mfma_f32_16x16x32_bf16 v[104:107], v[164:167], v[180:183], v[104:107]
	v_mfma_f32_16x16x32_bf16 v[92:95], v[156:159], v[188:191], v[92:95]
	v_mfma_f32_16x16x32_bf16 v[88:91], v[164:167], v[188:191], v[88:91]
	v_mfma_f32_16x16x32_bf16 v[76:79], v[156:159], v[196:199], v[76:79]
	v_mfma_f32_16x16x32_bf16 v[72:75], v[164:167], v[196:199], v[72:75]
	v_mfma_f32_16x16x32_bf16 v[116:119], v[200:203], v[168:171], v[116:119]
	v_mfma_f32_16x16x32_bf16 v[112:115], v[208:211], v[168:171], v[112:115]
	v_mfma_f32_16x16x32_bf16 v[100:103], v[200:203], v[176:179], v[100:103]
	v_mfma_f32_16x16x32_bf16 v[96:99], v[208:211], v[176:179], v[96:99]
	v_mfma_f32_16x16x32_bf16 v[84:87], v[200:203], v[184:187], v[84:87]
	v_mfma_f32_16x16x32_bf16 v[80:83], v[208:211], v[184:187], v[80:83]
	v_mfma_f32_16x16x32_bf16 v[68:71], v[200:203], v[192:195], v[68:71]
	v_mfma_f32_16x16x32_bf16 v[64:67], v[208:211], v[192:195], v[64:67]
	v_mfma_f32_16x16x32_bf16 v[116:119], v[204:207], v[172:175], v[116:119]
	v_mfma_f32_16x16x32_bf16 v[112:115], v[212:215], v[172:175], v[112:115]
	v_mfma_f32_16x16x32_bf16 v[100:103], v[204:207], v[180:183], v[100:103]
	v_mfma_f32_16x16x32_bf16 v[96:99], v[212:215], v[180:183], v[96:99]
	v_mfma_f32_16x16x32_bf16 v[84:87], v[204:207], v[188:191], v[84:87]
	v_mfma_f32_16x16x32_bf16 v[80:83], v[212:215], v[188:191], v[80:83]
	v_mfma_f32_16x16x32_bf16 v[68:71], v[204:207], v[196:199], v[68:71]
	v_mfma_f32_16x16x32_bf16 v[64:67], v[212:215], v[196:199], v[64:67]
	s_barrier
	global_load_lds_dwordx4 v[148:149], off
	v_lshl_add_u64 v[148:149], s[28:29], 0, v[132:133]
	s_add_i32 m0, s24, 0x2000
	s_nop 0
	global_load_lds_dwordx4 v[148:149], off
	s_mov_b32 m0, s51
	v_lshl_add_u64 v[148:149], s[30:31], 0, v[130:131]
	ds_read_b128 v[168:171], v154 offset:16384
	ds_read_b128 v[172:175], v154 offset:17408
	ds_read_b128 v[176:179], v154 offset:18432
	ds_read_b128 v[180:183], v154 offset:19456
	ds_read_b128 v[184:187], v154 offset:20480
	ds_read_b128 v[188:191], v154 offset:21504
	ds_read_b128 v[192:195], v154 offset:22528
	ds_read_b128 v[196:199], v154 offset:23552
	global_load_lds_dwordx4 v[148:149], off
	v_lshl_add_u64 v[216:217], s[30:31], 0, v[134:135]
	s_mov_b32 m0, s52
	s_nop 0
	global_load_lds_dwordx4 v[216:217], off
	s_add_u32 s24, s28, 0x4000
	s_addc_u32 s25, s29, 0
	s_add_i32 s68, s60, s50
	v_lshl_add_u64 v[250:251], s[24:25], 0, v[128:129]
	s_mov_b32 m0, s68
	s_nop 0
	global_load_lds_dwordx4 v[250:251], off
	v_lshl_add_u64 v[250:251], s[24:25], 0, v[132:133]
	s_add_i32 m0, s68, 0x2000
	s_nop 0
	global_load_lds_dwordx4 v[250:251], off
	s_waitcnt vmcnt(8)
	s_waitcnt lgkmcnt(0)
	s_barrier
; #define PG8_STAGE(bufoff, gbase, voff) do { _Pragma("unroll") for (int _i = 0; _i < 2; ++_i) \
;         __builtin_amdgcn_global_load_lds((const unsigned*)((const char*)(gbase) + (voff)[_i]), (PG8_LAS unsigned*)(lds + (bufoff) + ldsw + _i * 8192), 16, 0, 0); } while (0)
; #define PG8_LDA(dst, b, h) do { _Pragma("unroll") for (int m = 0; m < 4; ++m) _Pragma("unroll") for (int k = 0; k < 2; ++k) dst[m][k] = *(const PG8_LAS bf16x8*)(lds + PG8_SA(b, h) + aoff + m * 2048 + k * 1024); } while (0)
; #define PG8_LDB(dst, b, h) do { _Pragma("unroll") for (int n = 0; n < 2; ++n) _Pragma("unroll") for (int k = 0; k < 2; ++k) dst[n][k] = *(const PG8_LAS bf16x8*)(lds + PG8_SB(b, h) + boff + n * 2048 + k * 1024); } while (0)
; #define PG8_MMA(ai, bj, At, Bt) do { __builtin_amdgcn_s_setprio(1); _Pragma("unroll") for (int m = 0; m < 4; ++m) _Pragma("unroll") for (int n = 0; n < 2; ++n) _Pragma("unroll") for (int k = 0; k < 2; ++k) \
;         acc[ai][bj][m][n] = __builtin_amdgcn_mfma_f32_16x16x32_bf16(Bt[n][k], At[m][k], acc[ai][bj][m][n], 0, 0, 0); __builtin_amdgcn_s_setprio(0); } while (0)
; #define PG8_WAIT_V(n) asm volatile("s_waitcnt vmcnt(" #n ")" ::: "memory")
; #define PG8_WAIT_L(n) asm volatile("s_waitcnt lgkmcnt(" #n ")" ::: "memory")
; #define PG8_BAR __builtin_amdgcn_s_barrier()
; #define PG8_SCHED __builtin_amdgcn_sched_barrier(0)
; template <class Epi, class Sched>
; __device__ __forceinline__ void gemm_phase(PG8_LAS unsigned char* lds, const Gemm g, const Sched& S, const Epi& E) {
;     ...
;             PG8_BAR; PG8_WAIT_L(0); PG8_MMA(1, 0, At, B0); PG8_BAR; PG8_SCHED;
;             PG8_STAGE(PG8_SB(0, 1), b2 + hstepB, voffB);
;             PG8_WAIT_V(6); PG8_BAR; PG8_MMA(1, 1, At, B1); PG8_BAR;
;             PG8_LDB(B0, 1, 0); PG8_SCHED; PG8_LDA(At, 1, 0); PG8_STAGE(PG8_SA(0, 1), a2 + hstep, voffA);
;             PG8_WAIT_L(8); PG8_BAR; PG8_WAIT_L(0); PG8_MMA(0, 0, At, B0); PG8_BAR; PG8_SCHED;
;             PG8_LDB(B1, 1, 1); PG8_STAGE(PG8_SB(1, 0), b3, voffB);
;             PG8_BAR; PG8_WAIT_L(0); PG8_MMA(0, 1, At, B1); PG8_BAR;
	v_mfma_f32_16x16x32_bf16 v[60:63], v[144:147], v[168:171], v[60:63]
	v_mfma_f32_16x16x32_bf16 v[56:59], v[160:163], v[168:171], v[56:59]
	v_mfma_f32_16x16x32_bf16 v[44:47], v[144:147], v[176:179], v[44:47]
	v_mfma_f32_16x16x32_bf16 v[40:43], v[160:163], v[176:179], v[40:43]
	v_mfma_f32_16x16x32_bf16 v[28:31], v[144:147], v[184:187], v[28:31]
	v_mfma_f32_16x16x32_bf16 v[24:27], v[160:163], v[184:187], v[24:27]
	v_mfma_f32_16x16x32_bf16 v[12:15], v[144:147], v[192:195], v[12:15]
	v_mfma_f32_16x16x32_bf16 v[8:11], v[160:163], v[192:195], v[8:11]
	v_mfma_f32_16x16x32_bf16 v[60:63], v[156:159], v[172:175], v[60:63]
	v_mfma_f32_16x16x32_bf16 v[56:59], v[164:167], v[172:175], v[56:59]
	v_mfma_f32_16x16x32_bf16 v[44:47], v[156:159], v[180:183], v[44:47]
	v_mfma_f32_16x16x32_bf16 v[40:43], v[164:167], v[180:183], v[40:43]
	v_mfma_f32_16x16x32_bf16 v[28:31], v[156:159], v[188:191], v[28:31]
	v_mfma_f32_16x16x32_bf16 v[24:27], v[164:167], v[188:191], v[24:27]
	v_mfma_f32_16x16x32_bf16 v[12:15], v[156:159], v[196:199], v[12:15]
	v_mfma_f32_16x16x32_bf16 v[8:11], v[164:167], v[196:199], v[8:11]
	v_mfma_f32_16x16x32_bf16 v[52:55], v[200:203], v[168:171], v[52:55]
	v_mfma_f32_16x16x32_bf16 v[48:51], v[208:211], v[168:171], v[48:51]
	v_mfma_f32_16x16x32_bf16 v[36:39], v[200:203], v[176:179], v[36:39]
	v_mfma_f32_16x16x32_bf16 v[32:35], v[208:211], v[176:179], v[32:35]
	v_mfma_f32_16x16x32_bf16 v[20:23], v[200:203], v[184:187], v[20:23]
	v_mfma_f32_16x16x32_bf16 v[16:19], v[208:211], v[184:187], v[16:19]
	v_mfma_f32_16x16x32_bf16 v[4:7], v[200:203], v[192:195], v[4:7]
	v_mfma_f32_16x16x32_bf16 v[0:3], v[208:211], v[192:195], v[0:3]
	v_mfma_f32_16x16x32_bf16 v[52:55], v[204:207], v[172:175], v[52:55]
	v_mfma_f32_16x16x32_bf16 v[48:51], v[212:215], v[172:175], v[48:51]
	v_mfma_f32_16x16x32_bf16 v[36:39], v[204:207], v[180:183], v[36:39]
	v_mfma_f32_16x16x32_bf16 v[32:35], v[212:215], v[180:183], v[32:35]
	v_mfma_f32_16x16x32_bf16 v[20:23], v[204:207], v[188:191], v[20:23]
	v_mfma_f32_16x16x32_bf16 v[16:19], v[212:215], v[188:191], v[16:19]
	v_mfma_f32_16x16x32_bf16 v[4:7], v[204:207], v[196:199], v[4:7]
	v_mfma_f32_16x16x32_bf16 v[0:3], v[212:215], v[196:199], v[0:3]
	s_barrier
	s_add_i32 s68, 0, 0x18000
	v_add_u32_e32 v164, s68, v151
	ds_read_b128 v[144:147], v164
	ds_read_b128 v[156:159], v164 offset:1024
	ds_read_b128 v[160:163], v164 offset:2048
	ds_read_b128 v[164:167], v164 offset:3072
	s_add_u32 s24, s30, 0x158000
	s_addc_u32 s25, s31, 0
	s_mov_b32 m0, s53
	v_lshl_add_u64 v[200:201], s[24:25], 0, v[130:131]
	ds_read_b128 v[168:171], v154 offset:32768
	ds_read_b128 v[172:175], v154 offset:33792
	ds_read_b128 v[176:179], v154 offset:34816
	ds_read_b128 v[180:183], v154 offset:35840
	ds_read_b128 v[184:187], v154 offset:36864
	ds_read_b128 v[188:191], v154 offset:37888
	ds_read_b128 v[192:195], v154 offset:38912
	ds_read_b128 v[196:199], v154 offset:39936
	global_load_lds_dwordx4 v[200:201], off
	v_lshl_add_u64 v[200:201], s[24:25], 0, v[134:135]
	s_mov_b32 m0, s54
	s_nop 0
	global_load_lds_dwordx4 v[200:201], off
	s_add_i32 s30, 0, 0x1c000
	s_add_u32 s24, s28, 0x8000
	s_addc_u32 s25, s29, 0
	s_add_i32 s31, s68, s50
	v_add_u32_e32 v212, s30, v151
	v_lshl_add_u64 v[218:219], s[24:25], 0, v[128:129]
	s_mov_b32 m0, s31
	ds_read_b128 v[200:203], v212
	ds_read_b128 v[204:207], v212 offset:1024
	ds_read_b128 v[208:211], v212 offset:2048
	ds_read_b128 v[212:215], v212 offset:3072
	s_waitcnt vmcnt(8)
	s_waitcnt lgkmcnt(0)
	s_barrier
	v_mfma_f32_16x16x32_bf16 v[124:127], v[144:147], v[168:171], v[124:127]
	v_mfma_f32_16x16x32_bf16 v[120:123], v[160:163], v[168:171], v[120:123]
	v_mfma_f32_16x16x32_bf16 v[108:111], v[144:147], v[176:179], v[108:111]
	v_mfma_f32_16x16x32_bf16 v[104:107], v[160:163], v[176:179], v[104:107]
	v_mfma_f32_16x16x32_bf16 v[92:95], v[144:147], v[184:187], v[92:95]
	v_mfma_f32_16x16x32_bf16 v[88:91], v[160:163], v[184:187], v[88:91]
	v_mfma_f32_16x16x32_bf16 v[76:79], v[144:147], v[192:195], v[76:79]
	v_mfma_f32_16x16x32_bf16 v[72:75], v[160:163], v[192:195], v[72:75]
	v_mfma_f32_16x16x32_bf16 v[124:127], v[156:159], v[172:175], v[124:127]
	v_mfma_f32_16x16x32_bf16 v[120:123], v[164:167], v[172:175], v[120:123]
	v_mfma_f32_16x16x32_bf16 v[108:111], v[156:159], v[180:183], v[108:111]
	v_mfma_f32_16x16x32_bf16 v[104:107], v[164:167], v[180:183], v[104:107]
	v_mfma_f32_16x16x32_bf16 v[92:95], v[156:159], v[188:191], v[92:95]
	v_mfma_f32_16x16x32_bf16 v[88:91], v[164:167], v[188:191], v[88:91]
	v_mfma_f32_16x16x32_bf16 v[76:79], v[156:159], v[196:199], v[76:79]
	v_mfma_f32_16x16x32_bf16 v[72:75], v[164:167], v[196:199], v[72:75]
	v_mfma_f32_16x16x32_bf16 v[116:119], v[200:203], v[168:171], v[116:119]
	v_mfma_f32_16x16x32_bf16 v[112:115], v[208:211], v[168:171], v[112:115]
	v_mfma_f32_16x16x32_bf16 v[100:103], v[200:203], v[176:179], v[100:103]
	v_mfma_f32_16x16x32_bf16 v[96:99], v[208:211], v[176:179], v[96:99]
	v_mfma_f32_16x16x32_bf16 v[84:87], v[200:203], v[184:187], v[84:87]
	v_mfma_f32_16x16x32_bf16 v[80:83], v[208:211], v[184:187], v[80:83]
	v_mfma_f32_16x16x32_bf16 v[68:71], v[200:203], v[192:195], v[68:71]
	v_mfma_f32_16x16x32_bf16 v[64:67], v[208:211], v[192:195], v[64:67]
	v_mfma_f32_16x16x32_bf16 v[116:119], v[204:207], v[172:175], v[116:119]
	v_mfma_f32_16x16x32_bf16 v[112:115], v[212:215], v[172:175], v[112:115]
	v_mfma_f32_16x16x32_bf16 v[100:103], v[204:207], v[180:183], v[100:103]
	v_mfma_f32_16x16x32_bf16 v[96:99], v[212:215], v[180:183], v[96:99]
	v_mfma_f32_16x16x32_bf16 v[84:87], v[204:207], v[188:191], v[84:87]
	v_mfma_f32_16x16x32_bf16 v[80:83], v[212:215], v[188:191], v[80:83]
	v_mfma_f32_16x16x32_bf16 v[68:71], v[204:207], v[196:199], v[68:71]
	v_mfma_f32_16x16x32_bf16 v[64:67], v[212:215], v[196:199], v[64:67]
	s_barrier
; #define PG8_STAGE(bufoff, gbase, voff) do { _Pragma("unroll") for (int _i = 0; _i < 2; ++_i) \
;         __builtin_amdgcn_global_load_lds((const unsigned*)((const char*)(gbase) + (voff)[_i]), (PG8_LAS unsigned*)(lds + (bufoff) + ldsw + _i * 8192), 16, 0, 0); } while (0)
; #define PG8_LDA(dst, b, h) do { _Pragma("unroll") for (int m = 0; m < 4; ++m) _Pragma("unroll") for (int k = 0; k < 2; ++k) dst[m][k] = *(const PG8_LAS bf16x8*)(lds + PG8_SA(b, h) + aoff + m * 2048 + k * 1024); } while (0)
; #define PG8_LDB(dst, b, h) do { _Pragma("unroll") for (int n = 0; n < 2; ++n) _Pragma("unroll") for (int k = 0; k < 2; ++k) dst[n][k] = *(const PG8_LAS bf16x8*)(lds + PG8_SB(b, h) + boff + n * 2048 + k * 1024); } while (0)
; #define PG8_MMA(ai, bj, At, Bt) do { __builtin_amdgcn_s_setprio(1); _Pragma("unroll") for (int m = 0; m < 4; ++m) _Pragma("unroll") for (int n = 0; n < 2; ++n) _Pragma("unroll") for (int k = 0; k < 2; ++k) \
;         acc[ai][bj][m][n] = __builtin_amdgcn_mfma_f32_16x16x32_bf16(Bt[n][k], At[m][k], acc[ai][bj][m][n], 0, 0, 0); __builtin_amdgcn_s_setprio(0); } while (0)
; #define PG8_WAIT_V(n) asm volatile("s_waitcnt vmcnt(" #n ")" ::: "memory")
; #define PG8_WAIT_L(n) asm volatile("s_waitcnt lgkmcnt(" #n ")" ::: "memory")
; #define PG8_BAR __builtin_amdgcn_s_barrier()
; #define PG8_SCHED __builtin_amdgcn_sched_barrier(0)
; template <class Epi, class Sched>
; __device__ __forceinline__ void gemm_phase(PG8_LAS unsigned char* lds, const Gemm g, const Sched& S, const Epi& E) {
;     ...
;             PG8_LDB(B1, 1, 1); PG8_STAGE(PG8_SB(1, 0), b3, voffB);
;             PG8_BAR; PG8_WAIT_L(0); PG8_MMA(0, 1, At, B1); PG8_BAR;
;             PG8_LDA(At, 1, 1); PG8_STAGE(PG8_SA(1, 0), a3, voffA);
;             PG8_BAR; PG8_WAIT_L(0); PG8_MMA(1, 0, At, B0); PG8_BAR; PG8_SCHED;
;             PG8_STAGE(PG8_SB(1, 1), b3 + hstepB, voffB);
;             PG8_WAIT_V(6); PG8_BAR; PG8_MMA(1, 1, At, B1); PG8_BAR;
;         }
	global_load_lds_dwordx4 v[218:219], off
	v_lshl_add_u64 v[218:219], s[24:25], 0, v[132:133]
	s_add_i32 m0, s31, 0x2000
	s_nop 0
	global_load_lds_dwordx4 v[218:219], off
	s_mov_b32 m0, s56
	v_lshl_add_u64 v[148:149], v[148:149], 0, s[14:15]
	ds_read_b128 v[168:171], v154 offset:49152
	ds_read_b128 v[172:175], v154 offset:50176
	ds_read_b128 v[176:179], v154 offset:51200
	ds_read_b128 v[180:183], v154 offset:52224
	ds_read_b128 v[184:187], v154 offset:53248
	ds_read_b128 v[188:191], v154 offset:54272
	ds_read_b128 v[192:195], v154 offset:55296
	ds_read_b128 v[196:199], v154 offset:56320
	global_load_lds_dwordx4 v[148:149], off
	v_lshl_add_u64 v[148:149], v[216:217], 0, s[14:15]
	s_mov_b32 m0, s57
	s_nop 0
	global_load_lds_dwordx4 v[148:149], off
	s_add_u32 s24, s28, 0xc000
	s_addc_u32 s25, s29, 0
	s_add_i32 s28, s30, s50
	v_lshl_add_u64 v[252:253], s[24:25], 0, v[128:129]
	s_mov_b32 m0, s28
	s_nop 0
	global_load_lds_dwordx4 v[252:253], off
	v_lshl_add_u64 v[252:253], s[24:25], 0, v[132:133]
	s_add_i32 m0, s28, 0x2000
	s_nop 0
	global_load_lds_dwordx4 v[252:253], off
	s_add_i32 s67, s67, 2
	s_add_u32 s65, s65, 0x10000
	s_addc_u32 s66, s66, 0
	s_cmpk_gt_u32 s67, 0x53
	s_mov_b64 s[24:25], s[26:27]
	s_waitcnt vmcnt(8)
	s_waitcnt lgkmcnt(0)
	s_barrier
	v_mfma_f32_16x16x32_bf16 v[60:63], v[144:147], v[168:171], v[60:63]
	v_mfma_f32_16x16x32_bf16 v[56:59], v[160:163], v[168:171], v[56:59]
	v_mfma_f32_16x16x32_bf16 v[44:47], v[144:147], v[176:179], v[44:47]
	v_mfma_f32_16x16x32_bf16 v[40:43], v[160:163], v[176:179], v[40:43]
	v_mfma_f32_16x16x32_bf16 v[28:31], v[144:147], v[184:187], v[28:31]
	v_mfma_f32_16x16x32_bf16 v[24:27], v[160:163], v[184:187], v[24:27]
	v_mfma_f32_16x16x32_bf16 v[12:15], v[144:147], v[192:195], v[12:15]
	v_mfma_f32_16x16x32_bf16 v[8:11], v[160:163], v[192:195], v[8:11]
	v_mfma_f32_16x16x32_bf16 v[60:63], v[156:159], v[172:175], v[60:63]
	v_mfma_f32_16x16x32_bf16 v[56:59], v[164:167], v[172:175], v[56:59]
	v_mfma_f32_16x16x32_bf16 v[44:47], v[156:159], v[180:183], v[44:47]
	v_mfma_f32_16x16x32_bf16 v[40:43], v[164:167], v[180:183], v[40:43]
	v_mfma_f32_16x16x32_bf16 v[28:31], v[156:159], v[188:191], v[28:31]
	v_mfma_f32_16x16x32_bf16 v[24:27], v[164:167], v[188:191], v[24:27]
	v_mfma_f32_16x16x32_bf16 v[12:15], v[156:159], v[196:199], v[12:15]
	v_mfma_f32_16x16x32_bf16 v[8:11], v[164:167], v[196:199], v[8:11]
	v_mfma_f32_16x16x32_bf16 v[52:55], v[200:203], v[168:171], v[52:55]
	v_mfma_f32_16x16x32_bf16 v[48:51], v[208:211], v[168:171], v[48:51]
	v_mfma_f32_16x16x32_bf16 v[36:39], v[200:203], v[176:179], v[36:39]
	v_mfma_f32_16x16x32_bf16 v[32:35], v[208:211], v[176:179], v[32:35]
	v_mfma_f32_16x16x32_bf16 v[20:23], v[200:203], v[184:187], v[20:23]
	v_mfma_f32_16x16x32_bf16 v[16:19], v[208:211], v[184:187], v[16:19]
	v_mfma_f32_16x16x32_bf16 v[4:7], v[200:203], v[192:195], v[4:7]
	v_mfma_f32_16x16x32_bf16 v[0:3], v[208:211], v[192:195], v[0:3]
	v_mfma_f32_16x16x32_bf16 v[52:55], v[204:207], v[172:175], v[52:55]
	v_mfma_f32_16x16x32_bf16 v[48:51], v[212:215], v[172:175], v[48:51]
	v_mfma_f32_16x16x32_bf16 v[36:39], v[204:207], v[180:183], v[36:39]
	v_mfma_f32_16x16x32_bf16 v[32:35], v[212:215], v[180:183], v[32:35]
	v_mfma_f32_16x16x32_bf16 v[20:23], v[204:207], v[188:191], v[20:23]
	v_mfma_f32_16x16x32_bf16 v[16:19], v[212:215], v[188:191], v[16:19]
	v_mfma_f32_16x16x32_bf16 v[4:7], v[204:207], v[196:199], v[4:7]
	v_mfma_f32_16x16x32_bf16 v[0:3], v[212:215], v[196:199], v[0:3]
	s_barrier
	s_cbranch_scc0 .LBB0_155
	s_cmp_eq_u32 s78, 0
	s_cbranch_scc0 .Lhalf_skip_x_1
	s_barrier

; #define PG8_STAGE(bufoff, gbase, voff) do { _Pragma("unroll") for (int _i = 0; _i < 2; ++_i) \
;         __builtin_amdgcn_global_load_lds((const unsigned*)((const char*)(gbase) + (voff)[_i]), (PG8_LAS unsigned*)(lds + (bufoff) + ldsw + _i * 8192), 16, 0, 0); } while (0)
; #define PG8_LDA(dst, b, h) do { _Pragma("unroll") for (int m = 0; m < 4; ++m) _Pragma("unroll") for (int k = 0; k < 2; ++k) dst[m][k] = *(const PG8_LAS bf16x8*)(lds + PG8_SA(b, h) + aoff + m * 2048 + k * 1024); } while (0)
; #define PG8_LDB(dst, b, h) do { _Pragma("unroll") for (int n = 0; n < 2; ++n) _Pragma("unroll") for (int k = 0; k < 2; ++k) dst[n][k] = *(const PG8_LAS bf16x8*)(lds + PG8_SB(b, h) + boff + n * 2048 + k * 1024); } while (0)
; #define PG8_MMA(ai, bj, At, Bt) do { __builtin_amdgcn_s_setprio(1); _Pragma("unroll") for (int m = 0; m < 4; ++m) _Pragma("unroll") for (int n = 0; n < 2; ++n) _Pragma("unroll") for (int k = 0; k < 2; ++k) \
;         acc[ai][bj][m][n] = __builtin_amdgcn_mfma_f32_16x16x32_bf16(Bt[n][k], At[m][k], acc[ai][bj][m][n], 0, 0, 0); __builtin_amdgcn_s_setprio(0); } while (0)
; #define PG8_WAIT_V(n) asm volatile("s_waitcnt vmcnt(" #n ")" ::: "memory")
; template <class Epi, class Sched>
; __device__ __forceinline__ void gemm_phase(PG8_LAS unsigned char* lds, const Gemm g, const Sched& S, const Epi& E) {
;     ...
;         for (int t = 0; t < nt; t += 2) {
;             const bool last = (t == nt - 2);
;             const char* a1 = cA + (size_t)(t + 1) * kstep;
;             const char* a2 = last ? nA : cA + (size_t)(t + 2) * kstep; const char* b2 = last ? nB : cB + (size_t)(t + 2) * kstepB;
;             const char* a3 = a2 + kstep; const char* b3 = b2 + kstepB;
;             if (last && has_next) S.a_ready(nxt);
;             PG8_LDB(B0, 0, 0); PG8_SCHED; PG8_LDA(At, 0, 0); PG8_STAGE(PG8_SA(1, 1), a1 + hstep, voffA);
;             PG8_WAIT_L(8); PG8_BAR; PG8_WAIT_L(0); PG8_MMA(0, 0, At, B0); PG8_BAR; PG8_SCHED;
;             PG8_LDB(B1, 0, 1); PG8_STAGE(PG8_SB(0, 0), b2, voffB);
;             PG8_BAR; PG8_WAIT_L(0); PG8_MMA(0, 1, At, B1); PG8_BAR;
;             PG8_LDA(At, 0, 1); PG8_STAGE(PG8_SA(0, 0), a2, voffA);
;             PG8_BAR; PG8_WAIT_L(0); PG8_MMA(1, 0, At, B0); PG8_BAR; PG8_SCHED;
;             PG8_STAGE(PG8_SB(0, 1), b2 + hstepB, voffB);
;             PG8_WAIT_V(6); PG8_BAR; PG8_MMA(1, 1, At, B1); PG8_BAR;
.Lhalf_skip_y_2:
.LBB0_280:
	ds_read_b128 v[150:153], v147
	ds_read_b128 v[154:157], v147 offset:1024
	ds_read_b128 v[158:161], v147 offset:2048
	ds_read_b128 v[162:165], v147 offset:3072
	s_add_u32 s48, s6, 0xfff80080
	s_addc_u32 s49, s7, -1
	s_cmp_eq_u32 s69, 28
	s_cselect_b32 s51, s9, s49
	s_cselect_b32 s50, s29, s48
	s_cselect_b32 s49, s31, s68
	s_cselect_b32 s48, s47, s67
	v_lshl_add_u64 v[198:199], s[6:7], 0, v[136:137]
	s_add_i32 m0, s54, 0xc000
	ds_read_b128 v[166:169], v148
	ds_read_b128 v[170:173], v148 offset:1024
	ds_read_b128 v[174:177], v148 offset:2048
	ds_read_b128 v[178:181], v148 offset:3072
	ds_read_b128 v[182:185], v148 offset:4096
	ds_read_b128 v[186:189], v148 offset:5120
	ds_read_b128 v[190:193], v148 offset:6144
	ds_read_b128 v[194:197], v148 offset:7168
	global_load_lds_dwordx4 v[198:199], off
	v_lshl_add_u64 v[198:199], s[6:7], 0, v[138:139]
	s_add_i32 m0, s54, 0xe000
	s_nop 0
	global_load_lds_dwordx4 v[198:199], off
	s_add_i32 s70, s63, s53
	v_lshl_add_u64 v[214:215], s[48:49], 0, v[128:129]
	s_mov_b32 m0, s70
	ds_read_b128 v[198:201], v149
	ds_read_b128 v[202:205], v149 offset:1024
	ds_read_b128 v[206:209], v149 offset:2048
	ds_read_b128 v[210:213], v149 offset:3072
	s_waitcnt vmcnt(8)
	s_waitcnt lgkmcnt(0)
	s_barrier
	v_mfma_f32_16x16x32_bf16 v[124:127], v[150:153], v[166:169], v[124:127]
	v_mfma_f32_16x16x32_bf16 v[120:123], v[158:161], v[166:169], v[120:123]
	v_mfma_f32_16x16x32_bf16 v[108:111], v[150:153], v[174:177], v[108:111]
	v_mfma_f32_16x16x32_bf16 v[104:107], v[158:161], v[174:177], v[104:107]
	v_mfma_f32_16x16x32_bf16 v[92:95], v[150:153], v[182:185], v[92:95]
	v_mfma_f32_16x16x32_bf16 v[88:91], v[158:161], v[182:185], v[88:91]
	v_mfma_f32_16x16x32_bf16 v[76:79], v[150:153], v[190:193], v[76:79]
	v_mfma_f32_16x16x32_bf16 v[72:75], v[158:161], v[190:193], v[72:75]
	v_mfma_f32_16x16x32_bf16 v[124:127], v[154:157], v[170:173], v[124:127]
	v_mfma_f32_16x16x32_bf16 v[120:123], v[162:165], v[170:173], v[120:123]
	v_mfma_f32_16x16x32_bf16 v[108:111], v[154:157], v[178:181], v[108:111]
	v_mfma_f32_16x16x32_bf16 v[104:107], v[162:165], v[178:181], v[104:107]
	v_mfma_f32_16x16x32_bf16 v[92:95], v[154:157], v[186:189], v[92:95]
	v_mfma_f32_16x16x32_bf16 v[88:91], v[162:165], v[186:189], v[88:91]
	v_mfma_f32_16x16x32_bf16 v[76:79], v[154:157], v[194:197], v[76:79]
	v_mfma_f32_16x16x32_bf16 v[72:75], v[162:165], v[194:197], v[72:75]
	v_mfma_f32_16x16x32_bf16 v[116:119], v[198:201], v[166:169], v[116:119]
	v_mfma_f32_16x16x32_bf16 v[112:115], v[206:209], v[166:169], v[112:115]
	v_mfma_f32_16x16x32_bf16 v[100:103], v[198:201], v[174:177], v[100:103]
	v_mfma_f32_16x16x32_bf16 v[96:99], v[206:209], v[174:177], v[96:99]
	v_mfma_f32_16x16x32_bf16 v[84:87], v[198:201], v[182:185], v[84:87]
	v_mfma_f32_16x16x32_bf16 v[80:83], v[206:209], v[182:185], v[80:83]
	v_mfma_f32_16x16x32_bf16 v[68:71], v[198:201], v[190:193], v[68:71]
	v_mfma_f32_16x16x32_bf16 v[64:67], v[206:209], v[190:193], v[64:67]
	v_mfma_f32_16x16x32_bf16 v[116:119], v[202:205], v[170:173], v[116:119]
	v_mfma_f32_16x16x32_bf16 v[112:115], v[210:213], v[170:173], v[112:115]
	v_mfma_f32_16x16x32_bf16 v[100:103], v[202:205], v[178:181], v[100:103]
	v_mfma_f32_16x16x32_bf16 v[96:99], v[210:213], v[178:181], v[96:99]
	v_mfma_f32_16x16x32_bf16 v[84:87], v[202:205], v[186:189], v[84:87]
	v_mfma_f32_16x16x32_bf16 v[80:83], v[210:213], v[186:189], v[80:83]
	v_mfma_f32_16x16x32_bf16 v[68:71], v[202:205], v[194:197], v[68:71]
	v_mfma_f32_16x16x32_bf16 v[64:67], v[210:213], v[194:197], v[64:67]
	s_barrier
	global_load_lds_dwordx4 v[214:215], off
	v_lshl_add_u64 v[214:215], s[48:49], 0, v[132:133]
	s_add_i32 m0, s70, 0x2000
	s_nop 0
	global_load_lds_dwordx4 v[214:215], off
	s_mov_b32 m0, s54
	v_lshl_add_u64 v[214:215], s[50:51], 0, v[130:131]
	ds_read_b128 v[166:169], v148 offset:16384
	ds_read_b128 v[170:173], v148 offset:17408
	ds_read_b128 v[174:177], v148 offset:18432
	ds_read_b128 v[178:181], v148 offset:19456
	ds_read_b128 v[182:185], v148 offset:20480
	ds_read_b128 v[186:189], v148 offset:21504
	ds_read_b128 v[190:193], v148 offset:22528
	ds_read_b128 v[194:197], v148 offset:23552
	global_load_lds_dwordx4 v[214:215], off
	v_lshl_add_u64 v[216:217], s[50:51], 0, v[134:135]
	s_mov_b32 m0, s55
	s_nop 0
	global_load_lds_dwordx4 v[216:217], off
	s_add_u32 s70, s48, 0x4000
	s_addc_u32 s71, s49, 0
	s_add_i32 s72, s64, s53
	v_lshl_add_u64 v[250:251], s[70:71], 0, v[128:129]
	s_mov_b32 m0, s72
	s_nop 0
	global_load_lds_dwordx4 v[250:251], off
	v_lshl_add_u64 v[250:251], s[70:71], 0, v[132:133]
	s_add_i32 m0, s72, 0x2000
	s_nop 0
	global_load_lds_dwordx4 v[250:251], off
	s_waitcnt vmcnt(8)
	s_waitcnt lgkmcnt(0)
	s_barrier
; #define PG8_STAGE(bufoff, gbase, voff) do { _Pragma("unroll") for (int _i = 0; _i < 2; ++_i) \
;         __builtin_amdgcn_global_load_lds((const unsigned*)((const char*)(gbase) + (voff)[_i]), (PG8_LAS unsigned*)(lds + (bufoff) + ldsw + _i * 8192), 16, 0, 0); } while (0)
; #define PG8_LDA(dst, b, h) do { _Pragma("unroll") for (int m = 0; m < 4; ++m) _Pragma("unroll") for (int k = 0; k < 2; ++k) dst[m][k] = *(const PG8_LAS bf16x8*)(lds + PG8_SA(b, h) + aoff + m * 2048 + k * 1024); } while (0)
; #define PG8_LDB(dst, b, h) do { _Pragma("unroll") for (int n = 0; n < 2; ++n) _Pragma("unroll") for (int k = 0; k < 2; ++k) dst[n][k] = *(const PG8_LAS bf16x8*)(lds + PG8_SB(b, h) + boff + n * 2048 + k * 1024); } while (0)
; #define PG8_MMA(ai, bj, At, Bt) do { __builtin_amdgcn_s_setprio(1); _Pragma("unroll") for (int m = 0; m < 4; ++m) _Pragma("unroll") for (int n = 0; n < 2; ++n) _Pragma("unroll") for (int k = 0; k < 2; ++k) \
;         acc[ai][bj][m][n] = __builtin_amdgcn_mfma_f32_16x16x32_bf16(Bt[n][k], At[m][k], acc[ai][bj][m][n], 0, 0, 0); __builtin_amdgcn_s_setprio(0); } while (0)
; #define PG8_WAIT_V(n) asm volatile("s_waitcnt vmcnt(" #n ")" ::: "memory")
; #define PG8_WAIT_L(n) asm volatile("s_waitcnt lgkmcnt(" #n ")" ::: "memory")
; #define PG8_BAR __builtin_amdgcn_s_barrier()
; #define PG8_SCHED __builtin_amdgcn_sched_barrier(0)
; template <class Epi, class Sched>
; __device__ __forceinline__ void gemm_phase(PG8_LAS unsigned char* lds, const Gemm g, const Sched& S, const Epi& E) {
;     ...
;             PG8_BAR; PG8_WAIT_L(0); PG8_MMA(1, 0, At, B0); PG8_BAR; PG8_SCHED;
;             PG8_STAGE(PG8_SB(0, 1), b2 + hstepB, voffB);
;             PG8_WAIT_V(6); PG8_BAR; PG8_MMA(1, 1, At, B1); PG8_BAR;
;             PG8_LDB(B0, 1, 0); PG8_SCHED; PG8_LDA(At, 1, 0); PG8_STAGE(PG8_SA(0, 1), a2 + hstep, voffA);
;             PG8_WAIT_L(8); PG8_BAR; PG8_WAIT_L(0); PG8_MMA(0, 0, At, B0); PG8_BAR; PG8_SCHED;
;             PG8_LDB(B1, 1, 1); PG8_STAGE(PG8_SB(1, 0), b3, voffB);
;             PG8_BAR; PG8_WAIT_L(0); PG8_MMA(0, 1, At, B1); PG8_BAR;
;             PG8_LDA(At, 1, 1); PG8_STAGE(PG8_SA(1, 0), a3, voffA);
;             PG8_BAR; PG8_WAIT_L(0); PG8_MMA(1, 0, At, B0); PG8_BAR; PG8_SCHED;
	v_mfma_f32_16x16x32_bf16 v[60:63], v[150:153], v[166:169], v[60:63]
	v_mfma_f32_16x16x32_bf16 v[56:59], v[158:161], v[166:169], v[56:59]
	v_mfma_f32_16x16x32_bf16 v[44:47], v[150:153], v[174:177], v[44:47]
	v_mfma_f32_16x16x32_bf16 v[40:43], v[158:161], v[174:177], v[40:43]
	v_mfma_f32_16x16x32_bf16 v[28:31], v[150:153], v[182:185], v[28:31]
	v_mfma_f32_16x16x32_bf16 v[24:27], v[158:161], v[182:185], v[24:27]
	v_mfma_f32_16x16x32_bf16 v[12:15], v[150:153], v[190:193], v[12:15]
	v_mfma_f32_16x16x32_bf16 v[8:11], v[158:161], v[190:193], v[8:11]
	v_mfma_f32_16x16x32_bf16 v[60:63], v[154:157], v[170:173], v[60:63]
	v_mfma_f32_16x16x32_bf16 v[56:59], v[162:165], v[170:173], v[56:59]
	v_mfma_f32_16x16x32_bf16 v[44:47], v[154:157], v[178:181], v[44:47]
	v_mfma_f32_16x16x32_bf16 v[40:43], v[162:165], v[178:181], v[40:43]
	v_mfma_f32_16x16x32_bf16 v[28:31], v[154:157], v[186:189], v[28:31]
	v_mfma_f32_16x16x32_bf16 v[24:27], v[162:165], v[186:189], v[24:27]
	v_mfma_f32_16x16x32_bf16 v[12:15], v[154:157], v[194:197], v[12:15]
	v_mfma_f32_16x16x32_bf16 v[8:11], v[162:165], v[194:197], v[8:11]
	v_mfma_f32_16x16x32_bf16 v[52:55], v[198:201], v[166:169], v[52:55]
	v_mfma_f32_16x16x32_bf16 v[48:51], v[206:209], v[166:169], v[48:51]
	v_mfma_f32_16x16x32_bf16 v[36:39], v[198:201], v[174:177], v[36:39]
	v_mfma_f32_16x16x32_bf16 v[32:35], v[206:209], v[174:177], v[32:35]
	v_mfma_f32_16x16x32_bf16 v[20:23], v[198:201], v[182:185], v[20:23]
	v_mfma_f32_16x16x32_bf16 v[16:19], v[206:209], v[182:185], v[16:19]
	v_mfma_f32_16x16x32_bf16 v[4:7], v[198:201], v[190:193], v[4:7]
	v_mfma_f32_16x16x32_bf16 v[0:3], v[206:209], v[190:193], v[0:3]
	v_mfma_f32_16x16x32_bf16 v[52:55], v[202:205], v[170:173], v[52:55]
	v_mfma_f32_16x16x32_bf16 v[48:51], v[210:213], v[170:173], v[48:51]
	v_mfma_f32_16x16x32_bf16 v[36:39], v[202:205], v[178:181], v[36:39]
	v_mfma_f32_16x16x32_bf16 v[32:35], v[210:213], v[178:181], v[32:35]
	v_mfma_f32_16x16x32_bf16 v[20:23], v[202:205], v[186:189], v[20:23]
	v_mfma_f32_16x16x32_bf16 v[16:19], v[210:213], v[186:189], v[16:19]
	v_mfma_f32_16x16x32_bf16 v[4:7], v[202:205], v[194:197], v[4:7]
	v_mfma_f32_16x16x32_bf16 v[0:3], v[210:213], v[194:197], v[0:3]
	s_barrier
	s_add_i32 s70, 0, 0x18000
	v_add_u32_e32 v162, s70, v145
	ds_read_b128 v[150:153], v162
	ds_read_b128 v[154:157], v162 offset:1024
	ds_read_b128 v[158:161], v162 offset:2048
	ds_read_b128 v[162:165], v162 offset:3072
	s_add_u32 s50, s50, 0x80000
	s_addc_u32 s51, s51, 0
	s_mov_b32 m0, s56
	v_lshl_add_u64 v[198:199], s[50:51], 0, v[130:131]
	ds_read_b128 v[166:169], v148 offset:32768
	ds_read_b128 v[170:173], v148 offset:33792
	ds_read_b128 v[174:177], v148 offset:34816
	ds_read_b128 v[178:181], v148 offset:35840
	ds_read_b128 v[182:185], v148 offset:36864
	ds_read_b128 v[186:189], v148 offset:37888
	ds_read_b128 v[190:193], v148 offset:38912
	ds_read_b128 v[194:197], v148 offset:39936
	global_load_lds_dwordx4 v[198:199], off
	v_lshl_add_u64 v[198:199], s[50:51], 0, v[134:135]
	s_mov_b32 m0, s57
	s_nop 0
	global_load_lds_dwordx4 v[198:199], off
	s_add_i32 s71, 0, 0x1c000
	s_add_u32 s50, s48, 0x8000
	s_addc_u32 s51, s49, 0
	s_add_i32 s70, s70, s53
	v_add_u32_e32 v210, s71, v145
	v_lshl_add_u64 v[218:219], s[50:51], 0, v[128:129]
	s_mov_b32 m0, s70
	ds_read_b128 v[198:201], v210
	ds_read_b128 v[202:205], v210 offset:1024
	ds_read_b128 v[206:209], v210 offset:2048
	ds_read_b128 v[210:213], v210 offset:3072
	s_waitcnt vmcnt(8)
	s_waitcnt lgkmcnt(0)
	s_barrier
	v_mfma_f32_16x16x32_bf16 v[124:127], v[150:153], v[166:169], v[124:127]
	v_mfma_f32_16x16x32_bf16 v[120:123], v[158:161], v[166:169], v[120:123]
	v_mfma_f32_16x16x32_bf16 v[108:111], v[150:153], v[174:177], v[108:111]
	v_mfma_f32_16x16x32_bf16 v[104:107], v[158:161], v[174:177], v[104:107]
	v_mfma_f32_16x16x32_bf16 v[92:95], v[150:153], v[182:185], v[92:95]
	v_mfma_f32_16x16x32_bf16 v[88:91], v[158:161], v[182:185], v[88:91]
	v_mfma_f32_16x16x32_bf16 v[76:79], v[150:153], v[190:193], v[76:79]
	v_mfma_f32_16x16x32_bf16 v[72:75], v[158:161], v[190:193], v[72:75]
	v_mfma_f32_16x16x32_bf16 v[124:127], v[154:157], v[170:173], v[124:127]
	v_mfma_f32_16x16x32_bf16 v[120:123], v[162:165], v[170:173], v[120:123]
	v_mfma_f32_16x16x32_bf16 v[108:111], v[154:157], v[178:181], v[108:111]
	v_mfma_f32_16x16x32_bf16 v[104:107], v[162:165], v[178:181], v[104:107]
	v_mfma_f32_16x16x32_bf16 v[92:95], v[154:157], v[186:189], v[92:95]
	v_mfma_f32_16x16x32_bf16 v[88:91], v[162:165], v[186:189], v[88:91]
	v_mfma_f32_16x16x32_bf16 v[76:79], v[154:157], v[194:197], v[76:79]
	v_mfma_f32_16x16x32_bf16 v[72:75], v[162:165], v[194:197], v[72:75]
	v_mfma_f32_16x16x32_bf16 v[116:119], v[198:201], v[166:169], v[116:119]
	v_mfma_f32_16x16x32_bf16 v[112:115], v[206:209], v[166:169], v[112:115]
	v_mfma_f32_16x16x32_bf16 v[100:103], v[198:201], v[174:177], v[100:103]
	v_mfma_f32_16x16x32_bf16 v[96:99], v[206:209], v[174:177], v[96:99]
	v_mfma_f32_16x16x32_bf16 v[84:87], v[198:201], v[182:185], v[84:87]
	v_mfma_f32_16x16x32_bf16 v[80:83], v[206:209], v[182:185], v[80:83]
	v_mfma_f32_16x16x32_bf16 v[68:71], v[198:201], v[190:193], v[68:71]
	v_mfma_f32_16x16x32_bf16 v[64:67], v[206:209], v[190:193], v[64:67]
	v_mfma_f32_16x16x32_bf16 v[116:119], v[202:205], v[170:173], v[116:119]
	v_mfma_f32_16x16x32_bf16 v[112:115], v[210:213], v[170:173], v[112:115]
	v_mfma_f32_16x16x32_bf16 v[100:103], v[202:205], v[178:181], v[100:103]
	v_mfma_f32_16x16x32_bf16 v[96:99], v[210:213], v[178:181], v[96:99]
	v_mfma_f32_16x16x32_bf16 v[84:87], v[202:205], v[186:189], v[84:87]
	v_mfma_f32_16x16x32_bf16 v[80:83], v[210:213], v[186:189], v[80:83]
	v_mfma_f32_16x16x32_bf16 v[68:71], v[202:205], v[194:197], v[68:71]
	v_mfma_f32_16x16x32_bf16 v[64:67], v[210:213], v[194:197], v[64:67]
	s_barrier
; #define PG8_STAGE(bufoff, gbase, voff) do { _Pragma("unroll") for (int _i = 0; _i < 2; ++_i) \
;         __builtin_amdgcn_global_load_lds((const unsigned*)((const char*)(gbase) + (voff)[_i]), (PG8_LAS unsigned*)(lds + (bufoff) + ldsw + _i * 8192), 16, 0, 0); } while (0)
; #define PG8_LDA(dst, b, h) do { _Pragma("unroll") for (int m = 0; m < 4; ++m) _Pragma("unroll") for (int k = 0; k < 2; ++k) dst[m][k] = *(const PG8_LAS bf16x8*)(lds + PG8_SA(b, h) + aoff + m * 2048 + k * 1024); } while (0)
; #define PG8_MMA(ai, bj, At, Bt) do { __builtin_amdgcn_s_setprio(1); _Pragma("unroll") for (int m = 0; m < 4; ++m) _Pragma("unroll") for (int n = 0; n < 2; ++n) _Pragma("unroll") for (int k = 0; k < 2; ++k) \
;         acc[ai][bj][m][n] = __builtin_amdgcn_mfma_f32_16x16x32_bf16(Bt[n][k], At[m][k], acc[ai][bj][m][n], 0, 0, 0); __builtin_amdgcn_s_setprio(0); } while (0)
; #define PG8_WAIT_V(n) asm volatile("s_waitcnt vmcnt(" #n ")" ::: "memory")
; #define PG8_WAIT_L(n) asm volatile("s_waitcnt lgkmcnt(" #n ")" ::: "memory")
; #define PG8_BAR __builtin_amdgcn_s_barrier()
; #define PG8_SCHED __builtin_amdgcn_sched_barrier(0)
; template <class Epi, class Sched>
; __device__ __forceinline__ void gemm_phase(PG8_LAS unsigned char* lds, const Gemm g, const Sched& S, const Epi& E) {
;     ...
;             PG8_LDA(At, 1, 1); PG8_STAGE(PG8_SA(1, 0), a3, voffA);
;             PG8_BAR; PG8_WAIT_L(0); PG8_MMA(1, 0, At, B0); PG8_BAR; PG8_SCHED;
;             PG8_STAGE(PG8_SB(1, 1), b3 + hstepB, voffB);
;             PG8_WAIT_V(6); PG8_BAR; PG8_MMA(1, 1, At, B1); PG8_BAR;
;     ...
;     PG8_WAIT_V(0);
;     if (wr == 0) PG8_BAR;
;     PG8_BAR;
	global_load_lds_dwordx4 v[218:219], off
	v_lshl_add_u64 v[218:219], s[50:51], 0, v[132:133]
	s_add_i32 m0, s70, 0x2000
	s_nop 0
	global_load_lds_dwordx4 v[218:219], off
	s_mov_b32 m0, s59
	v_lshl_add_u64 v[214:215], v[214:215], 0, s[12:13]
	ds_read_b128 v[166:169], v148 offset:49152
	ds_read_b128 v[170:173], v148 offset:50176
	ds_read_b128 v[174:177], v148 offset:51200
	ds_read_b128 v[178:181], v148 offset:52224
	ds_read_b128 v[182:185], v148 offset:53248
	ds_read_b128 v[186:189], v148 offset:54272
	ds_read_b128 v[190:193], v148 offset:55296
	ds_read_b128 v[194:197], v148 offset:56320
	global_load_lds_dwordx4 v[214:215], off
	v_lshl_add_u64 v[214:215], v[216:217], 0, s[12:13]
	s_mov_b32 m0, s60
	s_nop 0
	global_load_lds_dwordx4 v[214:215], off
	s_add_u32 s48, s48, 0xc000
	s_addc_u32 s49, s49, 0
	s_add_i32 s50, s71, s53
	v_lshl_add_u64 v[252:253], s[48:49], 0, v[128:129]
	s_mov_b32 m0, s50
	s_nop 0
	global_load_lds_dwordx4 v[252:253], off
	v_lshl_add_u64 v[252:253], s[48:49], 0, v[132:133]
	s_add_i32 m0, s50, 0x2000
	s_nop 0
	global_load_lds_dwordx4 v[252:253], off
	s_add_i32 s69, s69, 2
	s_add_u32 s67, s67, 0x10000
	s_addc_u32 s68, s68, 0
	s_add_u32 s6, s6, 0x100
	s_addc_u32 s7, s7, 0
	s_cmp_gt_u32 s69, 29
	s_waitcnt vmcnt(8)
	s_waitcnt lgkmcnt(0)
	s_barrier
	v_mfma_f32_16x16x32_bf16 v[60:63], v[150:153], v[166:169], v[60:63]
	v_mfma_f32_16x16x32_bf16 v[56:59], v[158:161], v[166:169], v[56:59]
	v_mfma_f32_16x16x32_bf16 v[44:47], v[150:153], v[174:177], v[44:47]
	v_mfma_f32_16x16x32_bf16 v[40:43], v[158:161], v[174:177], v[40:43]
	v_mfma_f32_16x16x32_bf16 v[28:31], v[150:153], v[182:185], v[28:31]
	v_mfma_f32_16x16x32_bf16 v[24:27], v[158:161], v[182:185], v[24:27]
	v_mfma_f32_16x16x32_bf16 v[12:15], v[150:153], v[190:193], v[12:15]
	v_mfma_f32_16x16x32_bf16 v[8:11], v[158:161], v[190:193], v[8:11]
	v_mfma_f32_16x16x32_bf16 v[60:63], v[154:157], v[170:173], v[60:63]
	v_mfma_f32_16x16x32_bf16 v[56:59], v[162:165], v[170:173], v[56:59]
	v_mfma_f32_16x16x32_bf16 v[44:47], v[154:157], v[178:181], v[44:47]
	v_mfma_f32_16x16x32_bf16 v[40:43], v[162:165], v[178:181], v[40:43]
	v_mfma_f32_16x16x32_bf16 v[28:31], v[154:157], v[186:189], v[28:31]
	v_mfma_f32_16x16x32_bf16 v[24:27], v[162:165], v[186:189], v[24:27]
	v_mfma_f32_16x16x32_bf16 v[12:15], v[154:157], v[194:197], v[12:15]
	v_mfma_f32_16x16x32_bf16 v[8:11], v[162:165], v[194:197], v[8:11]
	v_mfma_f32_16x16x32_bf16 v[52:55], v[198:201], v[166:169], v[52:55]
	v_mfma_f32_16x16x32_bf16 v[48:51], v[206:209], v[166:169], v[48:51]
	v_mfma_f32_16x16x32_bf16 v[36:39], v[198:201], v[174:177], v[36:39]
	v_mfma_f32_16x16x32_bf16 v[32:35], v[206:209], v[174:177], v[32:35]
	v_mfma_f32_16x16x32_bf16 v[20:23], v[198:201], v[182:185], v[20:23]
	v_mfma_f32_16x16x32_bf16 v[16:19], v[206:209], v[182:185], v[16:19]
	v_mfma_f32_16x16x32_bf16 v[4:7], v[198:201], v[190:193], v[4:7]
	v_mfma_f32_16x16x32_bf16 v[0:3], v[206:209], v[190:193], v[0:3]
	v_mfma_f32_16x16x32_bf16 v[52:55], v[202:205], v[170:173], v[52:55]
	v_mfma_f32_16x16x32_bf16 v[48:51], v[210:213], v[170:173], v[48:51]
	v_mfma_f32_16x16x32_bf16 v[36:39], v[202:205], v[178:181], v[36:39]
	v_mfma_f32_16x16x32_bf16 v[32:35], v[210:213], v[178:181], v[32:35]
	v_mfma_f32_16x16x32_bf16 v[20:23], v[202:205], v[186:189], v[20:23]
	v_mfma_f32_16x16x32_bf16 v[16:19], v[210:213], v[186:189], v[16:19]
	v_mfma_f32_16x16x32_bf16 v[4:7], v[202:205], v[194:197], v[4:7]
	v_mfma_f32_16x16x32_bf16 v[0:3], v[210:213], v[194:197], v[0:3]
	s_barrier
	s_cbranch_scc0 .LBB0_280
	s_cmp_eq_u32 s78, 0
	s_cbranch_scc0 .Lhalf_skip_x_2
	s_barrier

; #define PG8_STAGE(bufoff, gbase, voff) do { _Pragma("unroll") for (int _i = 0; _i < 2; ++_i) \
;         __builtin_amdgcn_global_load_lds((const unsigned*)((const char*)(gbase) + (voff)[_i]), (PG8_LAS unsigned*)(lds + (bufoff) + ldsw + _i * 8192), 16, 0, 0); } while (0)
; #define PG8_LDA(dst, b, h) do { _Pragma("unroll") for (int m = 0; m < 4; ++m) _Pragma("unroll") for (int k = 0; k < 2; ++k) dst[m][k] = *(const PG8_LAS bf16x8*)(lds + PG8_SA(b, h) + aoff + m * 2048 + k * 1024); } while (0)
; #define PG8_LDB(dst, b, h) do { _Pragma("unroll") for (int n = 0; n < 2; ++n) _Pragma("unroll") for (int k = 0; k < 2; ++k) dst[n][k] = *(const PG8_LAS bf16x8*)(lds + PG8_SB(b, h) + boff + n * 2048 + k * 1024); } while (0)
; #define PG8_MMA(ai, bj, At, Bt) do { __builtin_amdgcn_s_setprio(1); _Pragma("unroll") for (int m = 0; m < 4; ++m) _Pragma("unroll") for (int n = 0; n < 2; ++n) _Pragma("unroll") for (int k = 0; k < 2; ++k) \
;         acc[ai][bj][m][n] = __builtin_amdgcn_mfma_f32_16x16x32_bf16(Bt[n][k], At[m][k], acc[ai][bj][m][n], 0, 0, 0); __builtin_amdgcn_s_setprio(0); } while (0)
; #define PG8_WAIT_V(n) asm volatile("s_waitcnt vmcnt(" #n ")" ::: "memory")
; #define PG8_WAIT_L(n) asm volatile("s_waitcnt lgkmcnt(" #n ")" ::: "memory")
; template <class Epi, class Sched>
; __device__ __forceinline__ void gemm_phase(PG8_LAS unsigned char* lds, const Gemm g, const Sched& S, const Epi& E) {
;     ...
;             const bool last = (t == nt - 2);
;             const char* a1 = cA + (size_t)(t + 1) * kstep;
;             const char* a2 = last ? nA : cA + (size_t)(t + 2) * kstep; const char* b2 = last ? nB : cB + (size_t)(t + 2) * kstepB;
;             const char* a3 = a2 + kstep; const char* b3 = b2 + kstepB;
;             if (last && has_next) S.a_ready(nxt);
;             PG8_LDB(B0, 0, 0); PG8_SCHED; PG8_LDA(At, 0, 0); PG8_STAGE(PG8_SA(1, 1), a1 + hstep, voffA);
;             PG8_WAIT_L(8); PG8_BAR; PG8_WAIT_L(0); PG8_MMA(0, 0, At, B0); PG8_BAR; PG8_SCHED;
;             PG8_LDB(B1, 0, 1); PG8_STAGE(PG8_SB(0, 0), b2, voffB);
;             PG8_BAR; PG8_WAIT_L(0); PG8_MMA(0, 1, At, B1); PG8_BAR;
;             PG8_LDA(At, 0, 1); PG8_STAGE(PG8_SA(0, 0), a2, voffA);
;             PG8_BAR; PG8_WAIT_L(0); PG8_MMA(1, 0, At, B0); PG8_BAR; PG8_SCHED;
;             PG8_STAGE(PG8_SB(0, 1), b2 + hstepB, voffB);
;             PG8_WAIT_V(6); PG8_BAR; PG8_MMA(1, 1, At, B1); PG8_BAR;
.Lhalf_skip_y_3:
.LBB0_397:
	ds_read_b128 v[142:145], v150
	ds_read_b128 v[154:157], v150 offset:1024
	ds_read_b128 v[158:161], v150 offset:2048
	ds_read_b128 v[162:165], v150 offset:3072
	s_add_u32 s26, s24, 0xfff80080
	s_addc_u32 s27, s25, -1
	s_cmp_eq_u32 s66, 28
	s_cselect_b32 s29, s5, s27
	s_cselect_b32 s28, s15, s26
	s_cselect_b32 s27, s17, s65
	s_cselect_b32 s26, s23, s64
	v_lshl_add_u64 v[198:199], s[24:25], 0, v[138:139]
	s_add_i32 m0, s48, 0xc000
	ds_read_b128 v[166:169], v151
	ds_read_b128 v[170:173], v151 offset:1024
	ds_read_b128 v[174:177], v151 offset:2048
	ds_read_b128 v[178:181], v151 offset:3072
	ds_read_b128 v[182:185], v151 offset:4096
	ds_read_b128 v[186:189], v151 offset:5120
	ds_read_b128 v[190:193], v151 offset:6144
	ds_read_b128 v[194:197], v151 offset:7168
	global_load_lds_dwordx4 v[198:199], off
	v_lshl_add_u64 v[198:199], s[24:25], 0, v[140:141]
	s_add_i32 m0, s48, 0xe000
	s_nop 0
	global_load_lds_dwordx4 v[198:199], off
	s_add_i32 s67, s59, s39
	v_lshl_add_u64 v[214:215], s[26:27], 0, v[128:129]
	s_mov_b32 m0, s67
	ds_read_b128 v[198:201], v152
	ds_read_b128 v[202:205], v152 offset:1024
	ds_read_b128 v[206:209], v152 offset:2048
	ds_read_b128 v[210:213], v152 offset:3072
	s_waitcnt vmcnt(8)
	s_waitcnt lgkmcnt(0)
	s_barrier
	v_mfma_f32_16x16x32_bf16 v[124:127], v[142:145], v[166:169], v[124:127]
	v_mfma_f32_16x16x32_bf16 v[120:123], v[158:161], v[166:169], v[120:123]
	v_mfma_f32_16x16x32_bf16 v[108:111], v[142:145], v[174:177], v[108:111]
	v_mfma_f32_16x16x32_bf16 v[104:107], v[158:161], v[174:177], v[104:107]
	v_mfma_f32_16x16x32_bf16 v[92:95], v[142:145], v[182:185], v[92:95]
	v_mfma_f32_16x16x32_bf16 v[88:91], v[158:161], v[182:185], v[88:91]
	v_mfma_f32_16x16x32_bf16 v[76:79], v[142:145], v[190:193], v[76:79]
	v_mfma_f32_16x16x32_bf16 v[72:75], v[158:161], v[190:193], v[72:75]
	v_mfma_f32_16x16x32_bf16 v[124:127], v[154:157], v[170:173], v[124:127]
	v_mfma_f32_16x16x32_bf16 v[120:123], v[162:165], v[170:173], v[120:123]
	v_mfma_f32_16x16x32_bf16 v[108:111], v[154:157], v[178:181], v[108:111]
	v_mfma_f32_16x16x32_bf16 v[104:107], v[162:165], v[178:181], v[104:107]
	v_mfma_f32_16x16x32_bf16 v[92:95], v[154:157], v[186:189], v[92:95]
	v_mfma_f32_16x16x32_bf16 v[88:91], v[162:165], v[186:189], v[88:91]
	v_mfma_f32_16x16x32_bf16 v[76:79], v[154:157], v[194:197], v[76:79]
	v_mfma_f32_16x16x32_bf16 v[72:75], v[162:165], v[194:197], v[72:75]
	v_mfma_f32_16x16x32_bf16 v[116:119], v[198:201], v[166:169], v[116:119]
	v_mfma_f32_16x16x32_bf16 v[112:115], v[206:209], v[166:169], v[112:115]
	v_mfma_f32_16x16x32_bf16 v[100:103], v[198:201], v[174:177], v[100:103]
	v_mfma_f32_16x16x32_bf16 v[96:99], v[206:209], v[174:177], v[96:99]
	v_mfma_f32_16x16x32_bf16 v[84:87], v[198:201], v[182:185], v[84:87]
	v_mfma_f32_16x16x32_bf16 v[80:83], v[206:209], v[182:185], v[80:83]
	v_mfma_f32_16x16x32_bf16 v[68:71], v[198:201], v[190:193], v[68:71]
	v_mfma_f32_16x16x32_bf16 v[64:67], v[206:209], v[190:193], v[64:67]
	v_mfma_f32_16x16x32_bf16 v[116:119], v[202:205], v[170:173], v[116:119]
	v_mfma_f32_16x16x32_bf16 v[112:115], v[210:213], v[170:173], v[112:115]
	v_mfma_f32_16x16x32_bf16 v[100:103], v[202:205], v[178:181], v[100:103]
	v_mfma_f32_16x16x32_bf16 v[96:99], v[210:213], v[178:181], v[96:99]
	v_mfma_f32_16x16x32_bf16 v[84:87], v[202:205], v[186:189], v[84:87]
	v_mfma_f32_16x16x32_bf16 v[80:83], v[210:213], v[186:189], v[80:83]
	v_mfma_f32_16x16x32_bf16 v[68:71], v[202:205], v[194:197], v[68:71]
	v_mfma_f32_16x16x32_bf16 v[64:67], v[210:213], v[194:197], v[64:67]
	s_barrier
	global_load_lds_dwordx4 v[214:215], off
	v_lshl_add_u64 v[214:215], s[26:27], 0, v[132:133]
	s_add_i32 m0, s67, 0x2000
	s_nop 0
	global_load_lds_dwordx4 v[214:215], off
	s_mov_b32 m0, s48
	v_lshl_add_u64 v[214:215], s[28:29], 0, v[130:131]
	ds_read_b128 v[166:169], v151 offset:16384
	ds_read_b128 v[170:173], v151 offset:17408
	ds_read_b128 v[174:177], v151 offset:18432
	ds_read_b128 v[178:181], v151 offset:19456
	ds_read_b128 v[182:185], v151 offset:20480
	ds_read_b128 v[186:189], v151 offset:21504
	ds_read_b128 v[190:193], v151 offset:22528
	ds_read_b128 v[194:197], v151 offset:23552
	global_load_lds_dwordx4 v[214:215], off
	v_lshl_add_u64 v[216:217], s[28:29], 0, v[134:135]
	s_mov_b32 m0, s49
	s_nop 0
	global_load_lds_dwordx4 v[216:217], off
	s_add_u32 s68, s26, 0x4000
	s_addc_u32 s69, s27, 0
	s_add_i32 s67, s60, s39
	v_lshl_add_u64 v[250:251], s[68:69], 0, v[128:129]
	s_mov_b32 m0, s67
	s_nop 0
	global_load_lds_dwordx4 v[250:251], off
	v_lshl_add_u64 v[250:251], s[68:69], 0, v[132:133]
	s_add_i32 m0, s67, 0x2000
	s_nop 0
	global_load_lds_dwordx4 v[250:251], off
	s_waitcnt vmcnt(8)
	s_waitcnt lgkmcnt(0)
	s_barrier
; #define PG8_STAGE(bufoff, gbase, voff) do { _Pragma("unroll") for (int _i = 0; _i < 2; ++_i) \
;         __builtin_amdgcn_global_load_lds((const unsigned*)((const char*)(gbase) + (voff)[_i]), (PG8_LAS unsigned*)(lds + (bufoff) + ldsw + _i * 8192), 16, 0, 0); } while (0)
; #define PG8_LDA(dst, b, h) do { _Pragma("unroll") for (int m = 0; m < 4; ++m) _Pragma("unroll") for (int k = 0; k < 2; ++k) dst[m][k] = *(const PG8_LAS bf16x8*)(lds + PG8_SA(b, h) + aoff + m * 2048 + k * 1024); } while (0)
; #define PG8_LDB(dst, b, h) do { _Pragma("unroll") for (int n = 0; n < 2; ++n) _Pragma("unroll") for (int k = 0; k < 2; ++k) dst[n][k] = *(const PG8_LAS bf16x8*)(lds + PG8_SB(b, h) + boff + n * 2048 + k * 1024); } while (0)
; #define PG8_MMA(ai, bj, At, Bt) do { __builtin_amdgcn_s_setprio(1); _Pragma("unroll") for (int m = 0; m < 4; ++m) _Pragma("unroll") for (int n = 0; n < 2; ++n) _Pragma("unroll") for (int k = 0; k < 2; ++k) \
;         acc[ai][bj][m][n] = __builtin_amdgcn_mfma_f32_16x16x32_bf16(Bt[n][k], At[m][k], acc[ai][bj][m][n], 0, 0, 0); __builtin_amdgcn_s_setprio(0); } while (0)
; #define PG8_WAIT_V(n) asm volatile("s_waitcnt vmcnt(" #n ")" ::: "memory")
; #define PG8_WAIT_L(n) asm volatile("s_waitcnt lgkmcnt(" #n ")" ::: "memory")
; #define PG8_BAR __builtin_amdgcn_s_barrier()
; #define PG8_SCHED __builtin_amdgcn_sched_barrier(0)
; template <class Epi, class Sched>
; __device__ __forceinline__ void gemm_phase(PG8_LAS unsigned char* lds, const Gemm g, const Sched& S, const Epi& E) {
;     ...
;             PG8_BAR; PG8_WAIT_L(0); PG8_MMA(1, 0, At, B0); PG8_BAR; PG8_SCHED;
;             PG8_STAGE(PG8_SB(0, 1), b2 + hstepB, voffB);
;             PG8_WAIT_V(6); PG8_BAR; PG8_MMA(1, 1, At, B1); PG8_BAR;
;             PG8_LDB(B0, 1, 0); PG8_SCHED; PG8_LDA(At, 1, 0); PG8_STAGE(PG8_SA(0, 1), a2 + hstep, voffA);
;             PG8_WAIT_L(8); PG8_BAR; PG8_WAIT_L(0); PG8_MMA(0, 0, At, B0); PG8_BAR; PG8_SCHED;
;             PG8_LDB(B1, 1, 1); PG8_STAGE(PG8_SB(1, 0), b3, voffB);
;             PG8_BAR; PG8_WAIT_L(0); PG8_MMA(0, 1, At, B1); PG8_BAR;
;             PG8_LDA(At, 1, 1); PG8_STAGE(PG8_SA(1, 0), a3, voffA);
;             PG8_BAR; PG8_WAIT_L(0); PG8_MMA(1, 0, At, B0); PG8_BAR; PG8_SCHED;
	v_mfma_f32_16x16x32_bf16 v[60:63], v[142:145], v[166:169], v[60:63]
	v_mfma_f32_16x16x32_bf16 v[56:59], v[158:161], v[166:169], v[56:59]
	v_mfma_f32_16x16x32_bf16 v[44:47], v[142:145], v[174:177], v[44:47]
	v_mfma_f32_16x16x32_bf16 v[40:43], v[158:161], v[174:177], v[40:43]
	v_mfma_f32_16x16x32_bf16 v[28:31], v[142:145], v[182:185], v[28:31]
	v_mfma_f32_16x16x32_bf16 v[24:27], v[158:161], v[182:185], v[24:27]
	v_mfma_f32_16x16x32_bf16 v[12:15], v[142:145], v[190:193], v[12:15]
	v_mfma_f32_16x16x32_bf16 v[8:11], v[158:161], v[190:193], v[8:11]
	v_mfma_f32_16x16x32_bf16 v[60:63], v[154:157], v[170:173], v[60:63]
	v_mfma_f32_16x16x32_bf16 v[56:59], v[162:165], v[170:173], v[56:59]
	v_mfma_f32_16x16x32_bf16 v[44:47], v[154:157], v[178:181], v[44:47]
	v_mfma_f32_16x16x32_bf16 v[40:43], v[162:165], v[178:181], v[40:43]
	v_mfma_f32_16x16x32_bf16 v[28:31], v[154:157], v[186:189], v[28:31]
	v_mfma_f32_16x16x32_bf16 v[24:27], v[162:165], v[186:189], v[24:27]
	v_mfma_f32_16x16x32_bf16 v[12:15], v[154:157], v[194:197], v[12:15]
	v_mfma_f32_16x16x32_bf16 v[8:11], v[162:165], v[194:197], v[8:11]
	v_mfma_f32_16x16x32_bf16 v[52:55], v[198:201], v[166:169], v[52:55]
	v_mfma_f32_16x16x32_bf16 v[48:51], v[206:209], v[166:169], v[48:51]
	v_mfma_f32_16x16x32_bf16 v[36:39], v[198:201], v[174:177], v[36:39]
	v_mfma_f32_16x16x32_bf16 v[32:35], v[206:209], v[174:177], v[32:35]
	v_mfma_f32_16x16x32_bf16 v[20:23], v[198:201], v[182:185], v[20:23]
	v_mfma_f32_16x16x32_bf16 v[16:19], v[206:209], v[182:185], v[16:19]
	v_mfma_f32_16x16x32_bf16 v[4:7], v[198:201], v[190:193], v[4:7]
	v_mfma_f32_16x16x32_bf16 v[0:3], v[206:209], v[190:193], v[0:3]
	v_mfma_f32_16x16x32_bf16 v[52:55], v[202:205], v[170:173], v[52:55]
	v_mfma_f32_16x16x32_bf16 v[48:51], v[210:213], v[170:173], v[48:51]
	v_mfma_f32_16x16x32_bf16 v[36:39], v[202:205], v[178:181], v[36:39]
	v_mfma_f32_16x16x32_bf16 v[32:35], v[210:213], v[178:181], v[32:35]
	v_mfma_f32_16x16x32_bf16 v[20:23], v[202:205], v[186:189], v[20:23]
	v_mfma_f32_16x16x32_bf16 v[16:19], v[210:213], v[186:189], v[16:19]
	v_mfma_f32_16x16x32_bf16 v[4:7], v[202:205], v[194:197], v[4:7]
	v_mfma_f32_16x16x32_bf16 v[0:3], v[210:213], v[194:197], v[0:3]
	s_barrier
	s_add_i32 s67, 0, 0x18000
	v_add_u32_e32 v136, s67, v148
	ds_read_b128 v[142:145], v136
	ds_read_b128 v[154:157], v136 offset:1024
	ds_read_b128 v[158:161], v136 offset:2048
	ds_read_b128 v[162:165], v136 offset:3072
	s_add_u32 s28, s28, 0x80000
	s_addc_u32 s29, s29, 0
	s_mov_b32 m0, s50
	v_lshl_add_u64 v[198:199], s[28:29], 0, v[130:131]
	ds_read_b128 v[166:169], v151 offset:32768
	ds_read_b128 v[170:173], v151 offset:33792
	ds_read_b128 v[174:177], v151 offset:34816
	ds_read_b128 v[178:181], v151 offset:35840
	ds_read_b128 v[182:185], v151 offset:36864
	ds_read_b128 v[186:189], v151 offset:37888
	ds_read_b128 v[190:193], v151 offset:38912
	ds_read_b128 v[194:197], v151 offset:39936
	global_load_lds_dwordx4 v[198:199], off
	v_lshl_add_u64 v[198:199], s[28:29], 0, v[134:135]
	s_mov_b32 m0, s51
	s_nop 0
	global_load_lds_dwordx4 v[198:199], off
	s_add_i32 s68, 0, 0x1c000
	s_add_u32 s28, s26, 0x8000
	s_addc_u32 s29, s27, 0
	s_add_i32 s67, s67, s39
	v_add_u32_e32 v136, s68, v148
	v_lshl_add_u64 v[218:219], s[28:29], 0, v[128:129]
	s_mov_b32 m0, s67
	ds_read_b128 v[198:201], v136
	ds_read_b128 v[202:205], v136 offset:1024
	ds_read_b128 v[206:209], v136 offset:2048
	ds_read_b128 v[210:213], v136 offset:3072
	s_waitcnt vmcnt(8)
	s_waitcnt lgkmcnt(0)
	s_barrier
	v_mfma_f32_16x16x32_bf16 v[124:127], v[142:145], v[166:169], v[124:127]
	v_mfma_f32_16x16x32_bf16 v[120:123], v[158:161], v[166:169], v[120:123]
	v_mfma_f32_16x16x32_bf16 v[108:111], v[142:145], v[174:177], v[108:111]
	v_mfma_f32_16x16x32_bf16 v[104:107], v[158:161], v[174:177], v[104:107]
	v_mfma_f32_16x16x32_bf16 v[92:95], v[142:145], v[182:185], v[92:95]
	v_mfma_f32_16x16x32_bf16 v[88:91], v[158:161], v[182:185], v[88:91]
	v_mfma_f32_16x16x32_bf16 v[76:79], v[142:145], v[190:193], v[76:79]
	v_mfma_f32_16x16x32_bf16 v[72:75], v[158:161], v[190:193], v[72:75]
	v_mfma_f32_16x16x32_bf16 v[124:127], v[154:157], v[170:173], v[124:127]
	v_mfma_f32_16x16x32_bf16 v[120:123], v[162:165], v[170:173], v[120:123]
	v_mfma_f32_16x16x32_bf16 v[108:111], v[154:157], v[178:181], v[108:111]
	v_mfma_f32_16x16x32_bf16 v[104:107], v[162:165], v[178:181], v[104:107]
	v_mfma_f32_16x16x32_bf16 v[92:95], v[154:157], v[186:189], v[92:95]
	v_mfma_f32_16x16x32_bf16 v[88:91], v[162:165], v[186:189], v[88:91]
	v_mfma_f32_16x16x32_bf16 v[76:79], v[154:157], v[194:197], v[76:79]
	v_mfma_f32_16x16x32_bf16 v[72:75], v[162:165], v[194:197], v[72:75]
	v_mfma_f32_16x16x32_bf16 v[116:119], v[198:201], v[166:169], v[116:119]
	v_mfma_f32_16x16x32_bf16 v[112:115], v[206:209], v[166:169], v[112:115]
	v_mfma_f32_16x16x32_bf16 v[100:103], v[198:201], v[174:177], v[100:103]
	v_mfma_f32_16x16x32_bf16 v[96:99], v[206:209], v[174:177], v[96:99]
	v_mfma_f32_16x16x32_bf16 v[84:87], v[198:201], v[182:185], v[84:87]
	v_mfma_f32_16x16x32_bf16 v[80:83], v[206:209], v[182:185], v[80:83]
	v_mfma_f32_16x16x32_bf16 v[68:71], v[198:201], v[190:193], v[68:71]
	v_mfma_f32_16x16x32_bf16 v[64:67], v[206:209], v[190:193], v[64:67]
	v_mfma_f32_16x16x32_bf16 v[116:119], v[202:205], v[170:173], v[116:119]
	v_mfma_f32_16x16x32_bf16 v[112:115], v[210:213], v[170:173], v[112:115]
	v_mfma_f32_16x16x32_bf16 v[100:103], v[202:205], v[178:181], v[100:103]
	v_mfma_f32_16x16x32_bf16 v[96:99], v[210:213], v[178:181], v[96:99]
	v_mfma_f32_16x16x32_bf16 v[84:87], v[202:205], v[186:189], v[84:87]
	v_mfma_f32_16x16x32_bf16 v[80:83], v[210:213], v[186:189], v[80:83]
	v_mfma_f32_16x16x32_bf16 v[68:71], v[202:205], v[194:197], v[68:71]
	v_mfma_f32_16x16x32_bf16 v[64:67], v[210:213], v[194:197], v[64:67]
	s_barrier
; #define PG8_STAGE(bufoff, gbase, voff) do { _Pragma("unroll") for (int _i = 0; _i < 2; ++_i) \
;         __builtin_amdgcn_global_load_lds((const unsigned*)((const char*)(gbase) + (voff)[_i]), (PG8_LAS unsigned*)(lds + (bufoff) + ldsw + _i * 8192), 16, 0, 0); } while (0)
; #define PG8_LDA(dst, b, h) do { _Pragma("unroll") for (int m = 0; m < 4; ++m) _Pragma("unroll") for (int k = 0; k < 2; ++k) dst[m][k] = *(const PG8_LAS bf16x8*)(lds + PG8_SA(b, h) + aoff + m * 2048 + k * 1024); } while (0)
; #define PG8_MMA(ai, bj, At, Bt) do { __builtin_amdgcn_s_setprio(1); _Pragma("unroll") for (int m = 0; m < 4; ++m) _Pragma("unroll") for (int n = 0; n < 2; ++n) _Pragma("unroll") for (int k = 0; k < 2; ++k) \
;         acc[ai][bj][m][n] = __builtin_amdgcn_mfma_f32_16x16x32_bf16(Bt[n][k], At[m][k], acc[ai][bj][m][n], 0, 0, 0); __builtin_amdgcn_s_setprio(0); } while (0)
; #define PG8_WAIT_V(n) asm volatile("s_waitcnt vmcnt(" #n ")" ::: "memory")
; #define PG8_WAIT_L(n) asm volatile("s_waitcnt lgkmcnt(" #n ")" ::: "memory")
; #define PG8_BAR __builtin_amdgcn_s_barrier()
; #define PG8_SCHED __builtin_amdgcn_sched_barrier(0)
; template <class Epi, class Sched>
; __device__ __forceinline__ void gemm_phase(PG8_LAS unsigned char* lds, const Gemm g, const Sched& S, const Epi& E) {
;     ...
;             PG8_LDA(At, 1, 1); PG8_STAGE(PG8_SA(1, 0), a3, voffA);
;             PG8_BAR; PG8_WAIT_L(0); PG8_MMA(1, 0, At, B0); PG8_BAR; PG8_SCHED;
;             PG8_STAGE(PG8_SB(1, 1), b3 + hstepB, voffB);
;             PG8_WAIT_V(6); PG8_BAR; PG8_MMA(1, 1, At, B1); PG8_BAR;
;     ...
;     PG8_WAIT_V(0);
;     if (wr == 0) PG8_BAR;
;     PG8_BAR;
	global_load_lds_dwordx4 v[218:219], off
	v_lshl_add_u64 v[218:219], s[28:29], 0, v[132:133]
	s_add_i32 m0, s67, 0x2000
	s_nop 0
	global_load_lds_dwordx4 v[218:219], off
	s_mov_b32 m0, s55
	v_lshl_add_u64 v[214:215], v[214:215], 0, s[10:11]
	ds_read_b128 v[166:169], v151 offset:49152
	ds_read_b128 v[170:173], v151 offset:50176
	ds_read_b128 v[174:177], v151 offset:51200
	ds_read_b128 v[178:181], v151 offset:52224
	ds_read_b128 v[182:185], v151 offset:53248
	ds_read_b128 v[186:189], v151 offset:54272
	ds_read_b128 v[190:193], v151 offset:55296
	ds_read_b128 v[194:197], v151 offset:56320
	global_load_lds_dwordx4 v[214:215], off
	v_lshl_add_u64 v[214:215], v[216:217], 0, s[10:11]
	s_mov_b32 m0, s56
	s_nop 0
	global_load_lds_dwordx4 v[214:215], off
	s_add_u32 s26, s26, 0xc000
	s_addc_u32 s27, s27, 0
	s_add_i32 s28, s68, s39
	v_lshl_add_u64 v[252:253], s[26:27], 0, v[128:129]
	s_mov_b32 m0, s28
	s_nop 0
	global_load_lds_dwordx4 v[252:253], off
	v_lshl_add_u64 v[252:253], s[26:27], 0, v[132:133]
	s_add_i32 m0, s28, 0x2000
	s_nop 0
	global_load_lds_dwordx4 v[252:253], off
	s_add_i32 s66, s66, 2
	s_add_u32 s64, s64, 0x10000
	s_addc_u32 s65, s65, 0
	s_add_u32 s24, s24, 0x100
	s_addc_u32 s25, s25, 0
	s_cmp_gt_u32 s66, 29
	s_waitcnt vmcnt(8)
	s_waitcnt lgkmcnt(0)
	s_barrier
	v_mfma_f32_16x16x32_bf16 v[60:63], v[142:145], v[166:169], v[60:63]
	v_mfma_f32_16x16x32_bf16 v[56:59], v[158:161], v[166:169], v[56:59]
	v_mfma_f32_16x16x32_bf16 v[44:47], v[142:145], v[174:177], v[44:47]
	v_mfma_f32_16x16x32_bf16 v[40:43], v[158:161], v[174:177], v[40:43]
	v_mfma_f32_16x16x32_bf16 v[28:31], v[142:145], v[182:185], v[28:31]
	v_mfma_f32_16x16x32_bf16 v[24:27], v[158:161], v[182:185], v[24:27]
	v_mfma_f32_16x16x32_bf16 v[12:15], v[142:145], v[190:193], v[12:15]
	v_mfma_f32_16x16x32_bf16 v[8:11], v[158:161], v[190:193], v[8:11]
	v_mfma_f32_16x16x32_bf16 v[60:63], v[154:157], v[170:173], v[60:63]
	v_mfma_f32_16x16x32_bf16 v[56:59], v[162:165], v[170:173], v[56:59]
	v_mfma_f32_16x16x32_bf16 v[44:47], v[154:157], v[178:181], v[44:47]
	v_mfma_f32_16x16x32_bf16 v[40:43], v[162:165], v[178:181], v[40:43]
	v_mfma_f32_16x16x32_bf16 v[28:31], v[154:157], v[186:189], v[28:31]
	v_mfma_f32_16x16x32_bf16 v[24:27], v[162:165], v[186:189], v[24:27]
	v_mfma_f32_16x16x32_bf16 v[12:15], v[154:157], v[194:197], v[12:15]
	v_mfma_f32_16x16x32_bf16 v[8:11], v[162:165], v[194:197], v[8:11]
	v_mfma_f32_16x16x32_bf16 v[52:55], v[198:201], v[166:169], v[52:55]
	v_mfma_f32_16x16x32_bf16 v[48:51], v[206:209], v[166:169], v[48:51]
	v_mfma_f32_16x16x32_bf16 v[36:39], v[198:201], v[174:177], v[36:39]
	v_mfma_f32_16x16x32_bf16 v[32:35], v[206:209], v[174:177], v[32:35]
	v_mfma_f32_16x16x32_bf16 v[20:23], v[198:201], v[182:185], v[20:23]
	v_mfma_f32_16x16x32_bf16 v[16:19], v[206:209], v[182:185], v[16:19]
	v_mfma_f32_16x16x32_bf16 v[4:7], v[198:201], v[190:193], v[4:7]
	v_mfma_f32_16x16x32_bf16 v[0:3], v[206:209], v[190:193], v[0:3]
	v_mfma_f32_16x16x32_bf16 v[52:55], v[202:205], v[170:173], v[52:55]
	v_mfma_f32_16x16x32_bf16 v[48:51], v[210:213], v[170:173], v[48:51]
	v_mfma_f32_16x16x32_bf16 v[36:39], v[202:205], v[178:181], v[36:39]
	v_mfma_f32_16x16x32_bf16 v[32:35], v[210:213], v[178:181], v[32:35]
	v_mfma_f32_16x16x32_bf16 v[20:23], v[202:205], v[186:189], v[20:23]
	v_mfma_f32_16x16x32_bf16 v[16:19], v[210:213], v[186:189], v[16:19]
	v_mfma_f32_16x16x32_bf16 v[4:7], v[202:205], v[194:197], v[4:7]
	v_mfma_f32_16x16x32_bf16 v[0:3], v[210:213], v[194:197], v[0:3]
	s_barrier
	s_cbranch_scc0 .LBB0_397
	s_cmp_eq_u32 s78, 0
	s_cbranch_scc0 .Lhalf_skip_x_3
	s_barrier

; #define PG8_STAGE(bufoff, gbase, voff) do { _Pragma("unroll") for (int _i = 0; _i < 2; ++_i) \
;         __builtin_amdgcn_global_load_lds((const unsigned*)((const char*)(gbase) + (voff)[_i]), (PG8_LAS unsigned*)(lds + (bufoff) + ldsw + _i * 8192), 16, 0, 0); } while (0)
; #define PG8_LDA(dst, b, h) do { _Pragma("unroll") for (int m = 0; m < 4; ++m) _Pragma("unroll") for (int k = 0; k < 2; ++k) dst[m][k] = *(const PG8_LAS bf16x8*)(lds + PG8_SA(b, h) + aoff + m * 2048 + k * 1024); } while (0)
; #define PG8_LDB(dst, b, h) do { _Pragma("unroll") for (int n = 0; n < 2; ++n) _Pragma("unroll") for (int k = 0; k < 2; ++k) dst[n][k] = *(const PG8_LAS bf16x8*)(lds + PG8_SB(b, h) + boff + n * 2048 + k * 1024); } while (0)
; #define PG8_MMA(ai, bj, At, Bt) do { __builtin_amdgcn_s_setprio(1); _Pragma("unroll") for (int m = 0; m < 4; ++m) _Pragma("unroll") for (int n = 0; n < 2; ++n) _Pragma("unroll") for (int k = 0; k < 2; ++k) \
;         acc[ai][bj][m][n] = __builtin_amdgcn_mfma_f32_16x16x32_bf16(Bt[n][k], At[m][k], acc[ai][bj][m][n], 0, 0, 0); __builtin_amdgcn_s_setprio(0); } while (0)
; #define PG8_WAIT_V(n) asm volatile("s_waitcnt vmcnt(" #n ")" ::: "memory")
; #define PG8_WAIT_L(n) asm volatile("s_waitcnt lgkmcnt(" #n ")" ::: "memory")
; template <class Epi, class Sched>
; __device__ __forceinline__ void gemm_phase(PG8_LAS unsigned char* lds, const Gemm g, const Sched& S, const Epi& E) {
;     ...
;             const bool last = (t == nt - 2);
;             const char* a1 = cA + (size_t)(t + 1) * kstep;
;             const char* a2 = last ? nA : cA + (size_t)(t + 2) * kstep; const char* b2 = last ? nB : cB + (size_t)(t + 2) * kstepB;
;             const char* a3 = a2 + kstep; const char* b3 = b2 + kstepB;
;             if (last && has_next) S.a_ready(nxt);
;             PG8_LDB(B0, 0, 0); PG8_SCHED; PG8_LDA(At, 0, 0); PG8_STAGE(PG8_SA(1, 1), a1 + hstep, voffA);
;             PG8_WAIT_L(8); PG8_BAR; PG8_WAIT_L(0); PG8_MMA(0, 0, At, B0); PG8_BAR; PG8_SCHED;
;             PG8_LDB(B1, 0, 1); PG8_STAGE(PG8_SB(0, 0), b2, voffB);
;             PG8_BAR; PG8_WAIT_L(0); PG8_MMA(0, 1, At, B1); PG8_BAR;
;             PG8_LDA(At, 0, 1); PG8_STAGE(PG8_SA(0, 0), a2, voffA);
;             PG8_BAR; PG8_WAIT_L(0); PG8_MMA(1, 0, At, B0); PG8_BAR; PG8_SCHED;
;             PG8_STAGE(PG8_SB(0, 1), b2 + hstepB, voffB);
;             PG8_WAIT_V(6); PG8_BAR; PG8_MMA(1, 1, At, B1); PG8_BAR;
.Lhalf_skip_y_4:
.LBB0_613:
	v_add_u32_e32 v1, s57, v231
	ds_read_b128 v[132:135], v1
	ds_read_b128 v[136:139], v1 offset:1024
	ds_read_b128 v[140:143], v1 offset:2048
	ds_read_b128 v[144:147], v1 offset:3072
	s_add_u32 s26, s24, 0xfffc0080
	s_addc_u32 s27, s25, -1
	s_cmp_eq_u32 s63, 12
	s_cselect_b32 s29, s7, s27
	s_cselect_b32 s28, s15, s26
	s_cselect_b32 s27, s17, s62
	s_cselect_b32 s26, s19, s61
	v_lshl_add_u64 v[2:3], s[24:25], 0, v[204:205]
	s_add_i32 m0, s49, 0xc000
	ds_read_b128 v[148:151], v233
	ds_read_b128 v[152:155], v233 offset:1024
	ds_read_b128 v[156:159], v233 offset:2048
	ds_read_b128 v[160:163], v233 offset:3072
	ds_read_b128 v[164:167], v233 offset:4096
	ds_read_b128 v[168:171], v233 offset:5120
	ds_read_b128 v[172:175], v233 offset:6144
	ds_read_b128 v[176:179], v233 offset:7168
	global_load_lds_dwordx4 v[2:3], off
	v_lshl_add_u64 v[2:3], s[24:25], 0, v[206:207]
	s_add_i32 m0, s49, 0xe000
	s_nop 0
	global_load_lds_dwordx4 v[2:3], off
	s_add_i32 s64, s57, s48
	v_add_u32_e32 v1, s58, v231
	v_lshl_add_u64 v[250:251], s[26:27], 0, v[196:197]
	s_mov_b32 m0, s64
	ds_read_b128 v[180:183], v1
	ds_read_b128 v[184:187], v1 offset:1024
	ds_read_b128 v[188:191], v1 offset:2048
	ds_read_b128 v[192:195], v1 offset:3072
	s_waitcnt vmcnt(8)
	s_waitcnt lgkmcnt(0)
	s_barrier
	v_mfma_f32_16x16x32_bf16 v[2:5], v[132:135], v[148:151], v[4:7]
	v_mfma_f32_16x16x32_bf16 v[6:9], v[140:143], v[148:151], v[8:11]
	v_mfma_f32_16x16x32_bf16 v[32:35], v[132:135], v[156:159], v[32:35]
	v_mfma_f32_16x16x32_bf16 v[28:31], v[140:143], v[156:159], v[28:31]
	v_mfma_f32_16x16x32_bf16 v[24:27], v[132:135], v[164:167], v[24:27]
	v_mfma_f32_16x16x32_bf16 v[20:23], v[140:143], v[164:167], v[20:23]
	v_mfma_f32_16x16x32_bf16 v[16:19], v[132:135], v[172:175], v[16:19]
	v_mfma_f32_16x16x32_bf16 v[12:15], v[140:143], v[172:175], v[12:15]
	v_mfma_f32_16x16x32_bf16 v[2:5], v[136:139], v[152:155], v[2:5]
	v_mfma_f32_16x16x32_bf16 v[8:11], v[144:147], v[152:155], v[6:9]
	v_mfma_f32_16x16x32_bf16 v[32:35], v[136:139], v[160:163], v[32:35]
	v_mfma_f32_16x16x32_bf16 v[28:31], v[144:147], v[160:163], v[28:31]
	v_mfma_f32_16x16x32_bf16 v[24:27], v[136:139], v[168:171], v[24:27]
	v_mfma_f32_16x16x32_bf16 v[20:23], v[144:147], v[168:171], v[20:23]
	v_mfma_f32_16x16x32_bf16 v[16:19], v[136:139], v[176:179], v[16:19]
	v_mfma_f32_16x16x32_bf16 v[12:15], v[144:147], v[176:179], v[12:15]
	v_mfma_f32_16x16x32_bf16 v[128:131], v[180:183], v[148:151], v[128:131]
	v_mfma_f32_16x16x32_bf16 v[124:127], v[188:191], v[148:151], v[124:127]
	v_mfma_f32_16x16x32_bf16 v[120:123], v[180:183], v[156:159], v[120:123]
	v_mfma_f32_16x16x32_bf16 v[116:119], v[188:191], v[156:159], v[116:119]
	v_mfma_f32_16x16x32_bf16 v[112:115], v[180:183], v[164:167], v[112:115]
	v_mfma_f32_16x16x32_bf16 v[108:111], v[188:191], v[164:167], v[108:111]
	v_mfma_f32_16x16x32_bf16 v[104:107], v[180:183], v[172:175], v[104:107]
	v_mfma_f32_16x16x32_bf16 v[100:103], v[188:191], v[172:175], v[100:103]
	v_mfma_f32_16x16x32_bf16 v[128:131], v[184:187], v[152:155], v[128:131]
	v_mfma_f32_16x16x32_bf16 v[124:127], v[192:195], v[152:155], v[124:127]
	v_mfma_f32_16x16x32_bf16 v[120:123], v[184:187], v[160:163], v[120:123]
	v_mfma_f32_16x16x32_bf16 v[116:119], v[192:195], v[160:163], v[116:119]
	v_mfma_f32_16x16x32_bf16 v[112:115], v[184:187], v[168:171], v[112:115]
	v_mfma_f32_16x16x32_bf16 v[108:111], v[192:195], v[168:171], v[108:111]
	v_mfma_f32_16x16x32_bf16 v[104:107], v[184:187], v[176:179], v[104:107]
	v_mfma_f32_16x16x32_bf16 v[100:103], v[192:195], v[176:179], v[100:103]
	s_barrier
	global_load_lds_dwordx4 v[250:251], off
	v_lshl_add_u64 v[250:251], s[26:27], 0, v[200:201]
	s_add_i32 m0, s64, 0x2000
	s_nop 0
	global_load_lds_dwordx4 v[250:251], off
	s_mov_b32 m0, s49
	v_lshl_add_u64 v[212:213], s[28:29], 0, v[198:199]
	ds_read_b128 v[148:151], v233 offset:16384
	ds_read_b128 v[152:155], v233 offset:17408
	ds_read_b128 v[156:159], v233 offset:18432
	ds_read_b128 v[160:163], v233 offset:19456
	ds_read_b128 v[164:167], v233 offset:20480
	ds_read_b128 v[168:171], v233 offset:21504
	ds_read_b128 v[172:175], v233 offset:22528
	ds_read_b128 v[176:179], v233 offset:23552
	global_load_lds_dwordx4 v[212:213], off
	v_lshl_add_u64 v[214:215], s[28:29], 0, v[202:203]
	s_mov_b32 m0, s50
	s_nop 0
	global_load_lds_dwordx4 v[214:215], off
	s_add_u32 s64, s26, 0x4000
	s_addc_u32 s65, s27, 0
	s_add_i32 s66, s58, s48
	v_lshl_add_u64 v[6:7], s[64:65], 0, v[196:197]
	s_mov_b32 m0, s66
	s_nop 0
	global_load_lds_dwordx4 v[6:7], off
	v_lshl_add_u64 v[6:7], s[64:65], 0, v[200:201]
	s_add_i32 m0, s66, 0x2000
	s_nop 0
	global_load_lds_dwordx4 v[6:7], off
	s_waitcnt vmcnt(8)
	s_waitcnt lgkmcnt(0)
	s_barrier
; #define PG8_STAGE(bufoff, gbase, voff) do { _Pragma("unroll") for (int _i = 0; _i < 2; ++_i) \
;         __builtin_amdgcn_global_load_lds((const unsigned*)((const char*)(gbase) + (voff)[_i]), (PG8_LAS unsigned*)(lds + (bufoff) + ldsw + _i * 8192), 16, 0, 0); } while (0)
; #define PG8_LDA(dst, b, h) do { _Pragma("unroll") for (int m = 0; m < 4; ++m) _Pragma("unroll") for (int k = 0; k < 2; ++k) dst[m][k] = *(const PG8_LAS bf16x8*)(lds + PG8_SA(b, h) + aoff + m * 2048 + k * 1024); } while (0)
; #define PG8_LDB(dst, b, h) do { _Pragma("unroll") for (int n = 0; n < 2; ++n) _Pragma("unroll") for (int k = 0; k < 2; ++k) dst[n][k] = *(const PG8_LAS bf16x8*)(lds + PG8_SB(b, h) + boff + n * 2048 + k * 1024); } while (0)
; #define PG8_MMA(ai, bj, At, Bt) do { __builtin_amdgcn_s_setprio(1); _Pragma("unroll") for (int m = 0; m < 4; ++m) _Pragma("unroll") for (int n = 0; n < 2; ++n) _Pragma("unroll") for (int k = 0; k < 2; ++k) \
;         acc[ai][bj][m][n] = __builtin_amdgcn_mfma_f32_16x16x32_bf16(Bt[n][k], At[m][k], acc[ai][bj][m][n], 0, 0, 0); __builtin_amdgcn_s_setprio(0); } while (0)
; #define PG8_WAIT_V(n) asm volatile("s_waitcnt vmcnt(" #n ")" ::: "memory")
; #define PG8_WAIT_L(n) asm volatile("s_waitcnt lgkmcnt(" #n ")" ::: "memory")
; #define PG8_BAR __builtin_amdgcn_s_barrier()
; #define PG8_SCHED __builtin_amdgcn_sched_barrier(0)
; template <class Epi, class Sched>
; __device__ __forceinline__ void gemm_phase(PG8_LAS unsigned char* lds, const Gemm g, const Sched& S, const Epi& E) {
;     ...
;             PG8_BAR; PG8_WAIT_L(0); PG8_MMA(1, 0, At, B0); PG8_BAR; PG8_SCHED;
;             PG8_STAGE(PG8_SB(0, 1), b2 + hstepB, voffB);
;             PG8_WAIT_V(6); PG8_BAR; PG8_MMA(1, 1, At, B1); PG8_BAR;
;             PG8_LDB(B0, 1, 0); PG8_SCHED; PG8_LDA(At, 1, 0); PG8_STAGE(PG8_SA(0, 1), a2 + hstep, voffA);
;             PG8_WAIT_L(8); PG8_BAR; PG8_WAIT_L(0); PG8_MMA(0, 0, At, B0); PG8_BAR; PG8_SCHED;
;             PG8_LDB(B1, 1, 1); PG8_STAGE(PG8_SB(1, 0), b3, voffB);
;             PG8_BAR; PG8_WAIT_L(0); PG8_MMA(0, 1, At, B1); PG8_BAR;
;             PG8_LDA(At, 1, 1); PG8_STAGE(PG8_SA(1, 0), a3, voffA);
;             PG8_BAR; PG8_WAIT_L(0); PG8_MMA(1, 0, At, B0); PG8_BAR; PG8_SCHED;
	v_mfma_f32_16x16x32_bf16 v[96:99], v[132:135], v[148:151], v[96:99]
	v_mfma_f32_16x16x32_bf16 v[92:95], v[140:143], v[148:151], v[92:95]
	v_mfma_f32_16x16x32_bf16 v[88:91], v[132:135], v[156:159], v[88:91]
	v_mfma_f32_16x16x32_bf16 v[84:87], v[140:143], v[156:159], v[84:87]
	v_mfma_f32_16x16x32_bf16 v[80:83], v[132:135], v[164:167], v[80:83]
	v_mfma_f32_16x16x32_bf16 v[76:79], v[140:143], v[164:167], v[76:79]
	v_mfma_f32_16x16x32_bf16 v[72:75], v[132:135], v[172:175], v[72:75]
	v_mfma_f32_16x16x32_bf16 v[68:71], v[140:143], v[172:175], v[68:71]
	v_mfma_f32_16x16x32_bf16 v[96:99], v[136:139], v[152:155], v[96:99]
	v_mfma_f32_16x16x32_bf16 v[92:95], v[144:147], v[152:155], v[92:95]
	v_mfma_f32_16x16x32_bf16 v[88:91], v[136:139], v[160:163], v[88:91]
	v_mfma_f32_16x16x32_bf16 v[84:87], v[144:147], v[160:163], v[84:87]
	v_mfma_f32_16x16x32_bf16 v[80:83], v[136:139], v[168:171], v[80:83]
	v_mfma_f32_16x16x32_bf16 v[76:79], v[144:147], v[168:171], v[76:79]
	v_mfma_f32_16x16x32_bf16 v[72:75], v[136:139], v[176:179], v[72:75]
	v_mfma_f32_16x16x32_bf16 v[68:71], v[144:147], v[176:179], v[68:71]
	v_mfma_f32_16x16x32_bf16 v[64:67], v[180:183], v[148:151], v[64:67]
	v_mfma_f32_16x16x32_bf16 v[60:63], v[188:191], v[148:151], v[60:63]
	v_mfma_f32_16x16x32_bf16 v[56:59], v[180:183], v[156:159], v[56:59]
	v_mfma_f32_16x16x32_bf16 v[52:55], v[188:191], v[156:159], v[52:55]
	v_mfma_f32_16x16x32_bf16 v[48:51], v[180:183], v[164:167], v[48:51]
	v_mfma_f32_16x16x32_bf16 v[44:47], v[188:191], v[164:167], v[44:47]
	v_mfma_f32_16x16x32_bf16 v[40:43], v[180:183], v[172:175], v[40:43]
	v_mfma_f32_16x16x32_bf16 v[36:39], v[188:191], v[172:175], v[36:39]
	v_mfma_f32_16x16x32_bf16 v[64:67], v[184:187], v[152:155], v[64:67]
	v_mfma_f32_16x16x32_bf16 v[60:63], v[192:195], v[152:155], v[60:63]
	v_mfma_f32_16x16x32_bf16 v[56:59], v[184:187], v[160:163], v[56:59]
	v_mfma_f32_16x16x32_bf16 v[52:55], v[192:195], v[160:163], v[52:55]
	v_mfma_f32_16x16x32_bf16 v[48:51], v[184:187], v[168:171], v[48:51]
	v_mfma_f32_16x16x32_bf16 v[44:47], v[192:195], v[168:171], v[44:47]
	v_mfma_f32_16x16x32_bf16 v[40:43], v[184:187], v[176:179], v[40:43]
	v_mfma_f32_16x16x32_bf16 v[36:39], v[192:195], v[176:179], v[36:39]
	s_barrier
	s_add_i32 s64, 0, 0x18000
	v_add_u32_e32 v1, s64, v231
	ds_read_b128 v[132:135], v1
	ds_read_b128 v[136:139], v1 offset:1024
	ds_read_b128 v[140:143], v1 offset:2048
	ds_read_b128 v[144:147], v1 offset:3072
	s_add_u32 s28, s28, 0x40000
	s_addc_u32 s29, s29, 0
	s_mov_b32 m0, s51
	v_lshl_add_u64 v[6:7], s[28:29], 0, v[198:199]
	ds_read_b128 v[148:151], v233 offset:32768
	ds_read_b128 v[152:155], v233 offset:33792
	ds_read_b128 v[156:159], v233 offset:34816
	ds_read_b128 v[160:163], v233 offset:35840
	ds_read_b128 v[164:167], v233 offset:36864
	ds_read_b128 v[168:171], v233 offset:37888
	ds_read_b128 v[172:175], v233 offset:38912
	ds_read_b128 v[176:179], v233 offset:39936
	global_load_lds_dwordx4 v[6:7], off
	v_lshl_add_u64 v[6:7], s[28:29], 0, v[202:203]
	s_mov_b32 m0, s52
	s_nop 0
	global_load_lds_dwordx4 v[6:7], off
	s_add_i32 s65, 0, 0x1c000
	s_add_u32 s28, s26, 0x8000
	s_addc_u32 s29, s27, 0
	s_add_i32 s64, s64, s48
	v_add_u32_e32 v1, s65, v231
	v_lshl_add_u64 v[252:253], s[28:29], 0, v[196:197]
	s_mov_b32 m0, s64
	ds_read_b128 v[180:183], v1
	ds_read_b128 v[184:187], v1 offset:1024
	ds_read_b128 v[188:191], v1 offset:2048
	ds_read_b128 v[192:195], v1 offset:3072
	s_waitcnt vmcnt(8)
	s_waitcnt lgkmcnt(0)
	s_barrier
	v_mfma_f32_16x16x32_bf16 v[2:5], v[132:135], v[148:151], v[2:5]
	v_mfma_f32_16x16x32_bf16 v[8:11], v[140:143], v[148:151], v[8:11]
	v_mfma_f32_16x16x32_bf16 v[32:35], v[132:135], v[156:159], v[32:35]
	v_mfma_f32_16x16x32_bf16 v[28:31], v[140:143], v[156:159], v[28:31]
	v_mfma_f32_16x16x32_bf16 v[24:27], v[132:135], v[164:167], v[24:27]
	v_mfma_f32_16x16x32_bf16 v[20:23], v[140:143], v[164:167], v[20:23]
	v_mfma_f32_16x16x32_bf16 v[16:19], v[132:135], v[172:175], v[16:19]
	v_mfma_f32_16x16x32_bf16 v[12:15], v[140:143], v[172:175], v[12:15]
	v_mfma_f32_16x16x32_bf16 v[4:7], v[136:139], v[152:155], v[2:5]
	v_mfma_f32_16x16x32_bf16 v[8:11], v[144:147], v[152:155], v[8:11]
	v_mfma_f32_16x16x32_bf16 v[32:35], v[136:139], v[160:163], v[32:35]
	v_mfma_f32_16x16x32_bf16 v[28:31], v[144:147], v[160:163], v[28:31]
	v_mfma_f32_16x16x32_bf16 v[24:27], v[136:139], v[168:171], v[24:27]
	v_mfma_f32_16x16x32_bf16 v[20:23], v[144:147], v[168:171], v[20:23]
	v_mfma_f32_16x16x32_bf16 v[16:19], v[136:139], v[176:179], v[16:19]
	v_mfma_f32_16x16x32_bf16 v[12:15], v[144:147], v[176:179], v[12:15]
	v_mfma_f32_16x16x32_bf16 v[128:131], v[180:183], v[148:151], v[128:131]
	v_mfma_f32_16x16x32_bf16 v[124:127], v[188:191], v[148:151], v[124:127]
	v_mfma_f32_16x16x32_bf16 v[120:123], v[180:183], v[156:159], v[120:123]
	v_mfma_f32_16x16x32_bf16 v[116:119], v[188:191], v[156:159], v[116:119]
	v_mfma_f32_16x16x32_bf16 v[112:115], v[180:183], v[164:167], v[112:115]
	v_mfma_f32_16x16x32_bf16 v[108:111], v[188:191], v[164:167], v[108:111]
	v_mfma_f32_16x16x32_bf16 v[104:107], v[180:183], v[172:175], v[104:107]
	v_mfma_f32_16x16x32_bf16 v[100:103], v[188:191], v[172:175], v[100:103]
	v_mfma_f32_16x16x32_bf16 v[128:131], v[184:187], v[152:155], v[128:131]
	v_mfma_f32_16x16x32_bf16 v[124:127], v[192:195], v[152:155], v[124:127]
	v_mfma_f32_16x16x32_bf16 v[120:123], v[184:187], v[160:163], v[120:123]
	v_mfma_f32_16x16x32_bf16 v[116:119], v[192:195], v[160:163], v[116:119]
	v_mfma_f32_16x16x32_bf16 v[112:115], v[184:187], v[168:171], v[112:115]
	v_mfma_f32_16x16x32_bf16 v[108:111], v[192:195], v[168:171], v[108:111]
	v_mfma_f32_16x16x32_bf16 v[104:107], v[184:187], v[176:179], v[104:107]
	v_mfma_f32_16x16x32_bf16 v[100:103], v[192:195], v[176:179], v[100:103]
	s_barrier
; #define PG8_STAGE(bufoff, gbase, voff) do { _Pragma("unroll") for (int _i = 0; _i < 2; ++_i) \
;         __builtin_amdgcn_global_load_lds((const unsigned*)((const char*)(gbase) + (voff)[_i]), (PG8_LAS unsigned*)(lds + (bufoff) + ldsw + _i * 8192), 16, 0, 0); } while (0)
; #define PG8_LDA(dst, b, h) do { _Pragma("unroll") for (int m = 0; m < 4; ++m) _Pragma("unroll") for (int k = 0; k < 2; ++k) dst[m][k] = *(const PG8_LAS bf16x8*)(lds + PG8_SA(b, h) + aoff + m * 2048 + k * 1024); } while (0)
; #define PG8_MMA(ai, bj, At, Bt) do { __builtin_amdgcn_s_setprio(1); _Pragma("unroll") for (int m = 0; m < 4; ++m) _Pragma("unroll") for (int n = 0; n < 2; ++n) _Pragma("unroll") for (int k = 0; k < 2; ++k) \
;         acc[ai][bj][m][n] = __builtin_amdgcn_mfma_f32_16x16x32_bf16(Bt[n][k], At[m][k], acc[ai][bj][m][n], 0, 0, 0); __builtin_amdgcn_s_setprio(0); } while (0)
; #define PG8_WAIT_V(n) asm volatile("s_waitcnt vmcnt(" #n ")" ::: "memory")
; #define PG8_WAIT_L(n) asm volatile("s_waitcnt lgkmcnt(" #n ")" ::: "memory")
; #define PG8_BAR __builtin_amdgcn_s_barrier()
; #define PG8_SCHED __builtin_amdgcn_sched_barrier(0)
; template <class Epi, class Sched>
; __device__ __forceinline__ void gemm_phase(PG8_LAS unsigned char* lds, const Gemm g, const Sched& S, const Epi& E) {
;     ...
;             PG8_LDA(At, 1, 1); PG8_STAGE(PG8_SA(1, 0), a3, voffA);
;             PG8_BAR; PG8_WAIT_L(0); PG8_MMA(1, 0, At, B0); PG8_BAR; PG8_SCHED;
;             PG8_STAGE(PG8_SB(1, 1), b3 + hstepB, voffB);
;             PG8_WAIT_V(6); PG8_BAR; PG8_MMA(1, 1, At, B1); PG8_BAR;
;     ...
;     PG8_WAIT_V(0);
;     if (wr == 0) PG8_BAR;
;     PG8_BAR;
	global_load_lds_dwordx4 v[252:253], off
	v_lshl_add_u64 v[252:253], s[28:29], 0, v[200:201]
	s_add_i32 m0, s64, 0x2000
	s_nop 0
	global_load_lds_dwordx4 v[252:253], off
	s_mov_b32 m0, s55
	v_lshl_add_u64 v[2:3], v[212:213], 0, s[12:13]
	ds_read_b128 v[148:151], v233 offset:49152
	ds_read_b128 v[152:155], v233 offset:50176
	ds_read_b128 v[156:159], v233 offset:51200
	ds_read_b128 v[160:163], v233 offset:52224
	ds_read_b128 v[164:167], v233 offset:53248
	ds_read_b128 v[168:171], v233 offset:54272
	ds_read_b128 v[172:175], v233 offset:55296
	ds_read_b128 v[176:179], v233 offset:56320
	global_load_lds_dwordx4 v[2:3], off
	v_lshl_add_u64 v[2:3], v[214:215], 0, s[12:13]
	s_mov_b32 m0, s56
	s_nop 0
	global_load_lds_dwordx4 v[2:3], off
	s_add_u32 s26, s26, 0xc000
	s_addc_u32 s27, s27, 0
	s_add_i32 s28, s65, s48
	v_lshl_add_u64 v[2:3], s[26:27], 0, v[196:197]
	s_mov_b32 m0, s28
	s_nop 0
	global_load_lds_dwordx4 v[2:3], off
	v_lshl_add_u64 v[2:3], s[26:27], 0, v[200:201]
	s_add_i32 m0, s28, 0x2000
	s_nop 0
	global_load_lds_dwordx4 v[2:3], off
	s_add_i32 s63, s63, 2
	s_add_u32 s61, s61, 0x10000
	s_addc_u32 s62, s62, 0
	s_add_u32 s24, s24, 0x100
	s_addc_u32 s25, s25, 0
	s_cmp_gt_u32 s63, 13
	s_waitcnt vmcnt(8)
	s_waitcnt lgkmcnt(0)
	s_barrier
	v_mfma_f32_16x16x32_bf16 v[96:99], v[132:135], v[148:151], v[96:99]
	v_mfma_f32_16x16x32_bf16 v[92:95], v[140:143], v[148:151], v[92:95]
	v_mfma_f32_16x16x32_bf16 v[88:91], v[132:135], v[156:159], v[88:91]
	v_mfma_f32_16x16x32_bf16 v[84:87], v[140:143], v[156:159], v[84:87]
	v_mfma_f32_16x16x32_bf16 v[80:83], v[132:135], v[164:167], v[80:83]
	v_mfma_f32_16x16x32_bf16 v[76:79], v[140:143], v[164:167], v[76:79]
	v_mfma_f32_16x16x32_bf16 v[72:75], v[132:135], v[172:175], v[72:75]
	v_mfma_f32_16x16x32_bf16 v[68:71], v[140:143], v[172:175], v[68:71]
	v_mfma_f32_16x16x32_bf16 v[96:99], v[136:139], v[152:155], v[96:99]
	v_mfma_f32_16x16x32_bf16 v[92:95], v[144:147], v[152:155], v[92:95]
	v_mfma_f32_16x16x32_bf16 v[88:91], v[136:139], v[160:163], v[88:91]
	v_mfma_f32_16x16x32_bf16 v[84:87], v[144:147], v[160:163], v[84:87]
	v_mfma_f32_16x16x32_bf16 v[80:83], v[136:139], v[168:171], v[80:83]
	v_mfma_f32_16x16x32_bf16 v[76:79], v[144:147], v[168:171], v[76:79]
	v_mfma_f32_16x16x32_bf16 v[72:75], v[136:139], v[176:179], v[72:75]
	v_mfma_f32_16x16x32_bf16 v[68:71], v[144:147], v[176:179], v[68:71]
	v_mfma_f32_16x16x32_bf16 v[64:67], v[180:183], v[148:151], v[64:67]
	v_mfma_f32_16x16x32_bf16 v[60:63], v[188:191], v[148:151], v[60:63]
	v_mfma_f32_16x16x32_bf16 v[56:59], v[180:183], v[156:159], v[56:59]
	v_mfma_f32_16x16x32_bf16 v[52:55], v[188:191], v[156:159], v[52:55]
	v_mfma_f32_16x16x32_bf16 v[48:51], v[180:183], v[164:167], v[48:51]
	v_mfma_f32_16x16x32_bf16 v[44:47], v[188:191], v[164:167], v[44:47]
	v_mfma_f32_16x16x32_bf16 v[40:43], v[180:183], v[172:175], v[40:43]
	v_mfma_f32_16x16x32_bf16 v[36:39], v[188:191], v[172:175], v[36:39]
	v_mfma_f32_16x16x32_bf16 v[64:67], v[184:187], v[152:155], v[64:67]
	v_mfma_f32_16x16x32_bf16 v[60:63], v[192:195], v[152:155], v[60:63]
	v_mfma_f32_16x16x32_bf16 v[56:59], v[184:187], v[160:163], v[56:59]
	v_mfma_f32_16x16x32_bf16 v[52:55], v[192:195], v[160:163], v[52:55]
	v_mfma_f32_16x16x32_bf16 v[48:51], v[184:187], v[168:171], v[48:51]
	v_mfma_f32_16x16x32_bf16 v[44:47], v[192:195], v[168:171], v[44:47]
	v_mfma_f32_16x16x32_bf16 v[40:43], v[184:187], v[176:179], v[40:43]
	v_mfma_f32_16x16x32_bf16 v[36:39], v[192:195], v[176:179], v[36:39]
	s_barrier
	s_cbranch_scc0 .LBB0_613
	s_cmp_eq_u32 s78, 0
	s_cbranch_scc0 .Lhalf_skip_x_4
	s_barrier

; #define PG8_STAGE(bufoff, gbase, voff) do { _Pragma("unroll") for (int _i = 0; _i < 2; ++_i) \
;         __builtin_amdgcn_global_load_lds((const unsigned*)((const char*)(gbase) + (voff)[_i]), (PG8_LAS unsigned*)(lds + (bufoff) + ldsw + _i * 8192), 16, 0, 0); } while (0)
; #define PG8_LDA(dst, b, h) do { _Pragma("unroll") for (int m = 0; m < 4; ++m) _Pragma("unroll") for (int k = 0; k < 2; ++k) dst[m][k] = *(const PG8_LAS bf16x8*)(lds + PG8_SA(b, h) + aoff + m * 2048 + k * 1024); } while (0)
; #define PG8_LDB(dst, b, h) do { _Pragma("unroll") for (int n = 0; n < 2; ++n) _Pragma("unroll") for (int k = 0; k < 2; ++k) dst[n][k] = *(const PG8_LAS bf16x8*)(lds + PG8_SB(b, h) + boff + n * 2048 + k * 1024); } while (0)
; #define PG8_MMA(ai, bj, At, Bt) do { __builtin_amdgcn_s_setprio(1); _Pragma("unroll") for (int m = 0; m < 4; ++m) _Pragma("unroll") for (int n = 0; n < 2; ++n) _Pragma("unroll") for (int k = 0; k < 2; ++k) \
;         acc[ai][bj][m][n] = __builtin_amdgcn_mfma_f32_16x16x32_bf16(Bt[n][k], At[m][k], acc[ai][bj][m][n], 0, 0, 0); __builtin_amdgcn_s_setprio(0); } while (0)
; #define PG8_WAIT_V(n) asm volatile("s_waitcnt vmcnt(" #n ")" ::: "memory")
; #define PG8_WAIT_L(n) asm volatile("s_waitcnt lgkmcnt(" #n ")" ::: "memory")
; template <class Epi, class Sched>
; __device__ __forceinline__ void gemm_phase(PG8_LAS unsigned char* lds, const Gemm g, const Sched& S, const Epi& E) {
;     ...
;             const bool last = (t == nt - 2);
;             const char* a1 = cA + (size_t)(t + 1) * kstep;
;             const char* a2 = last ? nA : cA + (size_t)(t + 2) * kstep; const char* b2 = last ? nB : cB + (size_t)(t + 2) * kstepB;
;             const char* a3 = a2 + kstep; const char* b3 = b2 + kstepB;
;             if (last && has_next) S.a_ready(nxt);
;             PG8_LDB(B0, 0, 0); PG8_SCHED; PG8_LDA(At, 0, 0); PG8_STAGE(PG8_SA(1, 1), a1 + hstep, voffA);
;             PG8_WAIT_L(8); PG8_BAR; PG8_WAIT_L(0); PG8_MMA(0, 0, At, B0); PG8_BAR; PG8_SCHED;
;             PG8_LDB(B1, 0, 1); PG8_STAGE(PG8_SB(0, 0), b2, voffB);
;             PG8_BAR; PG8_WAIT_L(0); PG8_MMA(0, 1, At, B1); PG8_BAR;
;             PG8_LDA(At, 0, 1); PG8_STAGE(PG8_SA(0, 0), a2, voffA);
;             PG8_BAR; PG8_WAIT_L(0); PG8_MMA(1, 0, At, B0); PG8_BAR; PG8_SCHED;
;             PG8_STAGE(PG8_SB(0, 1), b2 + hstepB, voffB);
;             PG8_WAIT_V(6); PG8_BAR; PG8_MMA(1, 1, At, B1); PG8_BAR;
.Lhalf_skip_y_5:
.LBB0_783:
	ds_read_b128 v[128:131], v197
	ds_read_b128 v[132:135], v197 offset:1024
	ds_read_b128 v[136:139], v197 offset:2048
	ds_read_b128 v[140:143], v197 offset:3072
	s_add_u32 s30, s28, 0x100
	s_addc_u32 s31, s29, 0
	s_cmp_eq_u32 s69, 28
	s_cselect_b32 s39, s19, s31
	s_cselect_b32 s38, s65, s30
	s_cselect_b32 s37, s21, s68
	s_cselect_b32 s36, s66, s67
	v_lshl_add_u64 v[192:193], s[28:29], 0, v[172:173]
	s_add_i32 m0, s27, 0xc000
	ds_read_b128 v[144:147], v198
	ds_read_b128 v[148:151], v198 offset:1024
	ds_read_b128 v[152:155], v198 offset:2048
	ds_read_b128 v[156:159], v198 offset:3072
	ds_read_b128 v[160:163], v198 offset:4096
	ds_read_b128 v[180:183], v198 offset:5120
	ds_read_b128 v[184:187], v198 offset:6144
	ds_read_b128 v[188:191], v198 offset:7168
	global_load_lds_dwordx4 v[192:193], off
	v_lshl_add_u64 v[192:193], s[28:29], 0, v[174:175]
	s_add_i32 m0, s27, 0xe000
	s_nop 0
	global_load_lds_dwordx4 v[192:193], off
	s_add_i32 s28, s62, s54
	v_lshl_add_u64 v[192:193], s[36:37], 0, v[164:165]
	s_mov_b32 m0, s28
	ds_read_b128 v[200:203], v199
	ds_read_b128 v[204:207], v199 offset:1024
	ds_read_b128 v[208:211], v199 offset:2048
	ds_read_b128 v[212:215], v199 offset:3072
	s_waitcnt vmcnt(8)
	s_waitcnt lgkmcnt(0)
	s_barrier
	v_mfma_f32_16x16x32_bf16 v[124:127], v[128:131], v[144:147], v[124:127]
	v_mfma_f32_16x16x32_bf16 v[120:123], v[136:139], v[144:147], v[120:123]
	v_mfma_f32_16x16x32_bf16 v[116:119], v[128:131], v[152:155], v[116:119]
	v_mfma_f32_16x16x32_bf16 v[104:107], v[136:139], v[152:155], v[104:107]
	v_mfma_f32_16x16x32_bf16 v[92:95], v[128:131], v[160:163], v[92:95]
	v_mfma_f32_16x16x32_bf16 v[88:91], v[136:139], v[160:163], v[88:91]
	v_mfma_f32_16x16x32_bf16 v[76:79], v[128:131], v[184:187], v[76:79]
	v_mfma_f32_16x16x32_bf16 v[72:75], v[136:139], v[184:187], v[72:75]
	v_mfma_f32_16x16x32_bf16 v[124:127], v[132:135], v[148:151], v[124:127]
	v_mfma_f32_16x16x32_bf16 v[120:123], v[140:143], v[148:151], v[120:123]
	v_mfma_f32_16x16x32_bf16 v[116:119], v[132:135], v[156:159], v[116:119]
	v_mfma_f32_16x16x32_bf16 v[104:107], v[140:143], v[156:159], v[104:107]
	v_mfma_f32_16x16x32_bf16 v[92:95], v[132:135], v[180:183], v[92:95]
	v_mfma_f32_16x16x32_bf16 v[88:91], v[140:143], v[180:183], v[88:91]
	v_mfma_f32_16x16x32_bf16 v[76:79], v[132:135], v[188:191], v[76:79]
	v_mfma_f32_16x16x32_bf16 v[72:75], v[140:143], v[188:191], v[72:75]
	v_mfma_f32_16x16x32_bf16 v[112:115], v[200:203], v[144:147], v[112:115]
	v_mfma_f32_16x16x32_bf16 v[108:111], v[208:211], v[144:147], v[108:111]
	v_mfma_f32_16x16x32_bf16 v[100:103], v[200:203], v[152:155], v[100:103]
	v_mfma_f32_16x16x32_bf16 v[96:99], v[208:211], v[152:155], v[96:99]
	v_mfma_f32_16x16x32_bf16 v[84:87], v[200:203], v[160:163], v[84:87]
	v_mfma_f32_16x16x32_bf16 v[80:83], v[208:211], v[160:163], v[80:83]
	v_mfma_f32_16x16x32_bf16 v[68:71], v[200:203], v[184:187], v[68:71]
	v_mfma_f32_16x16x32_bf16 v[64:67], v[208:211], v[184:187], v[64:67]
	v_mfma_f32_16x16x32_bf16 v[112:115], v[204:207], v[148:151], v[112:115]
	v_mfma_f32_16x16x32_bf16 v[108:111], v[212:215], v[148:151], v[108:111]
	v_mfma_f32_16x16x32_bf16 v[100:103], v[204:207], v[156:159], v[100:103]
	v_mfma_f32_16x16x32_bf16 v[96:99], v[212:215], v[156:159], v[96:99]
	v_mfma_f32_16x16x32_bf16 v[84:87], v[204:207], v[180:183], v[84:87]
	v_mfma_f32_16x16x32_bf16 v[80:83], v[212:215], v[180:183], v[80:83]
	v_mfma_f32_16x16x32_bf16 v[68:71], v[204:207], v[188:191], v[68:71]
	v_mfma_f32_16x16x32_bf16 v[64:67], v[212:215], v[188:191], v[64:67]
	s_barrier
	global_load_lds_dwordx4 v[192:193], off
	v_lshl_add_u64 v[192:193], s[36:37], 0, v[168:169]
	s_add_i32 m0, s28, 0x2000
	s_nop 0
	global_load_lds_dwordx4 v[192:193], off
	s_mov_b32 m0, s27
	v_lshl_add_u64 v[192:193], s[38:39], 0, v[166:167]
	ds_read_b128 v[144:147], v198 offset:16384
	ds_read_b128 v[148:151], v198 offset:17408
	ds_read_b128 v[152:155], v198 offset:18432
	ds_read_b128 v[156:159], v198 offset:19456
	ds_read_b128 v[160:163], v198 offset:20480
	ds_read_b128 v[180:183], v198 offset:21504
	ds_read_b128 v[184:187], v198 offset:22528
	ds_read_b128 v[188:191], v198 offset:23552
	global_load_lds_dwordx4 v[192:193], off
	v_lshl_add_u64 v[216:217], s[38:39], 0, v[170:171]
	s_mov_b32 m0, s55
	s_nop 0
	global_load_lds_dwordx4 v[216:217], off
	s_add_u32 s28, s36, 0x4000
	s_addc_u32 s29, s37, 0
	s_add_i32 s70, s63, s54
	v_lshl_add_u64 v[250:251], s[28:29], 0, v[164:165]
	s_mov_b32 m0, s70
	s_nop 0
	global_load_lds_dwordx4 v[250:251], off
	v_lshl_add_u64 v[250:251], s[28:29], 0, v[168:169]
	s_add_i32 m0, s70, 0x2000
	s_nop 0
	global_load_lds_dwordx4 v[250:251], off
	s_waitcnt vmcnt(8)
	s_waitcnt lgkmcnt(0)
	s_barrier
; #define PG8_STAGE(bufoff, gbase, voff) do { _Pragma("unroll") for (int _i = 0; _i < 2; ++_i) \
;         __builtin_amdgcn_global_load_lds((const unsigned*)((const char*)(gbase) + (voff)[_i]), (PG8_LAS unsigned*)(lds + (bufoff) + ldsw + _i * 8192), 16, 0, 0); } while (0)
; #define PG8_LDA(dst, b, h) do { _Pragma("unroll") for (int m = 0; m < 4; ++m) _Pragma("unroll") for (int k = 0; k < 2; ++k) dst[m][k] = *(const PG8_LAS bf16x8*)(lds + PG8_SA(b, h) + aoff + m * 2048 + k * 1024); } while (0)
; #define PG8_LDB(dst, b, h) do { _Pragma("unroll") for (int n = 0; n < 2; ++n) _Pragma("unroll") for (int k = 0; k < 2; ++k) dst[n][k] = *(const PG8_LAS bf16x8*)(lds + PG8_SB(b, h) + boff + n * 2048 + k * 1024); } while (0)
; #define PG8_MMA(ai, bj, At, Bt) do { __builtin_amdgcn_s_setprio(1); _Pragma("unroll") for (int m = 0; m < 4; ++m) _Pragma("unroll") for (int n = 0; n < 2; ++n) _Pragma("unroll") for (int k = 0; k < 2; ++k) \
;         acc[ai][bj][m][n] = __builtin_amdgcn_mfma_f32_16x16x32_bf16(Bt[n][k], At[m][k], acc[ai][bj][m][n], 0, 0, 0); __builtin_amdgcn_s_setprio(0); } while (0)
; #define PG8_WAIT_V(n) asm volatile("s_waitcnt vmcnt(" #n ")" ::: "memory")
; #define PG8_WAIT_L(n) asm volatile("s_waitcnt lgkmcnt(" #n ")" ::: "memory")
; #define PG8_BAR __builtin_amdgcn_s_barrier()
; #define PG8_SCHED __builtin_amdgcn_sched_barrier(0)
; template <class Epi, class Sched>
; __device__ __forceinline__ void gemm_phase(PG8_LAS unsigned char* lds, const Gemm g, const Sched& S, const Epi& E) {
;     ...
;             PG8_BAR; PG8_WAIT_L(0); PG8_MMA(1, 0, At, B0); PG8_BAR; PG8_SCHED;
;             PG8_STAGE(PG8_SB(0, 1), b2 + hstepB, voffB);
;             PG8_WAIT_V(6); PG8_BAR; PG8_MMA(1, 1, At, B1); PG8_BAR;
;             PG8_LDB(B0, 1, 0); PG8_SCHED; PG8_LDA(At, 1, 0); PG8_STAGE(PG8_SA(0, 1), a2 + hstep, voffA);
;             PG8_WAIT_L(8); PG8_BAR; PG8_WAIT_L(0); PG8_MMA(0, 0, At, B0); PG8_BAR; PG8_SCHED;
;             PG8_LDB(B1, 1, 1); PG8_STAGE(PG8_SB(1, 0), b3, voffB);
;             PG8_BAR; PG8_WAIT_L(0); PG8_MMA(0, 1, At, B1); PG8_BAR;
;             PG8_LDA(At, 1, 1); PG8_STAGE(PG8_SA(1, 0), a3, voffA);
;             PG8_BAR; PG8_WAIT_L(0); PG8_MMA(1, 0, At, B0); PG8_BAR; PG8_SCHED;
	v_mfma_f32_16x16x32_bf16 v[60:63], v[128:131], v[144:147], v[60:63]
	v_mfma_f32_16x16x32_bf16 v[56:59], v[136:139], v[144:147], v[56:59]
	v_mfma_f32_16x16x32_bf16 v[44:47], v[128:131], v[152:155], v[44:47]
	v_mfma_f32_16x16x32_bf16 v[40:43], v[136:139], v[152:155], v[40:43]
	v_mfma_f32_16x16x32_bf16 v[28:31], v[128:131], v[160:163], v[28:31]
	v_mfma_f32_16x16x32_bf16 v[24:27], v[136:139], v[160:163], v[24:27]
	v_mfma_f32_16x16x32_bf16 v[12:15], v[128:131], v[184:187], v[12:15]
	v_mfma_f32_16x16x32_bf16 v[8:11], v[136:139], v[184:187], v[8:11]
	v_mfma_f32_16x16x32_bf16 v[60:63], v[132:135], v[148:151], v[60:63]
	v_mfma_f32_16x16x32_bf16 v[56:59], v[140:143], v[148:151], v[56:59]
	v_mfma_f32_16x16x32_bf16 v[44:47], v[132:135], v[156:159], v[44:47]
	v_mfma_f32_16x16x32_bf16 v[40:43], v[140:143], v[156:159], v[40:43]
	v_mfma_f32_16x16x32_bf16 v[28:31], v[132:135], v[180:183], v[28:31]
	v_mfma_f32_16x16x32_bf16 v[24:27], v[140:143], v[180:183], v[24:27]
	v_mfma_f32_16x16x32_bf16 v[12:15], v[132:135], v[188:191], v[12:15]
	v_mfma_f32_16x16x32_bf16 v[8:11], v[140:143], v[188:191], v[8:11]
	v_mfma_f32_16x16x32_bf16 v[52:55], v[200:203], v[144:147], v[52:55]
	v_mfma_f32_16x16x32_bf16 v[48:51], v[208:211], v[144:147], v[48:51]
	v_mfma_f32_16x16x32_bf16 v[36:39], v[200:203], v[152:155], v[36:39]
	v_mfma_f32_16x16x32_bf16 v[32:35], v[208:211], v[152:155], v[32:35]
	v_mfma_f32_16x16x32_bf16 v[20:23], v[200:203], v[160:163], v[20:23]
	v_mfma_f32_16x16x32_bf16 v[16:19], v[208:211], v[160:163], v[16:19]
	v_mfma_f32_16x16x32_bf16 v[4:7], v[200:203], v[184:187], v[4:7]
	v_mfma_f32_16x16x32_bf16 v[0:3], v[208:211], v[184:187], v[0:3]
	v_mfma_f32_16x16x32_bf16 v[52:55], v[204:207], v[148:151], v[52:55]
	v_mfma_f32_16x16x32_bf16 v[48:51], v[212:215], v[148:151], v[48:51]
	v_mfma_f32_16x16x32_bf16 v[36:39], v[204:207], v[156:159], v[36:39]
	v_mfma_f32_16x16x32_bf16 v[32:35], v[212:215], v[156:159], v[32:35]
	v_mfma_f32_16x16x32_bf16 v[20:23], v[204:207], v[180:183], v[20:23]
	v_mfma_f32_16x16x32_bf16 v[16:19], v[212:215], v[180:183], v[16:19]
	v_mfma_f32_16x16x32_bf16 v[4:7], v[204:207], v[188:191], v[4:7]
	v_mfma_f32_16x16x32_bf16 v[0:3], v[212:215], v[188:191], v[0:3]
	s_barrier
	s_add_i32 s70, 0, 0x18000
	v_add_u32_e32 v140, s70, v195
	ds_read_b128 v[128:131], v140
	ds_read_b128 v[132:135], v140 offset:1024
	ds_read_b128 v[136:139], v140 offset:2048
	ds_read_b128 v[140:143], v140 offset:3072
	s_add_u32 s28, s38, 0x80000
	s_addc_u32 s29, s39, 0
	s_mov_b32 m0, s56
	v_lshl_add_u64 v[200:201], s[28:29], 0, v[166:167]
	ds_read_b128 v[144:147], v198 offset:32768
	ds_read_b128 v[148:151], v198 offset:33792
	ds_read_b128 v[152:155], v198 offset:34816
	ds_read_b128 v[156:159], v198 offset:35840
	ds_read_b128 v[160:163], v198 offset:36864
	ds_read_b128 v[180:183], v198 offset:37888
	ds_read_b128 v[184:187], v198 offset:38912
	ds_read_b128 v[188:191], v198 offset:39936
	global_load_lds_dwordx4 v[200:201], off
	v_lshl_add_u64 v[200:201], s[28:29], 0, v[170:171]
	s_mov_b32 m0, s57
	s_nop 0
	global_load_lds_dwordx4 v[200:201], off
	s_add_i32 s38, 0, 0x1c000
	s_add_u32 s28, s36, 0x8000
	s_addc_u32 s29, s37, 0
	s_add_i32 s39, s70, s54
	v_add_u32_e32 v212, s38, v195
	v_lshl_add_u64 v[218:219], s[28:29], 0, v[164:165]
	s_mov_b32 m0, s39
	ds_read_b128 v[200:203], v212
	ds_read_b128 v[204:207], v212 offset:1024
	ds_read_b128 v[208:211], v212 offset:2048
	ds_read_b128 v[212:215], v212 offset:3072
	s_waitcnt vmcnt(8)
	s_waitcnt lgkmcnt(0)
	s_barrier
	v_mfma_f32_16x16x32_bf16 v[124:127], v[128:131], v[144:147], v[124:127]
	v_mfma_f32_16x16x32_bf16 v[120:123], v[136:139], v[144:147], v[120:123]
	v_mfma_f32_16x16x32_bf16 v[116:119], v[128:131], v[152:155], v[116:119]
	v_mfma_f32_16x16x32_bf16 v[104:107], v[136:139], v[152:155], v[104:107]
	v_mfma_f32_16x16x32_bf16 v[92:95], v[128:131], v[160:163], v[92:95]
	v_mfma_f32_16x16x32_bf16 v[88:91], v[136:139], v[160:163], v[88:91]
	v_mfma_f32_16x16x32_bf16 v[76:79], v[128:131], v[184:187], v[76:79]
	v_mfma_f32_16x16x32_bf16 v[72:75], v[136:139], v[184:187], v[72:75]
	v_mfma_f32_16x16x32_bf16 v[124:127], v[132:135], v[148:151], v[124:127]
	v_mfma_f32_16x16x32_bf16 v[120:123], v[140:143], v[148:151], v[120:123]
	v_mfma_f32_16x16x32_bf16 v[116:119], v[132:135], v[156:159], v[116:119]
	v_mfma_f32_16x16x32_bf16 v[104:107], v[140:143], v[156:159], v[104:107]
	v_mfma_f32_16x16x32_bf16 v[92:95], v[132:135], v[180:183], v[92:95]
	v_mfma_f32_16x16x32_bf16 v[88:91], v[140:143], v[180:183], v[88:91]
	v_mfma_f32_16x16x32_bf16 v[76:79], v[132:135], v[188:191], v[76:79]
	v_mfma_f32_16x16x32_bf16 v[72:75], v[140:143], v[188:191], v[72:75]
	v_mfma_f32_16x16x32_bf16 v[112:115], v[200:203], v[144:147], v[112:115]
	v_mfma_f32_16x16x32_bf16 v[108:111], v[208:211], v[144:147], v[108:111]
	v_mfma_f32_16x16x32_bf16 v[100:103], v[200:203], v[152:155], v[100:103]
	v_mfma_f32_16x16x32_bf16 v[96:99], v[208:211], v[152:155], v[96:99]
	v_mfma_f32_16x16x32_bf16 v[84:87], v[200:203], v[160:163], v[84:87]
	v_mfma_f32_16x16x32_bf16 v[80:83], v[208:211], v[160:163], v[80:83]
	v_mfma_f32_16x16x32_bf16 v[68:71], v[200:203], v[184:187], v[68:71]
	v_mfma_f32_16x16x32_bf16 v[64:67], v[208:211], v[184:187], v[64:67]
	v_mfma_f32_16x16x32_bf16 v[112:115], v[204:207], v[148:151], v[112:115]
	v_mfma_f32_16x16x32_bf16 v[108:111], v[212:215], v[148:151], v[108:111]
	v_mfma_f32_16x16x32_bf16 v[100:103], v[204:207], v[156:159], v[100:103]
	v_mfma_f32_16x16x32_bf16 v[96:99], v[212:215], v[156:159], v[96:99]
	v_mfma_f32_16x16x32_bf16 v[84:87], v[204:207], v[180:183], v[84:87]
	v_mfma_f32_16x16x32_bf16 v[80:83], v[212:215], v[180:183], v[80:83]
	v_mfma_f32_16x16x32_bf16 v[68:71], v[204:207], v[188:191], v[68:71]
	v_mfma_f32_16x16x32_bf16 v[64:67], v[212:215], v[188:191], v[64:67]
	s_barrier
; #define PG8_STAGE(bufoff, gbase, voff) do { _Pragma("unroll") for (int _i = 0; _i < 2; ++_i) \
;         __builtin_amdgcn_global_load_lds((const unsigned*)((const char*)(gbase) + (voff)[_i]), (PG8_LAS unsigned*)(lds + (bufoff) + ldsw + _i * 8192), 16, 0, 0); } while (0)
; #define PG8_LDA(dst, b, h) do { _Pragma("unroll") for (int m = 0; m < 4; ++m) _Pragma("unroll") for (int k = 0; k < 2; ++k) dst[m][k] = *(const PG8_LAS bf16x8*)(lds + PG8_SA(b, h) + aoff + m * 2048 + k * 1024); } while (0)
; #define PG8_MMA(ai, bj, At, Bt) do { __builtin_amdgcn_s_setprio(1); _Pragma("unroll") for (int m = 0; m < 4; ++m) _Pragma("unroll") for (int n = 0; n < 2; ++n) _Pragma("unroll") for (int k = 0; k < 2; ++k) \
;         acc[ai][bj][m][n] = __builtin_amdgcn_mfma_f32_16x16x32_bf16(Bt[n][k], At[m][k], acc[ai][bj][m][n], 0, 0, 0); __builtin_amdgcn_s_setprio(0); } while (0)
; #define PG8_WAIT_V(n) asm volatile("s_waitcnt vmcnt(" #n ")" ::: "memory")
; #define PG8_WAIT_L(n) asm volatile("s_waitcnt lgkmcnt(" #n ")" ::: "memory")
; #define PG8_BAR __builtin_amdgcn_s_barrier()
; #define PG8_SCHED __builtin_amdgcn_sched_barrier(0)
; template <class Epi, class Sched>
; __device__ __forceinline__ void gemm_phase(PG8_LAS unsigned char* lds, const Gemm g, const Sched& S, const Epi& E) {
;     ...
;             PG8_LDA(At, 1, 1); PG8_STAGE(PG8_SA(1, 0), a3, voffA);
;             PG8_BAR; PG8_WAIT_L(0); PG8_MMA(1, 0, At, B0); PG8_BAR; PG8_SCHED;
;             PG8_STAGE(PG8_SB(1, 1), b3 + hstepB, voffB);
;             PG8_WAIT_V(6); PG8_BAR; PG8_MMA(1, 1, At, B1); PG8_BAR;
;     ...
;     PG8_WAIT_V(0);
;     if (wr == 0) PG8_BAR;
;     PG8_BAR;
	global_load_lds_dwordx4 v[218:219], off
	v_lshl_add_u64 v[218:219], s[28:29], 0, v[168:169]
	s_add_i32 m0, s39, 0x2000
	s_nop 0
	global_load_lds_dwordx4 v[218:219], off
	s_mov_b32 m0, s59
	v_lshl_add_u64 v[192:193], v[192:193], 0, s[10:11]
	ds_read_b128 v[144:147], v198 offset:49152
	ds_read_b128 v[148:151], v198 offset:50176
	ds_read_b128 v[152:155], v198 offset:51200
	ds_read_b128 v[156:159], v198 offset:52224
	ds_read_b128 v[160:163], v198 offset:53248
	ds_read_b128 v[180:183], v198 offset:54272
	ds_read_b128 v[184:187], v198 offset:55296
	ds_read_b128 v[188:191], v198 offset:56320
	global_load_lds_dwordx4 v[192:193], off
	v_lshl_add_u64 v[192:193], v[216:217], 0, s[10:11]
	s_mov_b32 m0, s60
	s_nop 0
	global_load_lds_dwordx4 v[192:193], off
	s_add_u32 s28, s36, 0xc000
	s_addc_u32 s29, s37, 0
	s_add_i32 s36, s38, s54
	v_lshl_add_u64 v[252:253], s[28:29], 0, v[164:165]
	s_mov_b32 m0, s36
	s_nop 0
	global_load_lds_dwordx4 v[252:253], off
	v_lshl_add_u64 v[252:253], s[28:29], 0, v[168:169]
	s_add_i32 m0, s36, 0x2000
	s_nop 0
	global_load_lds_dwordx4 v[252:253], off
	s_add_i32 s69, s69, 2
	s_add_u32 s67, s67, 0x10000
	s_addc_u32 s68, s68, 0
	s_cmp_gt_u32 s69, 29
	s_mov_b64 s[28:29], s[30:31]
	s_waitcnt vmcnt(8)
	s_waitcnt lgkmcnt(0)
	s_barrier
	v_mfma_f32_16x16x32_bf16 v[60:63], v[128:131], v[144:147], v[60:63]
	v_mfma_f32_16x16x32_bf16 v[56:59], v[136:139], v[144:147], v[56:59]
	v_mfma_f32_16x16x32_bf16 v[44:47], v[128:131], v[152:155], v[44:47]
	v_mfma_f32_16x16x32_bf16 v[40:43], v[136:139], v[152:155], v[40:43]
	v_mfma_f32_16x16x32_bf16 v[28:31], v[128:131], v[160:163], v[28:31]
	v_mfma_f32_16x16x32_bf16 v[24:27], v[136:139], v[160:163], v[24:27]
	v_mfma_f32_16x16x32_bf16 v[12:15], v[128:131], v[184:187], v[12:15]
	v_mfma_f32_16x16x32_bf16 v[8:11], v[136:139], v[184:187], v[8:11]
	v_mfma_f32_16x16x32_bf16 v[60:63], v[132:135], v[148:151], v[60:63]
	v_mfma_f32_16x16x32_bf16 v[56:59], v[140:143], v[148:151], v[56:59]
	v_mfma_f32_16x16x32_bf16 v[44:47], v[132:135], v[156:159], v[44:47]
	v_mfma_f32_16x16x32_bf16 v[40:43], v[140:143], v[156:159], v[40:43]
	v_mfma_f32_16x16x32_bf16 v[28:31], v[132:135], v[180:183], v[28:31]
	v_mfma_f32_16x16x32_bf16 v[24:27], v[140:143], v[180:183], v[24:27]
	v_mfma_f32_16x16x32_bf16 v[12:15], v[132:135], v[188:191], v[12:15]
	v_mfma_f32_16x16x32_bf16 v[8:11], v[140:143], v[188:191], v[8:11]
	v_mfma_f32_16x16x32_bf16 v[52:55], v[200:203], v[144:147], v[52:55]
	v_mfma_f32_16x16x32_bf16 v[48:51], v[208:211], v[144:147], v[48:51]
	v_mfma_f32_16x16x32_bf16 v[36:39], v[200:203], v[152:155], v[36:39]
	v_mfma_f32_16x16x32_bf16 v[32:35], v[208:211], v[152:155], v[32:35]
	v_mfma_f32_16x16x32_bf16 v[20:23], v[200:203], v[160:163], v[20:23]
	v_mfma_f32_16x16x32_bf16 v[16:19], v[208:211], v[160:163], v[16:19]
	v_mfma_f32_16x16x32_bf16 v[4:7], v[200:203], v[184:187], v[4:7]
	v_mfma_f32_16x16x32_bf16 v[0:3], v[208:211], v[184:187], v[0:3]
	v_mfma_f32_16x16x32_bf16 v[52:55], v[204:207], v[148:151], v[52:55]
	v_mfma_f32_16x16x32_bf16 v[48:51], v[212:215], v[148:151], v[48:51]
	v_mfma_f32_16x16x32_bf16 v[36:39], v[204:207], v[156:159], v[36:39]
	v_mfma_f32_16x16x32_bf16 v[32:35], v[212:215], v[156:159], v[32:35]
	v_mfma_f32_16x16x32_bf16 v[20:23], v[204:207], v[180:183], v[20:23]
	v_mfma_f32_16x16x32_bf16 v[16:19], v[212:215], v[180:183], v[16:19]
	v_mfma_f32_16x16x32_bf16 v[4:7], v[204:207], v[188:191], v[4:7]
	v_mfma_f32_16x16x32_bf16 v[0:3], v[212:215], v[188:191], v[0:3]
	s_barrier
	s_cbranch_scc0 .LBB0_783
	s_cmp_eq_u32 s78, 0
	s_cbranch_scc0 .Lhalf_skip_x_5
	s_barrier

; #define PG8_STAGE(bufoff, gbase, voff) do { _Pragma("unroll") for (int _i = 0; _i < 2; ++_i) \
;         __builtin_amdgcn_global_load_lds((const unsigned*)((const char*)(gbase) + (voff)[_i]), (PG8_LAS unsigned*)(lds + (bufoff) + ldsw + _i * 8192), 16, 0, 0); } while (0)
; #define PG8_LDA(dst, b, h) do { _Pragma("unroll") for (int m = 0; m < 4; ++m) _Pragma("unroll") for (int k = 0; k < 2; ++k) dst[m][k] = *(const PG8_LAS bf16x8*)(lds + PG8_SA(b, h) + aoff + m * 2048 + k * 1024); } while (0)
; #define PG8_LDB(dst, b, h) do { _Pragma("unroll") for (int n = 0; n < 2; ++n) _Pragma("unroll") for (int k = 0; k < 2; ++k) dst[n][k] = *(const PG8_LAS bf16x8*)(lds + PG8_SB(b, h) + boff + n * 2048 + k * 1024); } while (0)
; #define PG8_MMA(ai, bj, At, Bt) do { __builtin_amdgcn_s_setprio(1); _Pragma("unroll") for (int m = 0; m < 4; ++m) _Pragma("unroll") for (int n = 0; n < 2; ++n) _Pragma("unroll") for (int k = 0; k < 2; ++k) \
;         acc[ai][bj][m][n] = __builtin_amdgcn_mfma_f32_16x16x32_bf16(Bt[n][k], At[m][k], acc[ai][bj][m][n], 0, 0, 0); __builtin_amdgcn_s_setprio(0); } while (0)
; #define PG8_WAIT_V(n) asm volatile("s_waitcnt vmcnt(" #n ")" ::: "memory")
; #define PG8_WAIT_L(n) asm volatile("s_waitcnt lgkmcnt(" #n ")" ::: "memory")
; template <class Epi, class Sched>
; __device__ __forceinline__ void gemm_phase(PG8_LAS unsigned char* lds, const Gemm g, const Sched& S, const Epi& E) {
;     ...
;             const bool last = (t == nt - 2);
;             const char* a1 = cA + (size_t)(t + 1) * kstep;
;             const char* a2 = last ? nA : cA + (size_t)(t + 2) * kstep; const char* b2 = last ? nB : cB + (size_t)(t + 2) * kstepB;
;             const char* a3 = a2 + kstep; const char* b3 = b2 + kstepB;
;             if (last && has_next) S.a_ready(nxt);
;             PG8_LDB(B0, 0, 0); PG8_SCHED; PG8_LDA(At, 0, 0); PG8_STAGE(PG8_SA(1, 1), a1 + hstep, voffA);
;             PG8_WAIT_L(8); PG8_BAR; PG8_WAIT_L(0); PG8_MMA(0, 0, At, B0); PG8_BAR; PG8_SCHED;
;             PG8_LDB(B1, 0, 1); PG8_STAGE(PG8_SB(0, 0), b2, voffB);
;             PG8_BAR; PG8_WAIT_L(0); PG8_MMA(0, 1, At, B1); PG8_BAR;
;             PG8_LDA(At, 0, 1); PG8_STAGE(PG8_SA(0, 0), a2, voffA);
;             PG8_BAR; PG8_WAIT_L(0); PG8_MMA(1, 0, At, B0); PG8_BAR; PG8_SCHED;
;             PG8_STAGE(PG8_SB(0, 1), b2 + hstepB, voffB);
;             PG8_WAIT_V(6); PG8_BAR; PG8_MMA(1, 1, At, B1); PG8_BAR;
.Lhalf_skip_y_6:
.LBB0_904:
	ds_read_b128 v[152:155], v149
	ds_read_b128 v[156:159], v149 offset:1024
	ds_read_b128 v[160:163], v149 offset:2048
	ds_read_b128 v[164:167], v149 offset:3072
	s_add_u32 s22, s20, 0xfff80080
	s_addc_u32 s23, s21, -1
	s_cmp_eq_u32 s61, 28
	s_cselect_b32 s25, s11, s23
	s_cselect_b32 s24, s57, s22
	s_cselect_b32 s23, s13, s60
	s_cselect_b32 s22, s58, s59
	v_lshl_add_u64 v[144:145], s[20:21], 0, v[136:137]
	s_add_i32 m0, s19, 0xc000
	ds_read_b128 v[168:171], v150
	ds_read_b128 v[172:175], v150 offset:1024
	ds_read_b128 v[176:179], v150 offset:2048
	ds_read_b128 v[180:183], v150 offset:3072
	ds_read_b128 v[184:187], v150 offset:4096
	ds_read_b128 v[188:191], v150 offset:5120
	ds_read_b128 v[192:195], v150 offset:6144
	ds_read_b128 v[196:199], v150 offset:7168
	global_load_lds_dwordx4 v[144:145], off
	v_lshl_add_u64 v[144:145], s[20:21], 0, v[138:139]
	s_add_i32 m0, s19, 0xe000
	s_nop 0
	global_load_lds_dwordx4 v[144:145], off
	s_add_i32 s62, s53, s38
	v_lshl_add_u64 v[144:145], s[22:23], 0, v[128:129]
	s_mov_b32 m0, s62
	ds_read_b128 v[200:203], v151
	ds_read_b128 v[204:207], v151 offset:1024
	ds_read_b128 v[208:211], v151 offset:2048
	ds_read_b128 v[212:215], v151 offset:3072
	s_waitcnt vmcnt(8)
	s_waitcnt lgkmcnt(0)
	s_barrier
	v_mfma_f32_16x16x32_bf16 v[124:127], v[152:155], v[168:171], v[124:127]
	v_mfma_f32_16x16x32_bf16 v[120:123], v[160:163], v[168:171], v[120:123]
	v_mfma_f32_16x16x32_bf16 v[108:111], v[152:155], v[176:179], v[108:111]
	v_mfma_f32_16x16x32_bf16 v[104:107], v[160:163], v[176:179], v[104:107]
	v_mfma_f32_16x16x32_bf16 v[92:95], v[152:155], v[184:187], v[92:95]
	v_mfma_f32_16x16x32_bf16 v[88:91], v[160:163], v[184:187], v[88:91]
	v_mfma_f32_16x16x32_bf16 v[76:79], v[152:155], v[192:195], v[76:79]
	v_mfma_f32_16x16x32_bf16 v[72:75], v[160:163], v[192:195], v[72:75]
	v_mfma_f32_16x16x32_bf16 v[124:127], v[156:159], v[172:175], v[124:127]
	v_mfma_f32_16x16x32_bf16 v[120:123], v[164:167], v[172:175], v[120:123]
	v_mfma_f32_16x16x32_bf16 v[108:111], v[156:159], v[180:183], v[108:111]
	v_mfma_f32_16x16x32_bf16 v[104:107], v[164:167], v[180:183], v[104:107]
	v_mfma_f32_16x16x32_bf16 v[92:95], v[156:159], v[188:191], v[92:95]
	v_mfma_f32_16x16x32_bf16 v[88:91], v[164:167], v[188:191], v[88:91]
	v_mfma_f32_16x16x32_bf16 v[76:79], v[156:159], v[196:199], v[76:79]
	v_mfma_f32_16x16x32_bf16 v[72:75], v[164:167], v[196:199], v[72:75]
	v_mfma_f32_16x16x32_bf16 v[116:119], v[200:203], v[168:171], v[116:119]
	v_mfma_f32_16x16x32_bf16 v[112:115], v[208:211], v[168:171], v[112:115]
	v_mfma_f32_16x16x32_bf16 v[100:103], v[200:203], v[176:179], v[100:103]
	v_mfma_f32_16x16x32_bf16 v[96:99], v[208:211], v[176:179], v[96:99]
	v_mfma_f32_16x16x32_bf16 v[84:87], v[200:203], v[184:187], v[84:87]
	v_mfma_f32_16x16x32_bf16 v[80:83], v[208:211], v[184:187], v[80:83]
	v_mfma_f32_16x16x32_bf16 v[68:71], v[200:203], v[192:195], v[68:71]
	v_mfma_f32_16x16x32_bf16 v[64:67], v[208:211], v[192:195], v[64:67]
	v_mfma_f32_16x16x32_bf16 v[116:119], v[204:207], v[172:175], v[116:119]
	v_mfma_f32_16x16x32_bf16 v[112:115], v[212:215], v[172:175], v[112:115]
	v_mfma_f32_16x16x32_bf16 v[100:103], v[204:207], v[180:183], v[100:103]
	v_mfma_f32_16x16x32_bf16 v[96:99], v[212:215], v[180:183], v[96:99]
	v_mfma_f32_16x16x32_bf16 v[84:87], v[204:207], v[188:191], v[84:87]
	v_mfma_f32_16x16x32_bf16 v[80:83], v[212:215], v[188:191], v[80:83]
	v_mfma_f32_16x16x32_bf16 v[68:71], v[204:207], v[196:199], v[68:71]
	v_mfma_f32_16x16x32_bf16 v[64:67], v[212:215], v[196:199], v[64:67]
	s_barrier
	global_load_lds_dwordx4 v[144:145], off
	v_lshl_add_u64 v[144:145], s[22:23], 0, v[130:131]
	s_add_i32 m0, s62, 0x2000
	s_nop 0
	global_load_lds_dwordx4 v[144:145], off
	s_mov_b32 m0, s19
	v_lshl_add_u64 v[144:145], s[24:25], 0, v[134:135]
	ds_read_b128 v[168:171], v150 offset:16384
	ds_read_b128 v[172:175], v150 offset:17408
	ds_read_b128 v[176:179], v150 offset:18432
	ds_read_b128 v[180:183], v150 offset:19456
	ds_read_b128 v[184:187], v150 offset:20480
	ds_read_b128 v[188:191], v150 offset:21504
	ds_read_b128 v[192:195], v150 offset:22528
	ds_read_b128 v[196:199], v150 offset:23552
	global_load_lds_dwordx4 v[144:145], off
	v_lshl_add_u64 v[216:217], s[24:25], 0, v[132:133]
	s_mov_b32 m0, s46
	s_nop 0
	global_load_lds_dwordx4 v[216:217], off
	s_add_u32 s62, s22, 0x4000
	s_addc_u32 s63, s23, 0
	s_add_i32 s64, s54, s38
	v_lshl_add_u64 v[250:251], s[62:63], 0, v[128:129]
	s_mov_b32 m0, s64
	s_nop 0
	global_load_lds_dwordx4 v[250:251], off
	v_lshl_add_u64 v[250:251], s[62:63], 0, v[130:131]
	s_add_i32 m0, s64, 0x2000
	s_nop 0
	global_load_lds_dwordx4 v[250:251], off
	s_waitcnt vmcnt(8)
	s_waitcnt lgkmcnt(0)
	s_barrier
; #define PG8_STAGE(bufoff, gbase, voff) do { _Pragma("unroll") for (int _i = 0; _i < 2; ++_i) \
;         __builtin_amdgcn_global_load_lds((const unsigned*)((const char*)(gbase) + (voff)[_i]), (PG8_LAS unsigned*)(lds + (bufoff) + ldsw + _i * 8192), 16, 0, 0); } while (0)
; #define PG8_LDA(dst, b, h) do { _Pragma("unroll") for (int m = 0; m < 4; ++m) _Pragma("unroll") for (int k = 0; k < 2; ++k) dst[m][k] = *(const PG8_LAS bf16x8*)(lds + PG8_SA(b, h) + aoff + m * 2048 + k * 1024); } while (0)
; #define PG8_LDB(dst, b, h) do { _Pragma("unroll") for (int n = 0; n < 2; ++n) _Pragma("unroll") for (int k = 0; k < 2; ++k) dst[n][k] = *(const PG8_LAS bf16x8*)(lds + PG8_SB(b, h) + boff + n * 2048 + k * 1024); } while (0)
; #define PG8_MMA(ai, bj, At, Bt) do { __builtin_amdgcn_s_setprio(1); _Pragma("unroll") for (int m = 0; m < 4; ++m) _Pragma("unroll") for (int n = 0; n < 2; ++n) _Pragma("unroll") for (int k = 0; k < 2; ++k) \
;         acc[ai][bj][m][n] = __builtin_amdgcn_mfma_f32_16x16x32_bf16(Bt[n][k], At[m][k], acc[ai][bj][m][n], 0, 0, 0); __builtin_amdgcn_s_setprio(0); } while (0)
; #define PG8_WAIT_V(n) asm volatile("s_waitcnt vmcnt(" #n ")" ::: "memory")
; #define PG8_WAIT_L(n) asm volatile("s_waitcnt lgkmcnt(" #n ")" ::: "memory")
; #define PG8_BAR __builtin_amdgcn_s_barrier()
; #define PG8_SCHED __builtin_amdgcn_sched_barrier(0)
; template <class Epi, class Sched>
; __device__ __forceinline__ void gemm_phase(PG8_LAS unsigned char* lds, const Gemm g, const Sched& S, const Epi& E) {
;     ...
;             PG8_BAR; PG8_WAIT_L(0); PG8_MMA(1, 0, At, B0); PG8_BAR; PG8_SCHED;
;             PG8_STAGE(PG8_SB(0, 1), b2 + hstepB, voffB);
;             PG8_WAIT_V(6); PG8_BAR; PG8_MMA(1, 1, At, B1); PG8_BAR;
;             PG8_LDB(B0, 1, 0); PG8_SCHED; PG8_LDA(At, 1, 0); PG8_STAGE(PG8_SA(0, 1), a2 + hstep, voffA);
;             PG8_WAIT_L(8); PG8_BAR; PG8_WAIT_L(0); PG8_MMA(0, 0, At, B0); PG8_BAR; PG8_SCHED;
;             PG8_LDB(B1, 1, 1); PG8_STAGE(PG8_SB(1, 0), b3, voffB);
;             PG8_BAR; PG8_WAIT_L(0); PG8_MMA(0, 1, At, B1); PG8_BAR;
;             PG8_LDA(At, 1, 1); PG8_STAGE(PG8_SA(1, 0), a3, voffA);
;             PG8_BAR; PG8_WAIT_L(0); PG8_MMA(1, 0, At, B0); PG8_BAR; PG8_SCHED;
	v_mfma_f32_16x16x32_bf16 v[60:63], v[152:155], v[168:171], v[60:63]
	v_mfma_f32_16x16x32_bf16 v[56:59], v[160:163], v[168:171], v[56:59]
	v_mfma_f32_16x16x32_bf16 v[44:47], v[152:155], v[176:179], v[44:47]
	v_mfma_f32_16x16x32_bf16 v[40:43], v[160:163], v[176:179], v[40:43]
	v_mfma_f32_16x16x32_bf16 v[28:31], v[152:155], v[184:187], v[28:31]
	v_mfma_f32_16x16x32_bf16 v[24:27], v[160:163], v[184:187], v[24:27]
	v_mfma_f32_16x16x32_bf16 v[12:15], v[152:155], v[192:195], v[12:15]
	v_mfma_f32_16x16x32_bf16 v[8:11], v[160:163], v[192:195], v[8:11]
	v_mfma_f32_16x16x32_bf16 v[60:63], v[156:159], v[172:175], v[60:63]
	v_mfma_f32_16x16x32_bf16 v[56:59], v[164:167], v[172:175], v[56:59]
	v_mfma_f32_16x16x32_bf16 v[44:47], v[156:159], v[180:183], v[44:47]
	v_mfma_f32_16x16x32_bf16 v[40:43], v[164:167], v[180:183], v[40:43]
	v_mfma_f32_16x16x32_bf16 v[28:31], v[156:159], v[188:191], v[28:31]
	v_mfma_f32_16x16x32_bf16 v[24:27], v[164:167], v[188:191], v[24:27]
	v_mfma_f32_16x16x32_bf16 v[12:15], v[156:159], v[196:199], v[12:15]
	v_mfma_f32_16x16x32_bf16 v[8:11], v[164:167], v[196:199], v[8:11]
	v_mfma_f32_16x16x32_bf16 v[52:55], v[200:203], v[168:171], v[52:55]
	v_mfma_f32_16x16x32_bf16 v[48:51], v[208:211], v[168:171], v[48:51]
	v_mfma_f32_16x16x32_bf16 v[36:39], v[200:203], v[176:179], v[36:39]
	v_mfma_f32_16x16x32_bf16 v[32:35], v[208:211], v[176:179], v[32:35]
	v_mfma_f32_16x16x32_bf16 v[20:23], v[200:203], v[184:187], v[20:23]
	v_mfma_f32_16x16x32_bf16 v[16:19], v[208:211], v[184:187], v[16:19]
	v_mfma_f32_16x16x32_bf16 v[4:7], v[200:203], v[192:195], v[4:7]
	v_mfma_f32_16x16x32_bf16 v[0:3], v[208:211], v[192:195], v[0:3]
	v_mfma_f32_16x16x32_bf16 v[52:55], v[204:207], v[172:175], v[52:55]
	v_mfma_f32_16x16x32_bf16 v[48:51], v[212:215], v[172:175], v[48:51]
	v_mfma_f32_16x16x32_bf16 v[36:39], v[204:207], v[180:183], v[36:39]
	v_mfma_f32_16x16x32_bf16 v[32:35], v[212:215], v[180:183], v[32:35]
	v_mfma_f32_16x16x32_bf16 v[20:23], v[204:207], v[188:191], v[20:23]
	v_mfma_f32_16x16x32_bf16 v[16:19], v[212:215], v[188:191], v[16:19]
	v_mfma_f32_16x16x32_bf16 v[4:7], v[204:207], v[196:199], v[4:7]
	v_mfma_f32_16x16x32_bf16 v[0:3], v[212:215], v[196:199], v[0:3]
	s_barrier
	s_add_i32 s62, 0, 0x18000
	v_add_u32_e32 v164, s62, v147
	ds_read_b128 v[152:155], v164
	ds_read_b128 v[156:159], v164 offset:1024
	ds_read_b128 v[160:163], v164 offset:2048
	ds_read_b128 v[164:167], v164 offset:3072
	s_add_u32 s24, s24, 0x80000
	s_addc_u32 s25, s25, 0
	s_mov_b32 m0, s47
	v_lshl_add_u64 v[200:201], s[24:25], 0, v[134:135]
	ds_read_b128 v[168:171], v150 offset:32768
	ds_read_b128 v[172:175], v150 offset:33792
	ds_read_b128 v[176:179], v150 offset:34816
	ds_read_b128 v[180:183], v150 offset:35840
	ds_read_b128 v[184:187], v150 offset:36864
	ds_read_b128 v[188:191], v150 offset:37888
	ds_read_b128 v[192:195], v150 offset:38912
	ds_read_b128 v[196:199], v150 offset:39936
	global_load_lds_dwordx4 v[200:201], off
	v_lshl_add_u64 v[200:201], s[24:25], 0, v[132:133]
	s_mov_b32 m0, s48
	s_nop 0
	global_load_lds_dwordx4 v[200:201], off
	s_add_i32 s63, 0, 0x1c000
	s_add_u32 s24, s22, 0x8000
	s_addc_u32 s25, s23, 0
	s_add_i32 s62, s62, s38
	v_add_u32_e32 v212, s63, v147
	v_lshl_add_u64 v[218:219], s[24:25], 0, v[128:129]
	s_mov_b32 m0, s62
	ds_read_b128 v[200:203], v212
	ds_read_b128 v[204:207], v212 offset:1024
	ds_read_b128 v[208:211], v212 offset:2048
	ds_read_b128 v[212:215], v212 offset:3072
	s_waitcnt vmcnt(8)
	s_waitcnt lgkmcnt(0)
	s_barrier
	v_mfma_f32_16x16x32_bf16 v[124:127], v[152:155], v[168:171], v[124:127]
	v_mfma_f32_16x16x32_bf16 v[120:123], v[160:163], v[168:171], v[120:123]
	v_mfma_f32_16x16x32_bf16 v[108:111], v[152:155], v[176:179], v[108:111]
	v_mfma_f32_16x16x32_bf16 v[104:107], v[160:163], v[176:179], v[104:107]
	v_mfma_f32_16x16x32_bf16 v[92:95], v[152:155], v[184:187], v[92:95]
	v_mfma_f32_16x16x32_bf16 v[88:91], v[160:163], v[184:187], v[88:91]
	v_mfma_f32_16x16x32_bf16 v[76:79], v[152:155], v[192:195], v[76:79]
	v_mfma_f32_16x16x32_bf16 v[72:75], v[160:163], v[192:195], v[72:75]
	v_mfma_f32_16x16x32_bf16 v[124:127], v[156:159], v[172:175], v[124:127]
	v_mfma_f32_16x16x32_bf16 v[120:123], v[164:167], v[172:175], v[120:123]
	v_mfma_f32_16x16x32_bf16 v[108:111], v[156:159], v[180:183], v[108:111]
	v_mfma_f32_16x16x32_bf16 v[104:107], v[164:167], v[180:183], v[104:107]
	v_mfma_f32_16x16x32_bf16 v[92:95], v[156:159], v[188:191], v[92:95]
	v_mfma_f32_16x16x32_bf16 v[88:91], v[164:167], v[188:191], v[88:91]
	v_mfma_f32_16x16x32_bf16 v[76:79], v[156:159], v[196:199], v[76:79]
	v_mfma_f32_16x16x32_bf16 v[72:75], v[164:167], v[196:199], v[72:75]
	v_mfma_f32_16x16x32_bf16 v[116:119], v[200:203], v[168:171], v[116:119]
	v_mfma_f32_16x16x32_bf16 v[112:115], v[208:211], v[168:171], v[112:115]
	v_mfma_f32_16x16x32_bf16 v[100:103], v[200:203], v[176:179], v[100:103]
	v_mfma_f32_16x16x32_bf16 v[96:99], v[208:211], v[176:179], v[96:99]
	v_mfma_f32_16x16x32_bf16 v[84:87], v[200:203], v[184:187], v[84:87]
	v_mfma_f32_16x16x32_bf16 v[80:83], v[208:211], v[184:187], v[80:83]
	v_mfma_f32_16x16x32_bf16 v[68:71], v[200:203], v[192:195], v[68:71]
	v_mfma_f32_16x16x32_bf16 v[64:67], v[208:211], v[192:195], v[64:67]
	v_mfma_f32_16x16x32_bf16 v[116:119], v[204:207], v[172:175], v[116:119]
	v_mfma_f32_16x16x32_bf16 v[112:115], v[212:215], v[172:175], v[112:115]
	v_mfma_f32_16x16x32_bf16 v[100:103], v[204:207], v[180:183], v[100:103]
	v_mfma_f32_16x16x32_bf16 v[96:99], v[212:215], v[180:183], v[96:99]
	v_mfma_f32_16x16x32_bf16 v[84:87], v[204:207], v[188:191], v[84:87]
	v_mfma_f32_16x16x32_bf16 v[80:83], v[212:215], v[188:191], v[80:83]
	v_mfma_f32_16x16x32_bf16 v[68:71], v[204:207], v[196:199], v[68:71]
	v_mfma_f32_16x16x32_bf16 v[64:67], v[212:215], v[196:199], v[64:67]
	s_barrier
; #define PG8_STAGE(bufoff, gbase, voff) do { _Pragma("unroll") for (int _i = 0; _i < 2; ++_i) \
;         __builtin_amdgcn_global_load_lds((const unsigned*)((const char*)(gbase) + (voff)[_i]), (PG8_LAS unsigned*)(lds + (bufoff) + ldsw + _i * 8192), 16, 0, 0); } while (0)
; #define PG8_LDA(dst, b, h) do { _Pragma("unroll") for (int m = 0; m < 4; ++m) _Pragma("unroll") for (int k = 0; k < 2; ++k) dst[m][k] = *(const PG8_LAS bf16x8*)(lds + PG8_SA(b, h) + aoff + m * 2048 + k * 1024); } while (0)
; #define PG8_MMA(ai, bj, At, Bt) do { __builtin_amdgcn_s_setprio(1); _Pragma("unroll") for (int m = 0; m < 4; ++m) _Pragma("unroll") for (int n = 0; n < 2; ++n) _Pragma("unroll") for (int k = 0; k < 2; ++k) \
;         acc[ai][bj][m][n] = __builtin_amdgcn_mfma_f32_16x16x32_bf16(Bt[n][k], At[m][k], acc[ai][bj][m][n], 0, 0, 0); __builtin_amdgcn_s_setprio(0); } while (0)
; #define PG8_WAIT_V(n) asm volatile("s_waitcnt vmcnt(" #n ")" ::: "memory")
; #define PG8_WAIT_L(n) asm volatile("s_waitcnt lgkmcnt(" #n ")" ::: "memory")
; #define PG8_BAR __builtin_amdgcn_s_barrier()
; #define PG8_SCHED __builtin_amdgcn_sched_barrier(0)
; template <class Epi, class Sched>
; __device__ __forceinline__ void gemm_phase(PG8_LAS unsigned char* lds, const Gemm g, const Sched& S, const Epi& E) {
;     ...
;             PG8_LDA(At, 1, 1); PG8_STAGE(PG8_SA(1, 0), a3, voffA);
;             PG8_BAR; PG8_WAIT_L(0); PG8_MMA(1, 0, At, B0); PG8_BAR; PG8_SCHED;
;             PG8_STAGE(PG8_SB(1, 1), b3 + hstepB, voffB);
;             PG8_WAIT_V(6); PG8_BAR; PG8_MMA(1, 1, At, B1); PG8_BAR;
;     ...
;     PG8_WAIT_V(0);
;     if (wr == 0) PG8_BAR;
;     PG8_BAR;
	global_load_lds_dwordx4 v[218:219], off
	v_lshl_add_u64 v[218:219], s[24:25], 0, v[130:131]
	s_add_i32 m0, s62, 0x2000
	s_nop 0
	global_load_lds_dwordx4 v[218:219], off
	s_mov_b32 m0, s50
	v_lshl_add_u64 v[144:145], v[144:145], 0, s[8:9]
	ds_read_b128 v[168:171], v150 offset:49152
	ds_read_b128 v[172:175], v150 offset:50176
	ds_read_b128 v[176:179], v150 offset:51200
	ds_read_b128 v[180:183], v150 offset:52224
	ds_read_b128 v[184:187], v150 offset:53248
	ds_read_b128 v[188:191], v150 offset:54272
	ds_read_b128 v[192:195], v150 offset:55296
	ds_read_b128 v[196:199], v150 offset:56320
	global_load_lds_dwordx4 v[144:145], off
	v_lshl_add_u64 v[144:145], v[216:217], 0, s[8:9]
	s_mov_b32 m0, s51
	s_nop 0
	global_load_lds_dwordx4 v[144:145], off
	s_add_u32 s22, s22, 0xc000
	s_addc_u32 s23, s23, 0
	s_add_i32 s24, s63, s38
	v_lshl_add_u64 v[144:145], s[22:23], 0, v[128:129]
	s_mov_b32 m0, s24
	s_nop 0
	global_load_lds_dwordx4 v[144:145], off
	v_lshl_add_u64 v[144:145], s[22:23], 0, v[130:131]
	s_add_i32 m0, s24, 0x2000
	s_nop 0
	global_load_lds_dwordx4 v[144:145], off
	s_add_i32 s61, s61, 2
	s_add_u32 s59, s59, 0x10000
	s_addc_u32 s60, s60, 0
	s_add_u32 s20, s20, 0x100
	s_addc_u32 s21, s21, 0
	s_cmp_gt_u32 s61, 29
	s_waitcnt vmcnt(8)
	s_waitcnt lgkmcnt(0)
	s_barrier
	v_mfma_f32_16x16x32_bf16 v[60:63], v[152:155], v[168:171], v[60:63]
	v_mfma_f32_16x16x32_bf16 v[56:59], v[160:163], v[168:171], v[56:59]
	v_mfma_f32_16x16x32_bf16 v[44:47], v[152:155], v[176:179], v[44:47]
	v_mfma_f32_16x16x32_bf16 v[40:43], v[160:163], v[176:179], v[40:43]
	v_mfma_f32_16x16x32_bf16 v[28:31], v[152:155], v[184:187], v[28:31]
	v_mfma_f32_16x16x32_bf16 v[24:27], v[160:163], v[184:187], v[24:27]
	v_mfma_f32_16x16x32_bf16 v[12:15], v[152:155], v[192:195], v[12:15]
	v_mfma_f32_16x16x32_bf16 v[8:11], v[160:163], v[192:195], v[8:11]
	v_mfma_f32_16x16x32_bf16 v[60:63], v[156:159], v[172:175], v[60:63]
	v_mfma_f32_16x16x32_bf16 v[56:59], v[164:167], v[172:175], v[56:59]
	v_mfma_f32_16x16x32_bf16 v[44:47], v[156:159], v[180:183], v[44:47]
	v_mfma_f32_16x16x32_bf16 v[40:43], v[164:167], v[180:183], v[40:43]
	v_mfma_f32_16x16x32_bf16 v[28:31], v[156:159], v[188:191], v[28:31]
	v_mfma_f32_16x16x32_bf16 v[24:27], v[164:167], v[188:191], v[24:27]
	v_mfma_f32_16x16x32_bf16 v[12:15], v[156:159], v[196:199], v[12:15]
	v_mfma_f32_16x16x32_bf16 v[8:11], v[164:167], v[196:199], v[8:11]
	v_mfma_f32_16x16x32_bf16 v[52:55], v[200:203], v[168:171], v[52:55]
	v_mfma_f32_16x16x32_bf16 v[48:51], v[208:211], v[168:171], v[48:51]
	v_mfma_f32_16x16x32_bf16 v[36:39], v[200:203], v[176:179], v[36:39]
	v_mfma_f32_16x16x32_bf16 v[32:35], v[208:211], v[176:179], v[32:35]
	v_mfma_f32_16x16x32_bf16 v[20:23], v[200:203], v[184:187], v[20:23]
	v_mfma_f32_16x16x32_bf16 v[16:19], v[208:211], v[184:187], v[16:19]
	v_mfma_f32_16x16x32_bf16 v[4:7], v[200:203], v[192:195], v[4:7]
	v_mfma_f32_16x16x32_bf16 v[0:3], v[208:211], v[192:195], v[0:3]
	v_mfma_f32_16x16x32_bf16 v[52:55], v[204:207], v[172:175], v[52:55]
	v_mfma_f32_16x16x32_bf16 v[48:51], v[212:215], v[172:175], v[48:51]
	v_mfma_f32_16x16x32_bf16 v[36:39], v[204:207], v[180:183], v[36:39]
	v_mfma_f32_16x16x32_bf16 v[32:35], v[212:215], v[180:183], v[32:35]
	v_mfma_f32_16x16x32_bf16 v[20:23], v[204:207], v[188:191], v[20:23]
	v_mfma_f32_16x16x32_bf16 v[16:19], v[212:215], v[188:191], v[16:19]
	v_mfma_f32_16x16x32_bf16 v[4:7], v[204:207], v[196:199], v[4:7]
	v_mfma_f32_16x16x32_bf16 v[0:3], v[212:215], v[196:199], v[0:3]
	s_barrier
	s_cbranch_scc0 .LBB0_904
	s_cmp_eq_u32 s78, 0
	s_cbranch_scc0 .Lhalf_skip_x_6
	s_barrier

; #define PG8_STAGE(bufoff, gbase, voff) do { _Pragma("unroll") for (int _i = 0; _i < 2; ++_i) \
;         __builtin_amdgcn_global_load_lds((const unsigned*)((const char*)(gbase) + (voff)[_i]), (PG8_LAS unsigned*)(lds + (bufoff) + ldsw + _i * 8192), 16, 0, 0); } while (0)
; #define PG8_LDA(dst, b, h) do { _Pragma("unroll") for (int m = 0; m < 4; ++m) _Pragma("unroll") for (int k = 0; k < 2; ++k) dst[m][k] = *(const PG8_LAS bf16x8*)(lds + PG8_SA(b, h) + aoff + m * 2048 + k * 1024); } while (0)
; #define PG8_LDB(dst, b, h) do { _Pragma("unroll") for (int n = 0; n < 2; ++n) _Pragma("unroll") for (int k = 0; k < 2; ++k) dst[n][k] = *(const PG8_LAS bf16x8*)(lds + PG8_SB(b, h) + boff + n * 2048 + k * 1024); } while (0)
; #define PG8_MMA(ai, bj, At, Bt) do { __builtin_amdgcn_s_setprio(1); _Pragma("unroll") for (int m = 0; m < 4; ++m) _Pragma("unroll") for (int n = 0; n < 2; ++n) _Pragma("unroll") for (int k = 0; k < 2; ++k) \
;         acc[ai][bj][m][n] = __builtin_amdgcn_mfma_f32_16x16x32_bf16(Bt[n][k], At[m][k], acc[ai][bj][m][n], 0, 0, 0); __builtin_amdgcn_s_setprio(0); } while (0)
; #define PG8_WAIT_V(n) asm volatile("s_waitcnt vmcnt(" #n ")" ::: "memory")
; #define PG8_WAIT_L(n) asm volatile("s_waitcnt lgkmcnt(" #n ")" ::: "memory")
; template <class Epi, class Sched>
; __device__ __forceinline__ void gemm_phase(PG8_LAS unsigned char* lds, const Gemm g, const Sched& S, const Epi& E) {
;     ...
;             const bool last = (t == nt - 2);
;             const char* a1 = cA + (size_t)(t + 1) * kstep;
;             const char* a2 = last ? nA : cA + (size_t)(t + 2) * kstep; const char* b2 = last ? nB : cB + (size_t)(t + 2) * kstepB;
;             const char* a3 = a2 + kstep; const char* b3 = b2 + kstepB;
;             if (last && has_next) S.a_ready(nxt);
;             PG8_LDB(B0, 0, 0); PG8_SCHED; PG8_LDA(At, 0, 0); PG8_STAGE(PG8_SA(1, 1), a1 + hstep, voffA);
;             PG8_WAIT_L(8); PG8_BAR; PG8_WAIT_L(0); PG8_MMA(0, 0, At, B0); PG8_BAR; PG8_SCHED;
;             PG8_LDB(B1, 0, 1); PG8_STAGE(PG8_SB(0, 0), b2, voffB);
;             PG8_BAR; PG8_WAIT_L(0); PG8_MMA(0, 1, At, B1); PG8_BAR;
;             PG8_LDA(At, 0, 1); PG8_STAGE(PG8_SA(0, 0), a2, voffA);
;             PG8_BAR; PG8_WAIT_L(0); PG8_MMA(1, 0, At, B0); PG8_BAR; PG8_SCHED;
;             PG8_STAGE(PG8_SB(0, 1), b2 + hstepB, voffB);
;             PG8_WAIT_V(6); PG8_BAR; PG8_MMA(1, 1, At, B1); PG8_BAR;
.Lhalf_skip_y_7:
.LBB0_980:
	ds_read_b128 v[128:131], v197
	ds_read_b128 v[132:135], v197 offset:1024
	ds_read_b128 v[136:139], v197 offset:2048
	ds_read_b128 v[140:143], v197 offset:3072
	s_add_u32 s24, s22, 0x100
	s_addc_u32 s25, s23, 0
	s_cmpk_eq_i32 s65, 0x52
	s_cselect_b32 s29, s7, s25
	s_cselect_b32 s28, s6, s24
	s_cselect_b32 s27, s9, s64
	s_cselect_b32 s26, s8, s63
	v_lshl_add_u64 v[192:193], s[22:23], 0, v[172:173]
	s_add_i32 m0, s49, 0xc000
	ds_read_b128 v[144:147], v198
	ds_read_b128 v[148:151], v198 offset:1024
	ds_read_b128 v[152:155], v198 offset:2048
	ds_read_b128 v[156:159], v198 offset:3072
	ds_read_b128 v[160:163], v198 offset:4096
	ds_read_b128 v[180:183], v198 offset:5120
	ds_read_b128 v[184:187], v198 offset:6144
	ds_read_b128 v[188:191], v198 offset:7168
	global_load_lds_dwordx4 v[192:193], off
	v_lshl_add_u64 v[192:193], s[22:23], 0, v[174:175]
	s_add_i32 m0, s49, 0xe000
	s_nop 0
	global_load_lds_dwordx4 v[192:193], off
	s_add_i32 s22, s57, s48
	v_lshl_add_u64 v[192:193], s[26:27], 0, v[164:165]
	s_mov_b32 m0, s22
	ds_read_b128 v[200:203], v199
	ds_read_b128 v[204:207], v199 offset:1024
	ds_read_b128 v[208:211], v199 offset:2048
	ds_read_b128 v[212:215], v199 offset:3072
	s_waitcnt vmcnt(8)
	s_waitcnt lgkmcnt(0)
	s_barrier
	v_mfma_f32_16x16x32_bf16 v[124:127], v[128:131], v[144:147], v[124:127]
	v_mfma_f32_16x16x32_bf16 v[120:123], v[136:139], v[144:147], v[120:123]
	v_mfma_f32_16x16x32_bf16 v[116:119], v[128:131], v[152:155], v[116:119]
	v_mfma_f32_16x16x32_bf16 v[104:107], v[136:139], v[152:155], v[104:107]
	v_mfma_f32_16x16x32_bf16 v[92:95], v[128:131], v[160:163], v[92:95]
	v_mfma_f32_16x16x32_bf16 v[88:91], v[136:139], v[160:163], v[88:91]
	v_mfma_f32_16x16x32_bf16 v[76:79], v[128:131], v[184:187], v[76:79]
	v_mfma_f32_16x16x32_bf16 v[72:75], v[136:139], v[184:187], v[72:75]
	v_mfma_f32_16x16x32_bf16 v[124:127], v[132:135], v[148:151], v[124:127]
	v_mfma_f32_16x16x32_bf16 v[120:123], v[140:143], v[148:151], v[120:123]
	v_mfma_f32_16x16x32_bf16 v[116:119], v[132:135], v[156:159], v[116:119]
	v_mfma_f32_16x16x32_bf16 v[104:107], v[140:143], v[156:159], v[104:107]
	v_mfma_f32_16x16x32_bf16 v[92:95], v[132:135], v[180:183], v[92:95]
	v_mfma_f32_16x16x32_bf16 v[88:91], v[140:143], v[180:183], v[88:91]
	v_mfma_f32_16x16x32_bf16 v[76:79], v[132:135], v[188:191], v[76:79]
	v_mfma_f32_16x16x32_bf16 v[72:75], v[140:143], v[188:191], v[72:75]
	v_mfma_f32_16x16x32_bf16 v[112:115], v[200:203], v[144:147], v[112:115]
	v_mfma_f32_16x16x32_bf16 v[108:111], v[208:211], v[144:147], v[108:111]
	v_mfma_f32_16x16x32_bf16 v[100:103], v[200:203], v[152:155], v[100:103]
	v_mfma_f32_16x16x32_bf16 v[96:99], v[208:211], v[152:155], v[96:99]
	v_mfma_f32_16x16x32_bf16 v[84:87], v[200:203], v[160:163], v[84:87]
	v_mfma_f32_16x16x32_bf16 v[80:83], v[208:211], v[160:163], v[80:83]
	v_mfma_f32_16x16x32_bf16 v[68:71], v[200:203], v[184:187], v[68:71]
	v_mfma_f32_16x16x32_bf16 v[64:67], v[208:211], v[184:187], v[64:67]
	v_mfma_f32_16x16x32_bf16 v[112:115], v[204:207], v[148:151], v[112:115]
	v_mfma_f32_16x16x32_bf16 v[108:111], v[212:215], v[148:151], v[108:111]
	v_mfma_f32_16x16x32_bf16 v[100:103], v[204:207], v[156:159], v[100:103]
	v_mfma_f32_16x16x32_bf16 v[96:99], v[212:215], v[156:159], v[96:99]
	v_mfma_f32_16x16x32_bf16 v[84:87], v[204:207], v[180:183], v[84:87]
	v_mfma_f32_16x16x32_bf16 v[80:83], v[212:215], v[180:183], v[80:83]
	v_mfma_f32_16x16x32_bf16 v[68:71], v[204:207], v[188:191], v[68:71]
	v_mfma_f32_16x16x32_bf16 v[64:67], v[212:215], v[188:191], v[64:67]
	s_barrier
	global_load_lds_dwordx4 v[192:193], off
	v_lshl_add_u64 v[192:193], s[26:27], 0, v[168:169]
	s_add_i32 m0, s22, 0x2000
	s_nop 0
	global_load_lds_dwordx4 v[192:193], off
	s_mov_b32 m0, s49
	v_lshl_add_u64 v[192:193], s[28:29], 0, v[166:167]
	ds_read_b128 v[144:147], v198 offset:16384
	ds_read_b128 v[148:151], v198 offset:17408
	ds_read_b128 v[152:155], v198 offset:18432
	ds_read_b128 v[156:159], v198 offset:19456
	ds_read_b128 v[160:163], v198 offset:20480
	ds_read_b128 v[180:183], v198 offset:21504
	ds_read_b128 v[184:187], v198 offset:22528
	ds_read_b128 v[188:191], v198 offset:23552
	global_load_lds_dwordx4 v[192:193], off
	v_lshl_add_u64 v[216:217], s[28:29], 0, v[170:171]
	s_mov_b32 m0, s50
	s_nop 0
	global_load_lds_dwordx4 v[216:217], off
	s_add_u32 s22, s26, 0x4000
	s_addc_u32 s23, s27, 0
	s_add_i32 s66, s58, s48
	v_lshl_add_u64 v[250:251], s[22:23], 0, v[164:165]
	s_mov_b32 m0, s66
	s_nop 0
	global_load_lds_dwordx4 v[250:251], off
	v_lshl_add_u64 v[250:251], s[22:23], 0, v[168:169]
	s_add_i32 m0, s66, 0x2000
	s_nop 0
	global_load_lds_dwordx4 v[250:251], off
	s_waitcnt vmcnt(8)
	s_waitcnt lgkmcnt(0)
	s_barrier
; #define PG8_STAGE(bufoff, gbase, voff) do { _Pragma("unroll") for (int _i = 0; _i < 2; ++_i) \
;         __builtin_amdgcn_global_load_lds((const unsigned*)((const char*)(gbase) + (voff)[_i]), (PG8_LAS unsigned*)(lds + (bufoff) + ldsw + _i * 8192), 16, 0, 0); } while (0)
; #define PG8_LDA(dst, b, h) do { _Pragma("unroll") for (int m = 0; m < 4; ++m) _Pragma("unroll") for (int k = 0; k < 2; ++k) dst[m][k] = *(const PG8_LAS bf16x8*)(lds + PG8_SA(b, h) + aoff + m * 2048 + k * 1024); } while (0)
; #define PG8_LDB(dst, b, h) do { _Pragma("unroll") for (int n = 0; n < 2; ++n) _Pragma("unroll") for (int k = 0; k < 2; ++k) dst[n][k] = *(const PG8_LAS bf16x8*)(lds + PG8_SB(b, h) + boff + n * 2048 + k * 1024); } while (0)
; #define PG8_MMA(ai, bj, At, Bt) do { __builtin_amdgcn_s_setprio(1); _Pragma("unroll") for (int m = 0; m < 4; ++m) _Pragma("unroll") for (int n = 0; n < 2; ++n) _Pragma("unroll") for (int k = 0; k < 2; ++k) \
;         acc[ai][bj][m][n] = __builtin_amdgcn_mfma_f32_16x16x32_bf16(Bt[n][k], At[m][k], acc[ai][bj][m][n], 0, 0, 0); __builtin_amdgcn_s_setprio(0); } while (0)
; #define PG8_WAIT_V(n) asm volatile("s_waitcnt vmcnt(" #n ")" ::: "memory")
; #define PG8_WAIT_L(n) asm volatile("s_waitcnt lgkmcnt(" #n ")" ::: "memory")
; #define PG8_BAR __builtin_amdgcn_s_barrier()
; #define PG8_SCHED __builtin_amdgcn_sched_barrier(0)
; template <class Epi, class Sched>
; __device__ __forceinline__ void gemm_phase(PG8_LAS unsigned char* lds, const Gemm g, const Sched& S, const Epi& E) {
;     ...
;             PG8_BAR; PG8_WAIT_L(0); PG8_MMA(1, 0, At, B0); PG8_BAR; PG8_SCHED;
;             PG8_STAGE(PG8_SB(0, 1), b2 + hstepB, voffB);
;             PG8_WAIT_V(6); PG8_BAR; PG8_MMA(1, 1, At, B1); PG8_BAR;
;             PG8_LDB(B0, 1, 0); PG8_SCHED; PG8_LDA(At, 1, 0); PG8_STAGE(PG8_SA(0, 1), a2 + hstep, voffA);
;             PG8_WAIT_L(8); PG8_BAR; PG8_WAIT_L(0); PG8_MMA(0, 0, At, B0); PG8_BAR; PG8_SCHED;
;             PG8_LDB(B1, 1, 1); PG8_STAGE(PG8_SB(1, 0), b3, voffB);
;             PG8_BAR; PG8_WAIT_L(0); PG8_MMA(0, 1, At, B1); PG8_BAR;
;             PG8_LDA(At, 1, 1); PG8_STAGE(PG8_SA(1, 0), a3, voffA);
;             PG8_BAR; PG8_WAIT_L(0); PG8_MMA(1, 0, At, B0); PG8_BAR; PG8_SCHED;
	v_mfma_f32_16x16x32_bf16 v[60:63], v[128:131], v[144:147], v[60:63]
	v_mfma_f32_16x16x32_bf16 v[56:59], v[136:139], v[144:147], v[56:59]
	v_mfma_f32_16x16x32_bf16 v[44:47], v[128:131], v[152:155], v[44:47]
	v_mfma_f32_16x16x32_bf16 v[40:43], v[136:139], v[152:155], v[40:43]
	v_mfma_f32_16x16x32_bf16 v[28:31], v[128:131], v[160:163], v[28:31]
	v_mfma_f32_16x16x32_bf16 v[24:27], v[136:139], v[160:163], v[24:27]
	v_mfma_f32_16x16x32_bf16 v[12:15], v[128:131], v[184:187], v[12:15]
	v_mfma_f32_16x16x32_bf16 v[8:11], v[136:139], v[184:187], v[8:11]
	v_mfma_f32_16x16x32_bf16 v[60:63], v[132:135], v[148:151], v[60:63]
	v_mfma_f32_16x16x32_bf16 v[56:59], v[140:143], v[148:151], v[56:59]
	v_mfma_f32_16x16x32_bf16 v[44:47], v[132:135], v[156:159], v[44:47]
	v_mfma_f32_16x16x32_bf16 v[40:43], v[140:143], v[156:159], v[40:43]
	v_mfma_f32_16x16x32_bf16 v[28:31], v[132:135], v[180:183], v[28:31]
	v_mfma_f32_16x16x32_bf16 v[24:27], v[140:143], v[180:183], v[24:27]
	v_mfma_f32_16x16x32_bf16 v[12:15], v[132:135], v[188:191], v[12:15]
	v_mfma_f32_16x16x32_bf16 v[8:11], v[140:143], v[188:191], v[8:11]
	v_mfma_f32_16x16x32_bf16 v[52:55], v[200:203], v[144:147], v[52:55]
	v_mfma_f32_16x16x32_bf16 v[48:51], v[208:211], v[144:147], v[48:51]
	v_mfma_f32_16x16x32_bf16 v[36:39], v[200:203], v[152:155], v[36:39]
	v_mfma_f32_16x16x32_bf16 v[32:35], v[208:211], v[152:155], v[32:35]
	v_mfma_f32_16x16x32_bf16 v[20:23], v[200:203], v[160:163], v[20:23]
	v_mfma_f32_16x16x32_bf16 v[16:19], v[208:211], v[160:163], v[16:19]
	v_mfma_f32_16x16x32_bf16 v[4:7], v[200:203], v[184:187], v[4:7]
	v_mfma_f32_16x16x32_bf16 v[0:3], v[208:211], v[184:187], v[0:3]
	v_mfma_f32_16x16x32_bf16 v[52:55], v[204:207], v[148:151], v[52:55]
	v_mfma_f32_16x16x32_bf16 v[48:51], v[212:215], v[148:151], v[48:51]
	v_mfma_f32_16x16x32_bf16 v[36:39], v[204:207], v[156:159], v[36:39]
	v_mfma_f32_16x16x32_bf16 v[32:35], v[212:215], v[156:159], v[32:35]
	v_mfma_f32_16x16x32_bf16 v[20:23], v[204:207], v[180:183], v[20:23]
	v_mfma_f32_16x16x32_bf16 v[16:19], v[212:215], v[180:183], v[16:19]
	v_mfma_f32_16x16x32_bf16 v[4:7], v[204:207], v[188:191], v[4:7]
	v_mfma_f32_16x16x32_bf16 v[0:3], v[212:215], v[188:191], v[0:3]
	s_barrier
	s_add_i32 s66, 0, 0x18000
	v_add_u32_e32 v140, s66, v195
	ds_read_b128 v[128:131], v140
	ds_read_b128 v[132:135], v140 offset:1024
	ds_read_b128 v[136:139], v140 offset:2048
	ds_read_b128 v[140:143], v140 offset:3072
	s_add_u32 s22, s28, 0x158000
	s_addc_u32 s23, s29, 0
	s_mov_b32 m0, s51
	v_lshl_add_u64 v[200:201], s[22:23], 0, v[166:167]
	ds_read_b128 v[144:147], v198 offset:32768
	ds_read_b128 v[148:151], v198 offset:33792
	ds_read_b128 v[152:155], v198 offset:34816
	ds_read_b128 v[156:159], v198 offset:35840
	ds_read_b128 v[160:163], v198 offset:36864
	ds_read_b128 v[180:183], v198 offset:37888
	ds_read_b128 v[184:187], v198 offset:38912
	ds_read_b128 v[188:191], v198 offset:39936
	global_load_lds_dwordx4 v[200:201], off
	v_lshl_add_u64 v[200:201], s[22:23], 0, v[170:171]
	s_mov_b32 m0, s52
	s_nop 0
	global_load_lds_dwordx4 v[200:201], off
	s_add_i32 s28, 0, 0x1c000
	s_add_u32 s22, s26, 0x8000
	s_addc_u32 s23, s27, 0
	s_add_i32 s29, s66, s48
	v_add_u32_e32 v212, s28, v195
	v_lshl_add_u64 v[218:219], s[22:23], 0, v[164:165]
	s_mov_b32 m0, s29
	ds_read_b128 v[200:203], v212
	ds_read_b128 v[204:207], v212 offset:1024
	ds_read_b128 v[208:211], v212 offset:2048
	ds_read_b128 v[212:215], v212 offset:3072
	s_waitcnt vmcnt(8)
	s_waitcnt lgkmcnt(0)
	s_barrier
	v_mfma_f32_16x16x32_bf16 v[124:127], v[128:131], v[144:147], v[124:127]
	v_mfma_f32_16x16x32_bf16 v[120:123], v[136:139], v[144:147], v[120:123]
	v_mfma_f32_16x16x32_bf16 v[116:119], v[128:131], v[152:155], v[116:119]
	v_mfma_f32_16x16x32_bf16 v[104:107], v[136:139], v[152:155], v[104:107]
	v_mfma_f32_16x16x32_bf16 v[92:95], v[128:131], v[160:163], v[92:95]
	v_mfma_f32_16x16x32_bf16 v[88:91], v[136:139], v[160:163], v[88:91]
	v_mfma_f32_16x16x32_bf16 v[76:79], v[128:131], v[184:187], v[76:79]
	v_mfma_f32_16x16x32_bf16 v[72:75], v[136:139], v[184:187], v[72:75]
	v_mfma_f32_16x16x32_bf16 v[124:127], v[132:135], v[148:151], v[124:127]
	v_mfma_f32_16x16x32_bf16 v[120:123], v[140:143], v[148:151], v[120:123]
	v_mfma_f32_16x16x32_bf16 v[116:119], v[132:135], v[156:159], v[116:119]
	v_mfma_f32_16x16x32_bf16 v[104:107], v[140:143], v[156:159], v[104:107]
	v_mfma_f32_16x16x32_bf16 v[92:95], v[132:135], v[180:183], v[92:95]
	v_mfma_f32_16x16x32_bf16 v[88:91], v[140:143], v[180:183], v[88:91]
	v_mfma_f32_16x16x32_bf16 v[76:79], v[132:135], v[188:191], v[76:79]
	v_mfma_f32_16x16x32_bf16 v[72:75], v[140:143], v[188:191], v[72:75]
	v_mfma_f32_16x16x32_bf16 v[112:115], v[200:203], v[144:147], v[112:115]
	v_mfma_f32_16x16x32_bf16 v[108:111], v[208:211], v[144:147], v[108:111]
	v_mfma_f32_16x16x32_bf16 v[100:103], v[200:203], v[152:155], v[100:103]
	v_mfma_f32_16x16x32_bf16 v[96:99], v[208:211], v[152:155], v[96:99]
	v_mfma_f32_16x16x32_bf16 v[84:87], v[200:203], v[160:163], v[84:87]
	v_mfma_f32_16x16x32_bf16 v[80:83], v[208:211], v[160:163], v[80:83]
	v_mfma_f32_16x16x32_bf16 v[68:71], v[200:203], v[184:187], v[68:71]
	v_mfma_f32_16x16x32_bf16 v[64:67], v[208:211], v[184:187], v[64:67]
	v_mfma_f32_16x16x32_bf16 v[112:115], v[204:207], v[148:151], v[112:115]
	v_mfma_f32_16x16x32_bf16 v[108:111], v[212:215], v[148:151], v[108:111]
	v_mfma_f32_16x16x32_bf16 v[100:103], v[204:207], v[156:159], v[100:103]
	v_mfma_f32_16x16x32_bf16 v[96:99], v[212:215], v[156:159], v[96:99]
	v_mfma_f32_16x16x32_bf16 v[84:87], v[204:207], v[180:183], v[84:87]
	v_mfma_f32_16x16x32_bf16 v[80:83], v[212:215], v[180:183], v[80:83]
	v_mfma_f32_16x16x32_bf16 v[68:71], v[204:207], v[188:191], v[68:71]
	v_mfma_f32_16x16x32_bf16 v[64:67], v[212:215], v[188:191], v[64:67]
	s_barrier
; #define PG8_STAGE(bufoff, gbase, voff) do { _Pragma("unroll") for (int _i = 0; _i < 2; ++_i) \
;         __builtin_amdgcn_global_load_lds((const unsigned*)((const char*)(gbase) + (voff)[_i]), (PG8_LAS unsigned*)(lds + (bufoff) + ldsw + _i * 8192), 16, 0, 0); } while (0)
; #define PG8_LDA(dst, b, h) do { _Pragma("unroll") for (int m = 0; m < 4; ++m) _Pragma("unroll") for (int k = 0; k < 2; ++k) dst[m][k] = *(const PG8_LAS bf16x8*)(lds + PG8_SA(b, h) + aoff + m * 2048 + k * 1024); } while (0)
; #define PG8_MMA(ai, bj, At, Bt) do { __builtin_amdgcn_s_setprio(1); _Pragma("unroll") for (int m = 0; m < 4; ++m) _Pragma("unroll") for (int n = 0; n < 2; ++n) _Pragma("unroll") for (int k = 0; k < 2; ++k) \
;         acc[ai][bj][m][n] = __builtin_amdgcn_mfma_f32_16x16x32_bf16(Bt[n][k], At[m][k], acc[ai][bj][m][n], 0, 0, 0); __builtin_amdgcn_s_setprio(0); } while (0)
; #define PG8_WAIT_V(n) asm volatile("s_waitcnt vmcnt(" #n ")" ::: "memory")
; #define PG8_WAIT_L(n) asm volatile("s_waitcnt lgkmcnt(" #n ")" ::: "memory")
; #define PG8_BAR __builtin_amdgcn_s_barrier()
; #define PG8_SCHED __builtin_amdgcn_sched_barrier(0)
; template <class Epi, class Sched>
; __device__ __forceinline__ void gemm_phase(PG8_LAS unsigned char* lds, const Gemm g, const Sched& S, const Epi& E) {
;     ...
;             PG8_LDA(At, 1, 1); PG8_STAGE(PG8_SA(1, 0), a3, voffA);
;             PG8_BAR; PG8_WAIT_L(0); PG8_MMA(1, 0, At, B0); PG8_BAR; PG8_SCHED;
;             PG8_STAGE(PG8_SB(1, 1), b3 + hstepB, voffB);
;             PG8_WAIT_V(6); PG8_BAR; PG8_MMA(1, 1, At, B1); PG8_BAR;
;     ...
;     PG8_WAIT_V(0);
;     if (wr == 0) PG8_BAR;
;     PG8_BAR;
	global_load_lds_dwordx4 v[218:219], off
	v_lshl_add_u64 v[218:219], s[22:23], 0, v[168:169]
	s_add_i32 m0, s29, 0x2000
	s_nop 0
	global_load_lds_dwordx4 v[218:219], off
	s_mov_b32 m0, s54
	v_lshl_add_u64 v[192:193], v[192:193], 0, s[12:13]
	ds_read_b128 v[144:147], v198 offset:49152
	ds_read_b128 v[148:151], v198 offset:50176
	ds_read_b128 v[152:155], v198 offset:51200
	ds_read_b128 v[156:159], v198 offset:52224
	ds_read_b128 v[160:163], v198 offset:53248
	ds_read_b128 v[180:183], v198 offset:54272
	ds_read_b128 v[184:187], v198 offset:55296
	ds_read_b128 v[188:191], v198 offset:56320
	global_load_lds_dwordx4 v[192:193], off
	v_lshl_add_u64 v[192:193], v[216:217], 0, s[12:13]
	s_mov_b32 m0, s55
	s_nop 0
	global_load_lds_dwordx4 v[192:193], off
	s_add_u32 s22, s26, 0xc000
	s_addc_u32 s23, s27, 0
	s_add_i32 s26, s28, s48
	v_lshl_add_u64 v[252:253], s[22:23], 0, v[164:165]
	s_mov_b32 m0, s26
	s_nop 0
	global_load_lds_dwordx4 v[252:253], off
	v_lshl_add_u64 v[252:253], s[22:23], 0, v[168:169]
	s_add_i32 m0, s26, 0x2000
	s_nop 0
	global_load_lds_dwordx4 v[252:253], off
	s_add_i32 s65, s65, 2
	s_add_u32 s63, s63, 0x10000
	s_addc_u32 s64, s64, 0
	s_cmpk_gt_u32 s65, 0x53
	s_mov_b64 s[22:23], s[24:25]
	s_waitcnt vmcnt(8)
	s_waitcnt lgkmcnt(0)
	s_barrier
	v_mfma_f32_16x16x32_bf16 v[60:63], v[128:131], v[144:147], v[60:63]
	v_mfma_f32_16x16x32_bf16 v[56:59], v[136:139], v[144:147], v[56:59]
	v_mfma_f32_16x16x32_bf16 v[44:47], v[128:131], v[152:155], v[44:47]
	v_mfma_f32_16x16x32_bf16 v[40:43], v[136:139], v[152:155], v[40:43]
	v_mfma_f32_16x16x32_bf16 v[28:31], v[128:131], v[160:163], v[28:31]
	v_mfma_f32_16x16x32_bf16 v[24:27], v[136:139], v[160:163], v[24:27]
	v_mfma_f32_16x16x32_bf16 v[12:15], v[128:131], v[184:187], v[12:15]
	v_mfma_f32_16x16x32_bf16 v[8:11], v[136:139], v[184:187], v[8:11]
	v_mfma_f32_16x16x32_bf16 v[60:63], v[132:135], v[148:151], v[60:63]
	v_mfma_f32_16x16x32_bf16 v[56:59], v[140:143], v[148:151], v[56:59]
	v_mfma_f32_16x16x32_bf16 v[44:47], v[132:135], v[156:159], v[44:47]
	v_mfma_f32_16x16x32_bf16 v[40:43], v[140:143], v[156:159], v[40:43]
	v_mfma_f32_16x16x32_bf16 v[28:31], v[132:135], v[180:183], v[28:31]
	v_mfma_f32_16x16x32_bf16 v[24:27], v[140:143], v[180:183], v[24:27]
	v_mfma_f32_16x16x32_bf16 v[12:15], v[132:135], v[188:191], v[12:15]
	v_mfma_f32_16x16x32_bf16 v[8:11], v[140:143], v[188:191], v[8:11]
	v_mfma_f32_16x16x32_bf16 v[52:55], v[200:203], v[144:147], v[52:55]
	v_mfma_f32_16x16x32_bf16 v[48:51], v[208:211], v[144:147], v[48:51]
	v_mfma_f32_16x16x32_bf16 v[36:39], v[200:203], v[152:155], v[36:39]
	v_mfma_f32_16x16x32_bf16 v[32:35], v[208:211], v[152:155], v[32:35]
	v_mfma_f32_16x16x32_bf16 v[20:23], v[200:203], v[160:163], v[20:23]
	v_mfma_f32_16x16x32_bf16 v[16:19], v[208:211], v[160:163], v[16:19]
	v_mfma_f32_16x16x32_bf16 v[4:7], v[200:203], v[184:187], v[4:7]
	v_mfma_f32_16x16x32_bf16 v[0:3], v[208:211], v[184:187], v[0:3]
	v_mfma_f32_16x16x32_bf16 v[52:55], v[204:207], v[148:151], v[52:55]
	v_mfma_f32_16x16x32_bf16 v[48:51], v[212:215], v[148:151], v[48:51]
	v_mfma_f32_16x16x32_bf16 v[36:39], v[204:207], v[156:159], v[36:39]
	v_mfma_f32_16x16x32_bf16 v[32:35], v[212:215], v[156:159], v[32:35]
	v_mfma_f32_16x16x32_bf16 v[20:23], v[204:207], v[180:183], v[20:23]
	v_mfma_f32_16x16x32_bf16 v[16:19], v[212:215], v[180:183], v[16:19]
	v_mfma_f32_16x16x32_bf16 v[4:7], v[204:207], v[188:191], v[4:7]
	v_mfma_f32_16x16x32_bf16 v[0:3], v[212:215], v[188:191], v[0:3]
	s_barrier
	s_cbranch_scc0 .LBB0_980
	s_cmp_eq_u32 s78, 0
	s_cbranch_scc0 .Lhalf_skip_x_7
	s_barrier
